# v25rot
# baseline (speedup 1.0000x reference)
; #define WAIT_V(n) asm volatile("s_waitcnt vmcnt(" #n ")" ::: "memory")
; #define BAR __builtin_amdgcn_s_barrier()
; __device__ __forceinline__ void mainloop_8phase(const u16* __restrict__ A, const u16* __restrict__ Bt, int K,
;                                                 f32x4 (&acc)[2][2][4][2], int wid_s, int ld) {
;     ...
;   int tid = get_tid(wid_s), wid = tid >> 6, lane = tid & 63, wr = wid >> 2, wc = wid & 3, fr = lane & 15, fq = lane >> 4;
;   unsigned goff0, goff1;
;   {
;     int r0, c0, r1, c1;
;     stage_rc(tid * 16, r0, c0);
;     stage_rc(tid * 16 + 8192, r1, c1);
;     goff0 = (unsigned)(r0 * ld + c0) * 2u;
;     goff1 = (unsigned)(r1 * ld + c1) * 2u;
;   }
;   __amdgpu_buffer_rsrc_t rs_A, rs_Bt;
;   {
;     unsigned long ua = (unsigned long)A, ub = (unsigned long)Bt;
;     unsigned alo = __builtin_amdgcn_readfirstlane((unsigned)ua), ahi = __builtin_amdgcn_readfirstlane((unsigned)(ua >> 32));
;     unsigned blo = __builtin_amdgcn_readfirstlane((unsigned)ub), bhi = __builtin_amdgcn_readfirstlane((unsigned)(ub >> 32));
;     rs_A = __builtin_amdgcn_make_buffer_rsrc((void*)(((unsigned long)ahi << 32) | alo), (short)0, 0x7ffffff0, 0x00020000);
;     rs_Bt = __builtin_amdgcn_make_buffer_rsrc((void*)(((unsigned long)bhi << 32) | blo), (short)0, 0x7ffffff0, 0x00020000);
;   }
;   bf16x8 At[4][2], B0[2][2], B1[2][2];
;   const int brow = 0, bcol = 0;
;   int nt = K / G_BK;
;   if (wr == 1) BAR;
;   WAIT_V(0); BAR;
;   STAGE(SB(1, 0), Bt, bcol, 1); STAGE(SA(1, 0), A, brow, 1); STAGE(SB(1, 1), Bt, bcol + G_HALF, 1);
;   WAIT_V(6); BAR;
;     ...
;     f32x4 acc[2][2][4][2];
; #pragma unroll
;     for (int a = 0; a < 2; ++a)
; #pragma unroll
;       for (int b = 0; b < 2; ++b)
; #pragma unroll
;         for (int c = 0; c < 4; ++c)
; #pragma unroll
;           for (int d = 0; d < 2; ++d) acc[a][b][c][d] = f32x4{0.f, 0.f, 0.f, 0.f};
.LBB0_57:
	s_or_b64 exec, exec, s[0:1]
	v_bfe_i32 v8, v0, 27, 1
	v_lshlrev_b32_e32 v6, 4, v0
	v_lshrrev_b32_e32 v8, 22, v8
	v_add_u32_e32 v8, v6, v8
	v_and_b32_e32 v8, 0xfffffc00, v8
	v_sub_u32_e32 v8, v6, v8
	v_lshrrev_b32_e32 v9, 4, v8
	v_ashrrev_i32_e32 v7, 31, v0
	v_bitop3_b32 v8, v9, v8, 32 bitop3:0x6c
	v_lshrrev_b32_e32 v7, 26, v7
	v_ashrrev_i32_e32 v10, 31, v8
	v_add_u32_e32 v7, v0, v7
	v_lshrrev_b32_e32 v10, 26, v10
	v_ashrrev_i32_e32 v7, 6, v7
	v_add_u32_e32 v10, v8, v10
	v_lshlrev_b32_e32 v9, 3, v7
	v_lshrrev_b32_e32 v11, 6, v10
	v_and_b32_e32 v10, 0xc0, v10
	v_and_b32_e32 v9, 0xffff0, v9
	v_sub_u32_e32 v8, v8, v10
	v_add_u32_e32 v10, 0x2000, v6
	v_add_u32_e32 v9, v11, v9
	v_ashrrev_i32_e32 v11, 31, v10
	v_lshrrev_b32_e32 v11, 22, v11
	v_add_u32_e32 v11, v10, v11
	v_ashrrev_i32_e32 v11, 10, v11
	v_mul_i32_i24_e32 v12, 0x400, v11
	v_sub_u32_e32 v10, v10, v12
	v_lshrrev_b32_e32 v12, 4, v10
	v_bitop3_b32 v10, v12, v10, 32 bitop3:0x6c
	v_ashrrev_i32_e32 v13, 31, v10
	v_lshrrev_b32_e32 v13, 26, v13
	v_add_u32_e32 v13, v10, v13
	v_lshlrev_b32_e32 v7, 5, v7
	v_lshlrev_b32_e32 v12, 3, v11
	v_lshrrev_b32_e32 v14, 6, v13
	v_and_b32_e32 v13, 0xc0, v13
	v_readlane_b32 s6, v254, 43
	v_and_b32_e32 v7, 32, v7
	v_ashrrev_i16_sdwa v8, v244, sext(v8) dst_sel:DWORD dst_unused:UNUSED_PAD src0_sel:DWORD src1_sel:BYTE_0
	v_and_b32_e32 v12, 0xffff0, v12
	v_lshlrev_b32_e32 v11, 5, v11
	v_sub_u32_e32 v10, v10, v13
	s_waitcnt vmcnt(15)
	v_add_u32_e32 v138, s6, v6
	v_bfe_i32 v8, v8, 0, 16
	v_add_u32_e32 v12, v14, v12
	v_and_b32_e32 v11, 32, v11
	v_ashrrev_i16_sdwa v10, v244, sext(v10) dst_sel:DWORD dst_unused:UNUSED_PAD src0_sel:DWORD src1_sel:BYTE_0
	v_lshl_or_b32 v7, v9, 11, v7
	s_and_b32 s5, s13, 0xffff
	v_readfirstlane_b32 s0, v138
	v_add_u32_e32 v139, 0x2000, v138
	v_add_u32_e32 v140, 16, v6
	v_bfe_i32 v10, v10, 0, 16
	v_add_lshl_u32 v137, v7, v8, 1
	v_lshl_or_b32 v7, v12, 11, v11
	s_mov_b32 s20, s12
	s_mov_b32 s21, s5
	s_mov_b32 s22, s90
	s_mov_b32 s23, s91
	s_mov_b32 m0, s0
	s_movk_i32 s1, 0x80
	v_readfirstlane_b32 s0, v139
	v_add_u32_e32 v141, 0x8000, v140
	v_add_lshl_u32 v136, v7, v10, 1
	s_and_b32 s89, s11, 0xffff
	s_waitcnt vmcnt(0)
	s_barrier
	buffer_load_dwordx4 v137, s[20:23], s1 offen lds
	s_mov_b32 m0, s0
	v_readfirstlane_b32 s0, v141
	v_add_u32_e32 v142, 0xa000, v140
	v_readlane_b32 s7, v254, 44
	s_mov_b32 s16, s10
	s_mov_b32 s17, s89
	s_mov_b32 s18, s90
	s_mov_b32 s19, s91
	buffer_load_dwordx4 v136, s[20:23], s1 offen lds
	s_mov_b32 m0, s0
	v_readfirstlane_b32 s0, v142
	v_add_u32_e32 v143, s7, v6
	buffer_load_dwordx4 v137, s[16:19], s1 offen lds
	s_mov_b32 m0, s0
	v_readfirstlane_b32 s0, v143
	v_add_u32_e32 v146, 0x2000, v143
	buffer_load_dwordx4 v136, s[16:19], s1 offen lds
	s_mov_b32 m0, s0
	s_mov_b32 s1, 0x80080
	v_readfirstlane_b32 s0, v146
	buffer_load_dwordx4 v137, s[20:23], s1 offen lds
	s_mov_b32 m0, s0
	v_and_b32_e32 v4, 15, v2
	buffer_load_dwordx4 v136, s[20:23], s1 offen lds
	v_lshlrev_b32_e32 v7, 2, v2
	v_and_b32_e32 v5, 48, v2
	v_lshlrev_b32_e32 v4, 6, v4
	v_and_b32_e32 v7, 32, v7
	v_bitop3_b32 v4, v4, v7, v5 bitop3:0x36
	v_readlane_b32 s0, v254, 41
	v_lshlrev_b32_e32 v2, 6, v2
	s_waitcnt vmcnt(6)
	v_readlane_b32 s1, v254, 42
	v_add_u32_e32 v8, s0, v4
	v_add_u32_e32 v148, s0, v6
	s_movk_i32 s0, 0x3c0
	v_lshlrev_b32_e32 v11, 6, v0
	v_lshlrev_b32_e32 v3, 13, v3
	v_and_or_b32 v2, v2, s0, v5
	v_add_u32_e32 v9, s1, v4
	v_add_u32_e32 v151, s1, v6
	v_add_u32_e32 v6, s6, v4
	v_add_u32_e32 v10, s7, v4
	v_and_b32_e32 v11, 0x3000, v11
	v_add_u32_e32 v4, 16, v4
	v_xad_u32 v5, v2, v7, 16
	v_or_b32_e32 v7, 0x800, v3
	v_or_b32_e32 v12, 0x1000, v3
	v_or_b32_e32 v13, 0x1800, v3
	v_mov_b32_e32 v2, 0
	s_mov_b32 s88, s10
	s_mov_b32 s4, s12
	v_add_u32_e32 v145, 0xc000, v140
	v_add_u32_e32 v144, 0xe000, v140
	v_add_u32_e32 v149, 0x2000, v148
	v_add_u32_e32 v150, 0x2000, v140
	v_add_u32_e32 v152, 0x2000, v151
	v_add_u32_e32 v153, 0x4000, v140
	v_add_u32_e32 v154, 0x6000, v140
	s_mov_b32 s0, -2
	s_mov_b32 s1, 0x80180
	v_add_u32_e32 v155, v8, v11
	s_waitcnt lgkmcnt(0)
	v_add_u32_e32 v133, v4, v3
	v_add_u32_e32 v132, v5, v7
	v_add_u32_e32 v131, v5, v12
	v_add_u32_e32 v130, v5, v13
	v_add_u32_e32 v147, v9, v11
	v_add_u32_e32 v135, v6, v11
	v_add_u32_e32 v134, v10, v11
	v_mov_b32_e32 v3, v2
	v_mov_b32_e32 v4, v2
	v_mov_b32_e32 v5, v2
	v_mov_b32_e32 v6, v2
	v_mov_b32_e32 v7, v2
	v_mov_b32_e32 v8, v2
	v_mov_b32_e32 v9, v2
	v_mov_b32_e32 v10, v2
	v_mov_b32_e32 v11, v2
	v_mov_b32_e32 v12, v2
	v_mov_b32_e32 v13, v2
	v_mov_b32_e32 v14, v2
	v_mov_b32_e32 v15, v2
	v_mov_b32_e32 v16, v2
	v_mov_b32_e32 v17, v2
	v_mov_b32_e32 v18, v2
	v_mov_b32_e32 v19, v2
	v_mov_b32_e32 v20, v2
	v_mov_b32_e32 v21, v2
	v_mov_b32_e32 v22, v2
	v_mov_b32_e32 v23, v2
	v_mov_b32_e32 v24, v2
	v_mov_b32_e32 v25, v2
	v_mov_b32_e32 v26, v2
	v_mov_b32_e32 v27, v2
	v_mov_b32_e32 v28, v2
	v_mov_b32_e32 v29, v2
	v_mov_b32_e32 v30, v2
	v_mov_b32_e32 v31, v2
	v_mov_b32_e32 v32, v2
	v_mov_b32_e32 v33, v2
	v_mov_b32_e32 v34, v2
	v_mov_b32_e32 v35, v2
	v_mov_b32_e32 v36, v2
	v_mov_b32_e32 v37, v2
	v_mov_b32_e32 v38, v2
	v_mov_b32_e32 v39, v2
	v_mov_b32_e32 v40, v2
	v_mov_b32_e32 v41, v2
	v_mov_b32_e32 v42, v2
	v_mov_b32_e32 v43, v2
	v_mov_b32_e32 v44, v2
	v_mov_b32_e32 v45, v2
	v_mov_b32_e32 v46, v2
	v_mov_b32_e32 v47, v2
	v_mov_b32_e32 v48, v2
	v_mov_b32_e32 v49, v2
	v_mov_b32_e32 v50, v2
	v_mov_b32_e32 v51, v2
	v_mov_b32_e32 v52, v2
	v_mov_b32_e32 v53, v2
	v_mov_b32_e32 v54, v2
	v_mov_b32_e32 v55, v2
	v_mov_b32_e32 v56, v2
	v_mov_b32_e32 v57, v2
	v_mov_b32_e32 v58, v2
	v_mov_b32_e32 v59, v2
	v_mov_b32_e32 v60, v2
	v_mov_b32_e32 v61, v2
	v_mov_b32_e32 v62, v2
	v_mov_b32_e32 v63, v2
	v_mov_b32_e32 v64, v2
	v_mov_b32_e32 v65, v2
	v_mov_b32_e32 v66, v2
	v_mov_b32_e32 v67, v2
	s_waitcnt vmcnt(17)
; #define WAIT_L(n) asm volatile("s_waitcnt lgkmcnt(" #n ")" ::: "memory")
; #define BAR __builtin_amdgcn_s_barrier()
; #define SCHED __builtin_amdgcn_sched_barrier(0)
; __device__ __forceinline__ void mainloop_8phase(const u16* __restrict__ A, const u16* __restrict__ Bt, int K,
;                                                 f32x4 (&acc)[2][2][4][2], int wid_s, int ld) {
;     ...
;   for (int t = 0; t < nt - 2; t += 2) {
;     LDB(B0, 0, 0); SCHED; LDA(At, 0, 0); STAGE(SA(1, 1), A, brow + G_HALF, t + 1);
;     WAIT_L(8); BAR; WAIT_L(0); MMA(0, 0, At, B0); BAR; SCHED;
;     LDB(B1, 0, 1); STAGE(SB(0, 0), Bt, bcol, t + 2);
;     BAR; WAIT_L(0); MMA(0, 1, At, B1); BAR;
;     LDA(At, 0, 1); STAGE(SA(0, 0), A, brow, t + 2);
;     BAR; WAIT_L(0); MMA(1, 0, At, B0); BAR; SCHED;
	v_mov_b32_e32 v68, v2
	v_mov_b32_e32 v69, v2
	v_mov_b32_e32 v70, v2
	v_mov_b32_e32 v71, v2
	s_waitcnt vmcnt(16)
	v_mov_b32_e32 v72, v2
	v_mov_b32_e32 v73, v2
	v_mov_b32_e32 v74, v2
	v_mov_b32_e32 v75, v2
	s_waitcnt vmcnt(15)
	v_mov_b32_e32 v76, v2
	v_mov_b32_e32 v77, v2
	v_mov_b32_e32 v78, v2
	v_mov_b32_e32 v79, v2
	s_waitcnt vmcnt(14)
	v_mov_b32_e32 v80, v2
	v_mov_b32_e32 v81, v2
	v_mov_b32_e32 v82, v2
	v_mov_b32_e32 v83, v2
	v_mov_b32_e32 v84, v2
	v_mov_b32_e32 v85, v2
	v_mov_b32_e32 v86, v2
	v_mov_b32_e32 v87, v2
	v_mov_b32_e32 v88, v2
	v_mov_b32_e32 v89, v2
	v_mov_b32_e32 v90, v2
	v_mov_b32_e32 v91, v2
	v_mov_b32_e32 v92, v2
	v_mov_b32_e32 v93, v2
	v_mov_b32_e32 v94, v2
	v_mov_b32_e32 v95, v2
	v_mov_b32_e32 v96, v2
	v_mov_b32_e32 v97, v2
	v_mov_b32_e32 v98, v2
	v_mov_b32_e32 v99, v2
	v_mov_b32_e32 v100, v2
	v_mov_b32_e32 v101, v2
	v_mov_b32_e32 v102, v2
	v_mov_b32_e32 v103, v2
	v_mov_b32_e32 v104, v2
	v_mov_b32_e32 v105, v2
	v_mov_b32_e32 v106, v2
	v_mov_b32_e32 v107, v2
	v_mov_b32_e32 v108, v2
	v_mov_b32_e32 v109, v2
	v_mov_b32_e32 v110, v2
	v_mov_b32_e32 v111, v2
	v_mov_b32_e32 v112, v2
	v_mov_b32_e32 v113, v2
	v_mov_b32_e32 v114, v2
	v_mov_b32_e32 v115, v2
	v_mov_b32_e32 v116, v2
	v_mov_b32_e32 v117, v2
	v_mov_b32_e32 v118, v2
	v_mov_b32_e32 v119, v2
	v_mov_b32_e32 v120, v2
	v_mov_b32_e32 v121, v2
	v_mov_b32_e32 v122, v2
	v_mov_b32_e32 v123, v2
	v_mov_b32_e32 v124, v2
	v_mov_b32_e32 v125, v2
	v_mov_b32_e32 v126, v2
	v_mov_b32_e32 v127, v2
	v_mov_b32_e32 v128, v2
	v_mov_b32_e32 v129, v2
	s_mov_b32 s7, s91
.LBB0_58:
	s_barrier
	ds_read_b128 v[156:159], v155
	ds_read_b128 v[160:163], v155 offset:1024
	ds_read_b128 v[164:167], v155 offset:2048
	ds_read_b128 v[168:171], v155 offset:3072
	s_add_i32 s6, s1, 0xffffff00
	s_add_i32 m0, s100, 0xc000
	ds_read_b128 v[172:175], v133
	ds_read_b128 v[176:179], v133 offset:1024
	ds_read_b128 v[180:183], v132
	ds_read_b128 v[184:187], v132 offset:1024
	ds_read_b128 v[188:191], v131
	ds_read_b128 v[192:195], v131 offset:1024
	ds_read_b128 v[196:199], v130
	buffer_load_dwordx4 v137, s[88:91], s6 offen lds
	s_add_i32 m0, s100, 0xe000
	ds_read_b128 v[200:203], v130 offset:1024
	buffer_load_dwordx4 v136, s[88:91], s6 offen lds
	s_waitcnt lgkmcnt(8)
	s_barrier
	s_waitcnt lgkmcnt(1)
	v_mfma_f32_16x16x32_bf16 v[126:129], v[172:175], v[156:159], v[126:129]
	v_mfma_f32_16x16x32_bf16 v[122:125], v[172:175], v[164:167], v[122:125]
	v_mfma_f32_16x16x32_bf16 v[118:121], v[180:183], v[156:159], v[118:121]
	v_mfma_f32_16x16x32_bf16 v[114:117], v[180:183], v[164:167], v[114:117]
	v_mfma_f32_16x16x32_bf16 v[110:113], v[188:191], v[156:159], v[110:113]
	v_mfma_f32_16x16x32_bf16 v[106:109], v[188:191], v[164:167], v[106:109]
	v_mfma_f32_16x16x32_bf16 v[102:105], v[196:199], v[156:159], v[102:105]
	v_mfma_f32_16x16x32_bf16 v[98:101], v[196:199], v[164:167], v[98:101]
	v_mfma_f32_16x16x32_bf16 v[126:129], v[176:179], v[160:163], v[126:129]
	v_mfma_f32_16x16x32_bf16 v[122:125], v[176:179], v[168:171], v[122:125]
	v_mfma_f32_16x16x32_bf16 v[118:121], v[184:187], v[160:163], v[118:121]
	v_mfma_f32_16x16x32_bf16 v[114:117], v[184:187], v[168:171], v[114:117]
	v_mfma_f32_16x16x32_bf16 v[110:113], v[192:195], v[160:163], v[110:113]
	v_mfma_f32_16x16x32_bf16 v[106:109], v[192:195], v[168:171], v[106:109]
	s_waitcnt lgkmcnt(0)
	v_mfma_f32_16x16x32_bf16 v[102:105], v[200:203], v[160:163], v[102:105]
	v_mfma_f32_16x16x32_bf16 v[98:101], v[200:203], v[168:171], v[98:101]
	s_barrier
	s_add_i32 s15, s1, 0xfff7ff80
	s_mov_b32 s6, s90
	s_add_i32 m0, s100, 0x10000
	ds_read_b128 v[204:207], v147
	ds_read_b128 v[208:211], v147 offset:1024
	ds_read_b128 v[212:215], v147 offset:2048
	buffer_load_dwordx4 v137, s[4:7], s15 offen lds
	s_add_i32 m0, s100, 0x12000
	ds_read_b128 v[216:219], v147 offset:3072
	buffer_load_dwordx4 v136, s[4:7], s15 offen lds
	s_barrier
	s_waitcnt lgkmcnt(1)
	v_mfma_f32_16x16x32_bf16 v[94:97], v[172:175], v[204:207], v[94:97]
	v_mfma_f32_16x16x32_bf16 v[90:93], v[172:175], v[212:215], v[90:93]
	v_mfma_f32_16x16x32_bf16 v[86:89], v[180:183], v[204:207], v[86:89]
	v_mfma_f32_16x16x32_bf16 v[82:85], v[180:183], v[212:215], v[82:85]
	v_mfma_f32_16x16x32_bf16 v[78:81], v[188:191], v[204:207], v[78:81]
	v_mfma_f32_16x16x32_bf16 v[74:77], v[188:191], v[212:215], v[74:77]
	v_mfma_f32_16x16x32_bf16 v[70:73], v[196:199], v[204:207], v[70:73]
	v_mfma_f32_16x16x32_bf16 v[66:69], v[196:199], v[212:215], v[66:69]
	v_mfma_f32_16x16x32_bf16 v[94:97], v[176:179], v[208:211], v[94:97]
	s_waitcnt lgkmcnt(0)
	v_mfma_f32_16x16x32_bf16 v[90:93], v[176:179], v[216:219], v[90:93]
	v_mfma_f32_16x16x32_bf16 v[86:89], v[184:187], v[208:211], v[86:89]
	v_mfma_f32_16x16x32_bf16 v[82:85], v[184:187], v[216:219], v[82:85]
	v_mfma_f32_16x16x32_bf16 v[78:81], v[192:195], v[208:211], v[78:81]
	v_mfma_f32_16x16x32_bf16 v[74:77], v[192:195], v[216:219], v[74:77]
	v_mfma_f32_16x16x32_bf16 v[70:73], v[200:203], v[208:211], v[70:73]
	v_mfma_f32_16x16x32_bf16 v[66:69], v[200:203], v[216:219], v[66:69]
	s_mov_b32 m0, s100
	s_barrier
	ds_read_b128 v[172:175], v133 offset:16384
	ds_read_b128 v[176:179], v133 offset:17408
	ds_read_b128 v[180:183], v132 offset:16384
	ds_read_b128 v[184:187], v132 offset:17408
	ds_read_b128 v[188:191], v131 offset:16384
	ds_read_b128 v[192:195], v131 offset:17408
	ds_read_b128 v[196:199], v130 offset:16384
	buffer_load_dwordx4 v137, s[88:91], s15 offen lds
	s_add_i32 m0, s100, 0x2000
	ds_read_b128 v[200:203], v130 offset:17408
	buffer_load_dwordx4 v136, s[88:91], s15 offen lds
	s_barrier
; #define WAIT_V(n) asm volatile("s_waitcnt vmcnt(" #n ")" ::: "memory")
; #define WAIT_L(n) asm volatile("s_waitcnt lgkmcnt(" #n ")" ::: "memory")
; #define BAR __builtin_amdgcn_s_barrier()
; #define SCHED __builtin_amdgcn_sched_barrier(0)
; __device__ __forceinline__ void mainloop_8phase(const u16* __restrict__ A, const u16* __restrict__ Bt, int K,
;                                                 f32x4 (&acc)[2][2][4][2], int wid_s, int ld) {
;     ...
;     BAR; WAIT_L(0); MMA(1, 0, At, B0); BAR; SCHED;
;     STAGE(SB(0, 1), Bt, bcol + G_HALF, t + 2);
;     WAIT_V(6); BAR; MMA(1, 1, At, B1); BAR;
;     LDB(B0, 1, 0); SCHED; LDA(At, 1, 0); STAGE(SA(0, 1), A, brow + G_HALF, t + 2);
;     WAIT_L(8); BAR; WAIT_L(0); MMA(0, 0, At, B0); BAR; SCHED;
;     LDB(B1, 1, 1); STAGE(SB(1, 0), Bt, bcol, t + 3);
;     BAR; WAIT_L(0); MMA(0, 1, At, B1); BAR;
	s_waitcnt lgkmcnt(1)
	v_mfma_f32_16x16x32_bf16 v[62:65], v[172:175], v[156:159], v[62:65]
	v_mfma_f32_16x16x32_bf16 v[58:61], v[172:175], v[164:167], v[58:61]
	v_mfma_f32_16x16x32_bf16 v[54:57], v[180:183], v[156:159], v[54:57]
	v_mfma_f32_16x16x32_bf16 v[50:53], v[180:183], v[164:167], v[50:53]
	v_mfma_f32_16x16x32_bf16 v[46:49], v[188:191], v[156:159], v[46:49]
	v_mfma_f32_16x16x32_bf16 v[42:45], v[188:191], v[164:167], v[42:45]
	v_mfma_f32_16x16x32_bf16 v[38:41], v[196:199], v[156:159], v[38:41]
	v_mfma_f32_16x16x32_bf16 v[34:37], v[196:199], v[164:167], v[34:37]
	v_mfma_f32_16x16x32_bf16 v[62:65], v[176:179], v[160:163], v[62:65]
	v_mfma_f32_16x16x32_bf16 v[58:61], v[176:179], v[168:171], v[58:61]
	v_mfma_f32_16x16x32_bf16 v[54:57], v[184:187], v[160:163], v[54:57]
	v_mfma_f32_16x16x32_bf16 v[50:53], v[184:187], v[168:171], v[50:53]
	v_mfma_f32_16x16x32_bf16 v[46:49], v[192:195], v[160:163], v[46:49]
	v_mfma_f32_16x16x32_bf16 v[42:45], v[192:195], v[168:171], v[42:45]
	s_waitcnt lgkmcnt(0)
	v_mfma_f32_16x16x32_bf16 v[38:41], v[200:203], v[160:163], v[38:41]
	v_mfma_f32_16x16x32_bf16 v[34:37], v[200:203], v[168:171], v[34:37]
	s_barrier
	s_add_i32 m0, s100, 0x14000
	s_add_i32 s15, s1, 0xffffff80
	buffer_load_dwordx4 v137, s[4:7], s15 offen lds
	s_add_i32 m0, s100, 0x16000
	s_nop 0
	buffer_load_dwordx4 v136, s[4:7], s15 offen lds
	s_waitcnt vmcnt(6)
	s_barrier
	v_mfma_f32_16x16x32_bf16 v[30:33], v[172:175], v[204:207], v[30:33]
	v_mfma_f32_16x16x32_bf16 v[26:29], v[172:175], v[212:215], v[26:29]
	v_mfma_f32_16x16x32_bf16 v[22:25], v[180:183], v[204:207], v[22:25]
	v_mfma_f32_16x16x32_bf16 v[18:21], v[180:183], v[212:215], v[18:21]
	v_mfma_f32_16x16x32_bf16 v[14:17], v[188:191], v[204:207], v[14:17]
	v_mfma_f32_16x16x32_bf16 v[10:13], v[188:191], v[212:215], v[10:13]
	v_mfma_f32_16x16x32_bf16 v[6:9], v[196:199], v[204:207], v[6:9]
	v_mfma_f32_16x16x32_bf16 v[2:5], v[196:199], v[212:215], v[2:5]
	v_mfma_f32_16x16x32_bf16 v[30:33], v[176:179], v[208:211], v[30:33]
	v_mfma_f32_16x16x32_bf16 v[26:29], v[176:179], v[216:219], v[26:29]
	v_mfma_f32_16x16x32_bf16 v[22:25], v[184:187], v[208:211], v[22:25]
	v_mfma_f32_16x16x32_bf16 v[18:21], v[184:187], v[216:219], v[18:21]
	v_mfma_f32_16x16x32_bf16 v[14:17], v[192:195], v[208:211], v[14:17]
	v_mfma_f32_16x16x32_bf16 v[10:13], v[192:195], v[216:219], v[10:13]
	v_mfma_f32_16x16x32_bf16 v[6:9], v[200:203], v[208:211], v[6:9]
	v_mfma_f32_16x16x32_bf16 v[2:5], v[200:203], v[216:219], v[2:5]
	s_barrier
	ds_read_b128 v[156:159], v135
	ds_read_b128 v[160:163], v135 offset:1024
	ds_read_b128 v[164:167], v135 offset:2048
	ds_read_b128 v[168:171], v135 offset:3072
	s_add_i32 m0, s100, 0x4000
	ds_read_b128 v[172:175], v133 offset:32768
	ds_read_b128 v[176:179], v133 offset:33792
	ds_read_b128 v[180:183], v132 offset:32768
	ds_read_b128 v[184:187], v132 offset:33792
	ds_read_b128 v[188:191], v131 offset:32768
	ds_read_b128 v[192:195], v131 offset:33792
	ds_read_b128 v[196:199], v130 offset:32768
	buffer_load_dwordx4 v137, s[88:91], s15 offen lds
	s_add_i32 m0, s100, 0x6000
	ds_read_b128 v[200:203], v130 offset:33792
	buffer_load_dwordx4 v136, s[88:91], s15 offen lds
	s_waitcnt lgkmcnt(8)
	s_barrier
	s_waitcnt lgkmcnt(1)
	v_mfma_f32_16x16x32_bf16 v[126:129], v[172:175], v[156:159], v[126:129]
	v_mfma_f32_16x16x32_bf16 v[122:125], v[172:175], v[164:167], v[122:125]
	v_mfma_f32_16x16x32_bf16 v[118:121], v[180:183], v[156:159], v[118:121]
	v_mfma_f32_16x16x32_bf16 v[114:117], v[180:183], v[164:167], v[114:117]
	v_mfma_f32_16x16x32_bf16 v[110:113], v[188:191], v[156:159], v[110:113]
	v_mfma_f32_16x16x32_bf16 v[106:109], v[188:191], v[164:167], v[106:109]
	v_mfma_f32_16x16x32_bf16 v[102:105], v[196:199], v[156:159], v[102:105]
	v_mfma_f32_16x16x32_bf16 v[98:101], v[196:199], v[164:167], v[98:101]
	v_mfma_f32_16x16x32_bf16 v[126:129], v[176:179], v[160:163], v[126:129]
	v_mfma_f32_16x16x32_bf16 v[122:125], v[176:179], v[168:171], v[122:125]
	v_mfma_f32_16x16x32_bf16 v[118:121], v[184:187], v[160:163], v[118:121]
	v_mfma_f32_16x16x32_bf16 v[114:117], v[184:187], v[168:171], v[114:117]
	v_mfma_f32_16x16x32_bf16 v[110:113], v[192:195], v[160:163], v[110:113]
	v_mfma_f32_16x16x32_bf16 v[106:109], v[192:195], v[168:171], v[106:109]
	s_waitcnt lgkmcnt(0)
	v_mfma_f32_16x16x32_bf16 v[102:105], v[200:203], v[160:163], v[102:105]
	v_mfma_f32_16x16x32_bf16 v[98:101], v[200:203], v[168:171], v[98:101]
	s_barrier
	s_add_i32 s15, s1, 0xfff80000
	s_add_i32 m0, s100, 0x18000
	ds_read_b128 v[204:207], v134
	ds_read_b128 v[208:211], v134 offset:1024
	ds_read_b128 v[212:215], v134 offset:2048
	buffer_load_dwordx4 v137, s[4:7], s15 offen lds
	s_add_i32 m0, s100, 0x1a000
	ds_read_b128 v[216:219], v134 offset:3072
	buffer_load_dwordx4 v136, s[4:7], s15 offen lds
	s_barrier
	s_waitcnt lgkmcnt(1)
	v_mfma_f32_16x16x32_bf16 v[94:97], v[172:175], v[204:207], v[94:97]
	v_mfma_f32_16x16x32_bf16 v[90:93], v[172:175], v[212:215], v[90:93]
	v_mfma_f32_16x16x32_bf16 v[86:89], v[180:183], v[204:207], v[86:89]
	v_mfma_f32_16x16x32_bf16 v[82:85], v[180:183], v[212:215], v[82:85]
	v_mfma_f32_16x16x32_bf16 v[78:81], v[188:191], v[204:207], v[78:81]
	v_mfma_f32_16x16x32_bf16 v[74:77], v[188:191], v[212:215], v[74:77]
	v_mfma_f32_16x16x32_bf16 v[70:73], v[196:199], v[204:207], v[70:73]
	v_mfma_f32_16x16x32_bf16 v[66:69], v[196:199], v[212:215], v[66:69]
	v_mfma_f32_16x16x32_bf16 v[94:97], v[176:179], v[208:211], v[94:97]
	s_waitcnt lgkmcnt(0)
	v_mfma_f32_16x16x32_bf16 v[90:93], v[176:179], v[216:219], v[90:93]
	v_mfma_f32_16x16x32_bf16 v[86:89], v[184:187], v[208:211], v[86:89]
	v_mfma_f32_16x16x32_bf16 v[82:85], v[184:187], v[216:219], v[82:85]
	v_mfma_f32_16x16x32_bf16 v[78:81], v[192:195], v[208:211], v[78:81]
	v_mfma_f32_16x16x32_bf16 v[74:77], v[192:195], v[216:219], v[74:77]
	v_mfma_f32_16x16x32_bf16 v[70:73], v[200:203], v[208:211], v[70:73]
	v_mfma_f32_16x16x32_bf16 v[66:69], v[200:203], v[216:219], v[66:69]
	s_add_i32 m0, s100, 0x8000
	s_barrier
; #define WAIT_V(n) asm volatile("s_waitcnt vmcnt(" #n ")" ::: "memory")
; #define WAIT_L(n) asm volatile("s_waitcnt lgkmcnt(" #n ")" ::: "memory")
; #define BAR __builtin_amdgcn_s_barrier()
; #define SCHED __builtin_amdgcn_sched_barrier(0)
; __device__ __forceinline__ void mainloop_8phase(const u16* __restrict__ A, const u16* __restrict__ Bt, int K,
;                                                 f32x4 (&acc)[2][2][4][2], int wid_s, int ld) {
;     ...
;     LDA(At, 1, 1); STAGE(SA(1, 0), A, brow, t + 3);
;     BAR; WAIT_L(0); MMA(1, 0, At, B0); BAR; SCHED;
;     STAGE(SB(1, 1), Bt, bcol + G_HALF, t + 3);
;     WAIT_V(6); BAR; MMA(1, 1, At, B1); BAR;
;   }
;   { LDB(B0, 0, 0); LDA(At, 0, 0); STAGE(SA(1, 1), A, brow + G_HALF, nt - 1);
;     BAR; WAIT_L(0); MMA(0, 0, At, B0); BAR;
;     LDB(B1, 0, 1); BAR; WAIT_L(0); MMA(0, 1, At, B1); BAR;
	ds_read_b128 v[172:175], v133 offset:49152
	ds_read_b128 v[176:179], v133 offset:50176
	ds_read_b128 v[180:183], v132 offset:49152
	ds_read_b128 v[184:187], v132 offset:50176
	ds_read_b128 v[188:191], v131 offset:49152
	ds_read_b128 v[192:195], v131 offset:50176
	ds_read_b128 v[196:199], v130 offset:49152
	buffer_load_dwordx4 v137, s[88:91], s15 offen lds
	s_add_i32 m0, s100, 0xa000
	ds_read_b128 v[200:203], v130 offset:50176
	buffer_load_dwordx4 v136, s[88:91], s15 offen lds
	s_barrier
	s_waitcnt lgkmcnt(1)
	v_mfma_f32_16x16x32_bf16 v[62:65], v[172:175], v[156:159], v[62:65]
	v_mfma_f32_16x16x32_bf16 v[58:61], v[172:175], v[164:167], v[58:61]
	v_mfma_f32_16x16x32_bf16 v[54:57], v[180:183], v[156:159], v[54:57]
	v_mfma_f32_16x16x32_bf16 v[50:53], v[180:183], v[164:167], v[50:53]
	v_mfma_f32_16x16x32_bf16 v[46:49], v[188:191], v[156:159], v[46:49]
	v_mfma_f32_16x16x32_bf16 v[42:45], v[188:191], v[164:167], v[42:45]
	v_mfma_f32_16x16x32_bf16 v[38:41], v[196:199], v[156:159], v[38:41]
	v_mfma_f32_16x16x32_bf16 v[34:37], v[196:199], v[164:167], v[34:37]
	v_mfma_f32_16x16x32_bf16 v[62:65], v[176:179], v[160:163], v[62:65]
	v_mfma_f32_16x16x32_bf16 v[58:61], v[176:179], v[168:171], v[58:61]
	v_mfma_f32_16x16x32_bf16 v[54:57], v[184:187], v[160:163], v[54:57]
	v_mfma_f32_16x16x32_bf16 v[50:53], v[184:187], v[168:171], v[50:53]
	v_mfma_f32_16x16x32_bf16 v[46:49], v[192:195], v[160:163], v[46:49]
	v_mfma_f32_16x16x32_bf16 v[42:45], v[192:195], v[168:171], v[42:45]
	s_waitcnt lgkmcnt(0)
	v_mfma_f32_16x16x32_bf16 v[38:41], v[200:203], v[160:163], v[38:41]
	v_mfma_f32_16x16x32_bf16 v[34:37], v[200:203], v[168:171], v[34:37]
	s_barrier
	s_add_i32 m0, s100, 0x1c000
	s_nop 0
	buffer_load_dwordx4 v137, s[4:7], s1 offen lds
	s_add_i32 m0, s100, 0x1e000
	s_nop 0
	buffer_load_dwordx4 v136, s[4:7], s1 offen lds
	s_waitcnt vmcnt(6)
	s_barrier
	v_mfma_f32_16x16x32_bf16 v[30:33], v[172:175], v[204:207], v[30:33]
	v_mfma_f32_16x16x32_bf16 v[26:29], v[172:175], v[212:215], v[26:29]
	v_mfma_f32_16x16x32_bf16 v[22:25], v[180:183], v[204:207], v[22:25]
	v_mfma_f32_16x16x32_bf16 v[18:21], v[180:183], v[212:215], v[18:21]
	v_mfma_f32_16x16x32_bf16 v[14:17], v[188:191], v[204:207], v[14:17]
	v_mfma_f32_16x16x32_bf16 v[10:13], v[188:191], v[212:215], v[10:13]
	v_mfma_f32_16x16x32_bf16 v[6:9], v[196:199], v[204:207], v[6:9]
	v_mfma_f32_16x16x32_bf16 v[2:5], v[196:199], v[212:215], v[2:5]
	v_mfma_f32_16x16x32_bf16 v[30:33], v[176:179], v[208:211], v[30:33]
	v_mfma_f32_16x16x32_bf16 v[26:29], v[176:179], v[216:219], v[26:29]
	v_mfma_f32_16x16x32_bf16 v[22:25], v[184:187], v[208:211], v[22:25]
	v_mfma_f32_16x16x32_bf16 v[18:21], v[184:187], v[216:219], v[18:21]
	v_mfma_f32_16x16x32_bf16 v[14:17], v[192:195], v[208:211], v[14:17]
	v_mfma_f32_16x16x32_bf16 v[10:13], v[192:195], v[216:219], v[10:13]
	v_mfma_f32_16x16x32_bf16 v[6:9], v[200:203], v[208:211], v[6:9]
	v_mfma_f32_16x16x32_bf16 v[2:5], v[200:203], v[216:219], v[2:5]
	s_add_i32 s0, s0, 2
	s_addk_i32 s1, 0x100
	s_cmp_lt_u32 s0, 28
	s_cbranch_scc1 .LBB0_58
	s_barrier
	v_readfirstlane_b32 s0, v145
	s_mov_b32 m0, s0
	s_mov_b32 s1, 0x80f80
	v_readfirstlane_b32 s0, v144
	ds_read_b128 v[138:141], v155
	ds_read_b128 v[148:151], v155 offset:1024
	ds_read_b128 v[156:159], v155 offset:2048
	ds_read_b128 v[152:155], v155 offset:3072
	ds_read_b128 v[160:163], v133
	ds_read_b128 v[164:167], v133 offset:1024
	ds_read_b128 v[168:171], v132
	ds_read_b128 v[172:175], v132 offset:1024
	ds_read_b128 v[176:179], v131
	ds_read_b128 v[180:183], v131 offset:1024
	ds_read_b128 v[184:187], v130
	ds_read_b128 v[188:191], v130 offset:1024
	buffer_load_dwordx4 v137, s[88:91], s1 offen lds
	s_mov_b32 m0, s0
	s_nop 0
	buffer_load_dwordx4 v136, s[88:91], s1 offen lds
	s_barrier
	s_waitcnt lgkmcnt(0)
	v_mfma_f32_16x16x32_bf16 v[126:129], v[160:163], v[138:141], v[126:129]
	v_mfma_f32_16x16x32_bf16 v[122:125], v[160:163], v[156:159], v[122:125]
	v_mfma_f32_16x16x32_bf16 v[118:121], v[168:171], v[138:141], v[118:121]
	v_mfma_f32_16x16x32_bf16 v[114:117], v[168:171], v[156:159], v[114:117]
	v_mfma_f32_16x16x32_bf16 v[102:105], v[184:187], v[138:141], v[102:105]
	v_mfma_f32_16x16x32_bf16 v[98:101], v[184:187], v[156:159], v[98:101]
	v_mfma_f32_16x16x32_bf16 v[126:129], v[164:167], v[148:151], v[126:129]
	v_mfma_f32_16x16x32_bf16 v[122:125], v[164:167], v[152:155], v[122:125]
	v_mfma_f32_16x16x32_bf16 v[118:121], v[172:175], v[148:151], v[118:121]
	v_mfma_f32_16x16x32_bf16 v[114:117], v[172:175], v[152:155], v[114:117]
	v_mfma_f32_16x16x32_bf16 v[110:113], v[176:179], v[138:141], v[110:113]
	v_mfma_f32_16x16x32_bf16 v[106:109], v[176:179], v[156:159], v[106:109]
	v_mfma_f32_16x16x32_bf16 v[102:105], v[188:191], v[148:151], v[102:105]
	v_mfma_f32_16x16x32_bf16 v[98:101], v[188:191], v[152:155], v[98:101]
	v_mfma_f32_16x16x32_bf16 v[142:145], v[180:183], v[148:151], v[110:113]
	v_mfma_f32_16x16x32_bf16 v[192:195], v[180:183], v[152:155], v[106:109]
	s_barrier
	s_nop 0
	ds_read_b128 v[106:109], v147
	ds_read_b128 v[110:113], v147 offset:1024
	ds_read_b128 v[196:199], v147 offset:2048
	ds_read_b128 v[200:203], v147 offset:3072
	s_barrier
; #define WAIT_V(n) asm volatile("s_waitcnt vmcnt(" #n ")" ::: "memory")
; #define WAIT_L(n) asm volatile("s_waitcnt lgkmcnt(" #n ")" ::: "memory")
; #define BAR __builtin_amdgcn_s_barrier()
; __device__ __forceinline__ void mainloop_8phase(const u16* __restrict__ A, const u16* __restrict__ Bt, int K,
;                                                 f32x4 (&acc)[2][2][4][2], int wid_s, int ld) {
;     ...
;     LDB(B1, 0, 1); BAR; WAIT_L(0); MMA(0, 1, At, B1); BAR;
;     LDA(At, 0, 1); WAIT_V(4); BAR; WAIT_L(0); MMA(1, 0, At, B0); MMA(1, 1, At, B1); BAR; }
;   { LDB(B0, 1, 0); LDA(At, 1, 0); WAIT_V(2); BAR; WAIT_L(0); MMA(0, 0, At, B0); BAR;
	s_waitcnt lgkmcnt(0)
	v_mfma_f32_16x16x32_bf16 v[86:89], v[168:171], v[106:109], v[86:89]
	v_mfma_f32_16x16x32_bf16 v[82:85], v[168:171], v[196:199], v[82:85]
	v_mfma_f32_16x16x32_bf16 v[70:73], v[184:187], v[106:109], v[70:73]
	v_mfma_f32_16x16x32_bf16 v[66:69], v[184:187], v[196:199], v[66:69]
	v_mfma_f32_16x16x32_bf16 v[94:97], v[160:163], v[106:109], v[94:97]
	v_mfma_f32_16x16x32_bf16 v[90:93], v[160:163], v[196:199], v[90:93]
	v_mfma_f32_16x16x32_bf16 v[86:89], v[172:175], v[110:113], v[86:89]
	v_mfma_f32_16x16x32_bf16 v[82:85], v[172:175], v[200:203], v[82:85]
	v_mfma_f32_16x16x32_bf16 v[78:81], v[176:179], v[106:109], v[78:81]
	v_mfma_f32_16x16x32_bf16 v[74:77], v[176:179], v[196:199], v[74:77]
	v_mfma_f32_16x16x32_bf16 v[70:73], v[188:191], v[110:113], v[70:73]
	v_mfma_f32_16x16x32_bf16 v[66:69], v[188:191], v[200:203], v[66:69]
	v_mfma_f32_16x16x32_bf16 v[204:207], v[164:167], v[110:113], v[94:97]
	v_mfma_f32_16x16x32_bf16 v[160:163], v[164:167], v[200:203], v[90:93]
	v_mfma_f32_16x16x32_bf16 v[164:167], v[180:183], v[110:113], v[78:81]
	v_mfma_f32_16x16x32_bf16 v[168:171], v[180:183], v[200:203], v[74:77]
	s_barrier
	s_nop 0
	ds_read_b128 v[74:77], v133 offset:16384
	ds_read_b128 v[78:81], v133 offset:17408
	ds_read_b128 v[90:93], v132 offset:16384
	ds_read_b128 v[94:97], v132 offset:17408
	ds_read_b128 v[172:175], v131 offset:16384
	ds_read_b128 v[176:179], v131 offset:17408
	ds_read_b128 v[180:183], v130 offset:16384
	ds_read_b128 v[184:187], v130 offset:17408
	s_waitcnt vmcnt(4)
	s_barrier
	s_waitcnt lgkmcnt(0)
	v_mfma_f32_16x16x32_bf16 v[62:65], v[74:77], v[138:141], v[62:65]
	v_mfma_f32_16x16x32_bf16 v[58:61], v[74:77], v[156:159], v[58:61]
	v_mfma_f32_16x16x32_bf16 v[54:57], v[90:93], v[138:141], v[54:57]
	v_mfma_f32_16x16x32_bf16 v[50:53], v[90:93], v[156:159], v[50:53]
	v_mfma_f32_16x16x32_bf16 v[38:41], v[180:183], v[138:141], v[38:41]
	v_mfma_f32_16x16x32_bf16 v[34:37], v[180:183], v[156:159], v[34:37]
	v_mfma_f32_16x16x32_bf16 v[62:65], v[78:81], v[148:151], v[62:65]
	v_mfma_f32_16x16x32_bf16 v[58:61], v[78:81], v[152:155], v[58:61]
	v_mfma_f32_16x16x32_bf16 v[54:57], v[94:97], v[148:151], v[54:57]
	v_mfma_f32_16x16x32_bf16 v[50:53], v[94:97], v[152:155], v[50:53]
	v_mfma_f32_16x16x32_bf16 v[46:49], v[172:175], v[138:141], v[46:49]
	v_mfma_f32_16x16x32_bf16 v[42:45], v[172:175], v[156:159], v[42:45]
	v_mfma_f32_16x16x32_bf16 v[38:41], v[184:187], v[148:151], v[38:41]
	v_mfma_f32_16x16x32_bf16 v[34:37], v[184:187], v[152:155], v[34:37]
	v_mfma_f32_16x16x32_bf16 v[188:191], v[176:179], v[148:151], v[46:49]
	v_mfma_f32_16x16x32_bf16 v[208:211], v[176:179], v[152:155], v[42:45]
	v_mfma_f32_16x16x32_bf16 v[22:25], v[90:93], v[106:109], v[22:25]
	v_mfma_f32_16x16x32_bf16 v[18:21], v[90:93], v[196:199], v[18:21]
	v_mfma_f32_16x16x32_bf16 v[6:9], v[180:183], v[106:109], v[6:9]
	v_mfma_f32_16x16x32_bf16 v[2:5], v[180:183], v[196:199], v[2:5]
	v_mfma_f32_16x16x32_bf16 v[30:33], v[74:77], v[106:109], v[30:33]
	v_mfma_f32_16x16x32_bf16 v[26:29], v[74:77], v[196:199], v[26:29]
	v_mfma_f32_16x16x32_bf16 v[22:25], v[94:97], v[110:113], v[22:25]
	v_mfma_f32_16x16x32_bf16 v[18:21], v[94:97], v[200:203], v[18:21]
	v_mfma_f32_16x16x32_bf16 v[14:17], v[172:175], v[106:109], v[14:17]
	v_mfma_f32_16x16x32_bf16 v[10:13], v[172:175], v[196:199], v[10:13]
	v_mfma_f32_16x16x32_bf16 v[6:9], v[184:187], v[110:113], v[6:9]
	v_mfma_f32_16x16x32_bf16 v[2:5], v[184:187], v[200:203], v[2:5]
	v_mfma_f32_16x16x32_bf16 v[136:139], v[78:81], v[110:113], v[30:33]
	v_mfma_f32_16x16x32_bf16 v[146:149], v[78:81], v[200:203], v[26:29]
	v_mfma_f32_16x16x32_bf16 v[150:153], v[176:179], v[110:113], v[14:17]
	v_mfma_f32_16x16x32_bf16 v[154:157], v[176:179], v[200:203], v[10:13]
	s_barrier
	s_nop 0
	ds_read_b128 v[10:13], v135
	ds_read_b128 v[14:17], v135 offset:1024
	ds_read_b128 v[172:175], v135 offset:2048
	ds_read_b128 v[176:179], v135 offset:3072
	ds_read_b128 v[26:29], v133 offset:32768
	ds_read_b128 v[30:33], v133 offset:33792
	ds_read_b128 v[42:45], v132 offset:32768
	ds_read_b128 v[46:49], v132 offset:33792
	ds_read_b128 v[180:183], v131 offset:32768
	ds_read_b128 v[184:187], v131 offset:33792
	ds_read_b128 v[196:199], v130 offset:32768
	ds_read_b128 v[200:203], v130 offset:33792
	s_waitcnt vmcnt(2)
	s_barrier
; #define WAIT_V(n) asm volatile("s_waitcnt vmcnt(" #n ")" ::: "memory")
; #define WAIT_L(n) asm volatile("s_waitcnt lgkmcnt(" #n ")" ::: "memory")
; #define BAR __builtin_amdgcn_s_barrier()
; __device__ __forceinline__ void mainloop_8phase(const u16* __restrict__ A, const u16* __restrict__ Bt, int K,
;                                                 f32x4 (&acc)[2][2][4][2], int wid_s, int ld) {
;     ...
;   { LDB(B0, 1, 0); LDA(At, 1, 0); WAIT_V(2); BAR; WAIT_L(0); MMA(0, 0, At, B0); BAR;
;     LDB(B1, 1, 1); WAIT_V(0); BAR; WAIT_L(0); MMA(0, 1, At, B1); BAR;
;     LDA(At, 1, 1); BAR; WAIT_L(0); MMA(1, 0, At, B0); MMA(1, 1, At, B1); BAR; }
;   if (wr == 0) BAR;
	s_waitcnt lgkmcnt(0)
	v_mfma_f32_16x16x32_bf16 v[74:77], v[26:29], v[10:13], v[126:129]
	v_mfma_f32_16x16x32_bf16 v[126:129], v[30:33], v[14:17], v[74:77]
	v_mfma_f32_16x16x32_bf16 v[74:77], v[26:29], v[172:175], v[122:125]
	v_mfma_f32_16x16x32_bf16 v[122:125], v[30:33], v[176:179], v[74:77]
	v_mfma_f32_16x16x32_bf16 v[74:77], v[42:45], v[10:13], v[118:121]
	v_mfma_f32_16x16x32_bf16 v[110:113], v[46:49], v[14:17], v[74:77]
	v_mfma_f32_16x16x32_bf16 v[74:77], v[42:45], v[172:175], v[114:117]
	v_mfma_f32_16x16x32_bf16 v[106:109], v[46:49], v[176:179], v[74:77]
	v_mfma_f32_16x16x32_bf16 v[74:77], v[180:183], v[10:13], v[142:145]
	v_mfma_f32_16x16x32_bf16 v[94:97], v[184:187], v[14:17], v[74:77]
	v_mfma_f32_16x16x32_bf16 v[74:77], v[180:183], v[172:175], v[192:195]
	v_mfma_f32_16x16x32_bf16 v[90:93], v[184:187], v[176:179], v[74:77]
	v_mfma_f32_16x16x32_bf16 v[74:77], v[196:199], v[10:13], v[102:105]
	v_mfma_f32_16x16x32_bf16 v[78:81], v[200:203], v[14:17], v[74:77]
	v_mfma_f32_16x16x32_bf16 v[74:77], v[196:199], v[172:175], v[98:101]
	v_mfma_f32_16x16x32_bf16 v[74:77], v[200:203], v[176:179], v[74:77]
	s_barrier
	ds_read_b128 v[140:143], v134
	ds_read_b128 v[192:195], v134 offset:1024
	ds_read_b128 v[212:215], v134 offset:2048
	ds_read_b128 v[216:219], v134 offset:3072
	s_waitcnt vmcnt(0)
	s_barrier
	s_waitcnt lgkmcnt(0)
	v_mfma_f32_16x16x32_bf16 v[98:101], v[26:29], v[140:143], v[204:207]
	v_mfma_f32_16x16x32_bf16 v[26:29], v[26:29], v[212:215], v[160:163]
	v_mfma_f32_16x16x32_bf16 v[114:117], v[30:33], v[216:219], v[26:29]
	v_mfma_f32_16x16x32_bf16 v[26:29], v[42:45], v[140:143], v[86:89]
	v_mfma_f32_16x16x32_bf16 v[102:105], v[46:49], v[192:195], v[26:29]
	v_mfma_f32_16x16x32_bf16 v[26:29], v[42:45], v[212:215], v[82:85]
	v_mfma_f32_16x16x32_bf16 v[118:121], v[30:33], v[192:195], v[98:101]
	v_mfma_f32_16x16x32_bf16 v[98:101], v[46:49], v[216:219], v[26:29]
	v_mfma_f32_16x16x32_bf16 v[26:29], v[180:183], v[140:143], v[164:167]
	v_mfma_f32_16x16x32_bf16 v[86:89], v[184:187], v[192:195], v[26:29]
	v_mfma_f32_16x16x32_bf16 v[26:29], v[180:183], v[212:215], v[168:171]
	v_mfma_f32_16x16x32_bf16 v[82:85], v[184:187], v[216:219], v[26:29]
	v_mfma_f32_16x16x32_bf16 v[26:29], v[196:199], v[140:143], v[70:73]
	v_mfma_f32_16x16x32_bf16 v[70:73], v[200:203], v[192:195], v[26:29]
	v_mfma_f32_16x16x32_bf16 v[26:29], v[196:199], v[212:215], v[66:69]
	v_mfma_f32_16x16x32_bf16 v[66:69], v[200:203], v[216:219], v[26:29]
	s_barrier
	ds_read_b128 v[158:161], v133 offset:49152
	ds_read_b128 v[162:165], v133 offset:50176
	ds_read_b128 v[166:169], v132 offset:49152
	ds_read_b128 v[132:135], v132 offset:50176
	ds_read_b128 v[180:183], v131 offset:49152
	ds_read_b128 v[184:187], v131 offset:50176
	ds_read_b128 v[196:199], v130 offset:49152
	ds_read_b128 v[200:203], v130 offset:50176
	s_barrier
	s_waitcnt lgkmcnt(0)
	v_mfma_f32_16x16x32_bf16 v[26:29], v[158:161], v[10:13], v[62:65]
	v_mfma_f32_16x16x32_bf16 v[62:65], v[162:165], v[14:17], v[26:29]
	v_mfma_f32_16x16x32_bf16 v[26:29], v[158:161], v[172:175], v[58:61]
	v_mfma_f32_16x16x32_bf16 v[58:61], v[162:165], v[176:179], v[26:29]
	v_mfma_f32_16x16x32_bf16 v[26:29], v[166:169], v[10:13], v[54:57]
	v_mfma_f32_16x16x32_bf16 v[46:49], v[132:135], v[14:17], v[26:29]
	v_mfma_f32_16x16x32_bf16 v[26:29], v[166:169], v[172:175], v[50:53]
	v_mfma_f32_16x16x32_bf16 v[42:45], v[132:135], v[176:179], v[26:29]
	v_mfma_f32_16x16x32_bf16 v[26:29], v[180:183], v[10:13], v[188:191]
	v_mfma_f32_16x16x32_bf16 v[10:13], v[196:199], v[10:13], v[38:41]
	v_mfma_f32_16x16x32_bf16 v[30:33], v[184:187], v[14:17], v[26:29]
	v_mfma_f32_16x16x32_bf16 v[26:29], v[180:183], v[172:175], v[208:211]
	v_mfma_f32_16x16x32_bf16 v[14:17], v[200:203], v[14:17], v[10:13]
	v_mfma_f32_16x16x32_bf16 v[10:13], v[196:199], v[172:175], v[34:37]
	v_mfma_f32_16x16x32_bf16 v[26:29], v[184:187], v[176:179], v[26:29]
	v_mfma_f32_16x16x32_bf16 v[10:13], v[200:203], v[176:179], v[10:13]
	v_mfma_f32_16x16x32_bf16 v[34:37], v[158:161], v[140:143], v[136:139]
	v_mfma_f32_16x16x32_bf16 v[54:57], v[162:165], v[192:195], v[34:37]
	v_mfma_f32_16x16x32_bf16 v[34:37], v[158:161], v[212:215], v[146:149]
	v_mfma_f32_16x16x32_bf16 v[18:21], v[166:169], v[212:215], v[18:21]
	v_mfma_f32_16x16x32_bf16 v[50:53], v[162:165], v[216:219], v[34:37]
	v_mfma_f32_16x16x32_bf16 v[22:25], v[166:169], v[140:143], v[22:25]
	v_mfma_f32_16x16x32_bf16 v[34:37], v[132:135], v[216:219], v[18:21]
	v_mfma_f32_16x16x32_bf16 v[18:21], v[180:183], v[140:143], v[150:153]
	v_mfma_f32_16x16x32_bf16 v[38:41], v[132:135], v[192:195], v[22:25]
	v_mfma_f32_16x16x32_bf16 v[22:25], v[184:187], v[192:195], v[18:21]
	v_mfma_f32_16x16x32_bf16 v[18:21], v[180:183], v[212:215], v[154:157]
	v_mfma_f32_16x16x32_bf16 v[6:9], v[196:199], v[140:143], v[6:9]
	v_mfma_f32_16x16x32_bf16 v[2:5], v[196:199], v[212:215], v[2:5]
	v_mfma_f32_16x16x32_bf16 v[18:21], v[184:187], v[216:219], v[18:21]
	v_mfma_f32_16x16x32_bf16 v[6:9], v[200:203], v[192:195], v[6:9]
	v_mfma_f32_16x16x32_bf16 v[2:5], v[200:203], v[216:219], v[2:5]
	s_movk_i32 s0, 0x100
	v_cmp_gt_u32_e32 vcc, s0, v0
	s_barrier
	s_and_saveexec_b64 s[0:1], vcc
	s_cbranch_execz .LBB0_61
	s_barrier

; #define WAIT_V(n) asm volatile("s_waitcnt vmcnt(" #n ")" ::: "memory")
; #define BAR __builtin_amdgcn_s_barrier()
; __device__ __forceinline__ void mainloop_8phase(const u16* __restrict__ A, const u16* __restrict__ Bt, int K,
;                                                 f32x4 (&acc)[2][2][4][2], int wid_s, int ld) {
;     ...
;   int tid = get_tid(wid_s), wid = tid >> 6, lane = tid & 63, wr = wid >> 2, wc = wid & 3, fr = lane & 15, fq = lane >> 4;
;   unsigned goff0, goff1;
;   {
;     int r0, c0, r1, c1;
;     stage_rc(tid * 16, r0, c0);
;     stage_rc(tid * 16 + 8192, r1, c1);
;     goff0 = (unsigned)(r0 * ld + c0) * 2u;
;     goff1 = (unsigned)(r1 * ld + c1) * 2u;
;   }
;   __amdgpu_buffer_rsrc_t rs_A, rs_Bt;
;   {
;     unsigned long ua = (unsigned long)A, ub = (unsigned long)Bt;
;     unsigned alo = __builtin_amdgcn_readfirstlane((unsigned)ua), ahi = __builtin_amdgcn_readfirstlane((unsigned)(ua >> 32));
;     unsigned blo = __builtin_amdgcn_readfirstlane((unsigned)ub), bhi = __builtin_amdgcn_readfirstlane((unsigned)(ub >> 32));
;     rs_A = __builtin_amdgcn_make_buffer_rsrc((void*)(((unsigned long)ahi << 32) | alo), (short)0, 0x7ffffff0, 0x00020000);
;     rs_Bt = __builtin_amdgcn_make_buffer_rsrc((void*)(((unsigned long)bhi << 32) | blo), (short)0, 0x7ffffff0, 0x00020000);
;   }
;   bf16x8 At[4][2], B0[2][2], B1[2][2];
;   const int brow = 0, bcol = 0;
;   int nt = K / G_BK;
;   if (wr == 1) BAR;
;   WAIT_V(0); BAR;
;   STAGE(SB(1, 0), Bt, bcol, 1); STAGE(SA(1, 0), A, brow, 1); STAGE(SB(1, 1), Bt, bcol + G_HALF, 1);
;   WAIT_V(6); BAR;
;     ...
;     f32x4 acc[2][2][4][2];
; #pragma unroll
;     for (int a = 0; a < 2; ++a)
; #pragma unroll
;       for (int b = 0; b < 2; ++b)
; #pragma unroll
;         for (int c = 0; c < 4; ++c)
; #pragma unroll
;           for (int d = 0; d < 2; ++d) acc[a][b][c][d] = f32x4{0.f, 0.f, 0.f, 0.f};
.LBB0_161:
	s_or_b64 exec, exec, s[2:3]
	v_bfe_i32 v8, v0, 27, 1
	v_lshlrev_b32_e32 v6, 4, v0
	v_lshrrev_b32_e32 v8, 22, v8
	v_add_u32_e32 v8, v6, v8
	v_and_b32_e32 v8, 0xfffffc00, v8
	v_sub_u32_e32 v8, v6, v8
	v_lshrrev_b32_e32 v9, 4, v8
	v_ashrrev_i32_e32 v7, 31, v0
	v_bitop3_b32 v8, v9, v8, 32 bitop3:0x6c
	v_lshrrev_b32_e32 v7, 26, v7
	v_ashrrev_i32_e32 v10, 31, v8
	v_add_u32_e32 v7, v0, v7
	v_lshrrev_b32_e32 v10, 26, v10
	v_ashrrev_i32_e32 v7, 6, v7
	v_add_u32_e32 v10, v8, v10
	v_lshlrev_b32_e32 v9, 3, v7
	v_lshrrev_b32_e32 v11, 6, v10
	v_and_b32_e32 v10, 0xc0, v10
	v_and_b32_e32 v9, 0xffff0, v9
	v_sub_u32_e32 v8, v8, v10
	v_add_u32_e32 v10, 0x2000, v6
	v_add_u32_e32 v9, v11, v9
	v_ashrrev_i32_e32 v11, 31, v10
	v_lshrrev_b32_e32 v11, 22, v11
	v_add_u32_e32 v11, v10, v11
	v_ashrrev_i32_e32 v11, 10, v11
	v_mul_i32_i24_e32 v12, 0x400, v11
	v_sub_u32_e32 v10, v10, v12
	v_lshrrev_b32_e32 v12, 4, v10
	v_bitop3_b32 v10, v12, v10, 32 bitop3:0x6c
	v_ashrrev_i32_e32 v13, 31, v10
	v_lshrrev_b32_e32 v13, 26, v13
	v_add_u32_e32 v13, v10, v13
	v_lshlrev_b32_e32 v7, 5, v7
	v_lshlrev_b32_e32 v12, 3, v11
	v_lshrrev_b32_e32 v14, 6, v13
	v_and_b32_e32 v13, 0xc0, v13
	v_readlane_b32 s6, v254, 43
	v_and_b32_e32 v7, 32, v7
	v_ashrrev_i16_sdwa v8, v244, sext(v8) dst_sel:DWORD dst_unused:UNUSED_PAD src0_sel:DWORD src1_sel:BYTE_0
	v_and_b32_e32 v12, 0xffff0, v12
	v_lshlrev_b32_e32 v11, 5, v11
	v_sub_u32_e32 v10, v10, v13
	s_waitcnt vmcnt(7)
	v_add_u32_e32 v138, s6, v6
	v_bfe_i32 v8, v8, 0, 16
	v_add_u32_e32 v12, v14, v12
	v_and_b32_e32 v11, 32, v11
	v_ashrrev_i16_sdwa v10, v244, sext(v10) dst_sel:DWORD dst_unused:UNUSED_PAD src0_sel:DWORD src1_sel:BYTE_0
	v_lshl_or_b32 v7, v9, 11, v7
	s_and_b32 s5, s13, 0xffff
	v_readfirstlane_b32 s2, v138
	v_add_u32_e32 v139, 0x2000, v138
	v_add_u32_e32 v140, 16, v6
	v_bfe_i32 v10, v10, 0, 16
	v_add_lshl_u32 v137, v7, v8, 1
	v_lshl_or_b32 v7, v12, 11, v11
	s_mov_b32 s24, s12
	s_mov_b32 s25, s5
	s_mov_b32 s26, s90
	s_mov_b32 s27, s91
	s_mov_b32 m0, s2
	s_movk_i32 s3, 0x80
	v_readfirstlane_b32 s2, v139
	v_add_u32_e32 v141, 0x8000, v140
	v_add_lshl_u32 v136, v7, v10, 1
	s_and_b32 s89, s1, 0xffff
	s_waitcnt vmcnt(0)
	s_barrier
	buffer_load_dwordx4 v137, s[24:27], s3 offen lds
	s_mov_b32 m0, s2
	v_readfirstlane_b32 s2, v141
	v_add_u32_e32 v142, 0xa000, v140
	v_readlane_b32 s7, v254, 44
	s_mov_b32 s16, s0
	s_mov_b32 s17, s89
	s_mov_b32 s18, s90
	s_mov_b32 s19, s91
	buffer_load_dwordx4 v136, s[24:27], s3 offen lds
	s_mov_b32 m0, s2
	v_readfirstlane_b32 s2, v142
	v_add_u32_e32 v143, s7, v6
	buffer_load_dwordx4 v137, s[16:19], s3 offen lds
	s_mov_b32 m0, s2
	v_readfirstlane_b32 s2, v143
	v_add_u32_e32 v144, 0x2000, v143
	buffer_load_dwordx4 v136, s[16:19], s3 offen lds
	s_mov_b32 m0, s2
	s_mov_b32 s3, 0x80080
	v_readfirstlane_b32 s2, v144
	buffer_load_dwordx4 v137, s[24:27], s3 offen lds
	s_mov_b32 m0, s2
	v_and_b32_e32 v4, 15, v2
	buffer_load_dwordx4 v136, s[24:27], s3 offen lds
	v_lshlrev_b32_e32 v7, 2, v2
	v_and_b32_e32 v5, 48, v2
	v_lshlrev_b32_e32 v4, 6, v4
	v_and_b32_e32 v7, 32, v7
	v_bitop3_b32 v4, v4, v7, v5 bitop3:0x36
	v_readlane_b32 s2, v254, 41
	v_lshlrev_b32_e32 v2, 6, v2
	s_waitcnt vmcnt(6)
	v_readlane_b32 s3, v254, 42
	v_add_u32_e32 v8, s2, v4
	v_add_u32_e32 v146, s2, v6
	s_movk_i32 s2, 0x3c0
	v_lshlrev_b32_e32 v11, 6, v0
	v_lshlrev_b32_e32 v3, 13, v3
	v_and_or_b32 v2, v2, s2, v5
	v_add_u32_e32 v9, s3, v4
	v_add_u32_e32 v147, s3, v6
	v_add_u32_e32 v6, s6, v4
	v_add_u32_e32 v10, s7, v4
	v_and_b32_e32 v11, 0x3000, v11
	v_add_u32_e32 v4, 16, v4
	v_xad_u32 v5, v2, v7, 16
	v_or_b32_e32 v7, 0x800, v3
	v_or_b32_e32 v12, 0x1000, v3
	v_or_b32_e32 v13, 0x1800, v3
	v_mov_b32_e32 v2, 0
	s_mov_b32 s88, s0
	s_mov_b32 s4, s12
	s_mov_b32 s2, -2
	s_mov_b32 s3, 0x80180
	v_add_u32_e32 v148, v8, v11
	s_waitcnt lgkmcnt(0)
	v_add_u32_e32 v133, v4, v3
	v_add_u32_e32 v132, v5, v7
	v_add_u32_e32 v131, v5, v12
	v_add_u32_e32 v130, v5, v13
	v_add_u32_e32 v145, v9, v11
	v_add_u32_e32 v135, v6, v11
	v_add_u32_e32 v134, v10, v11
	v_mov_b32_e32 v3, v2
	v_mov_b32_e32 v4, v2
	v_mov_b32_e32 v5, v2
	v_mov_b32_e32 v6, v2
	v_mov_b32_e32 v7, v2
	v_mov_b32_e32 v8, v2
	v_mov_b32_e32 v9, v2
	v_mov_b32_e32 v10, v2
	v_mov_b32_e32 v11, v2
	v_mov_b32_e32 v12, v2
	v_mov_b32_e32 v13, v2
	v_mov_b32_e32 v14, v2
	v_mov_b32_e32 v15, v2
	v_mov_b32_e32 v16, v2
	v_mov_b32_e32 v17, v2
	v_mov_b32_e32 v18, v2
	v_mov_b32_e32 v19, v2
	v_mov_b32_e32 v20, v2
	v_mov_b32_e32 v21, v2
	v_mov_b32_e32 v22, v2
	v_mov_b32_e32 v23, v2
	v_mov_b32_e32 v24, v2
	v_mov_b32_e32 v25, v2
	v_mov_b32_e32 v26, v2
	v_mov_b32_e32 v27, v2
	v_mov_b32_e32 v28, v2
	v_mov_b32_e32 v29, v2
	v_mov_b32_e32 v30, v2
	v_mov_b32_e32 v31, v2
	v_mov_b32_e32 v32, v2
	v_mov_b32_e32 v33, v2
	v_mov_b32_e32 v34, v2
	v_mov_b32_e32 v35, v2
	v_mov_b32_e32 v36, v2
	v_mov_b32_e32 v37, v2
	v_mov_b32_e32 v38, v2
	v_mov_b32_e32 v39, v2
	v_mov_b32_e32 v40, v2
	v_mov_b32_e32 v41, v2
	v_mov_b32_e32 v42, v2
	v_mov_b32_e32 v43, v2
	v_mov_b32_e32 v44, v2
	v_mov_b32_e32 v45, v2
	v_mov_b32_e32 v46, v2
	v_mov_b32_e32 v47, v2
	v_mov_b32_e32 v48, v2
	v_mov_b32_e32 v49, v2
	v_mov_b32_e32 v50, v2
	v_mov_b32_e32 v51, v2
	v_mov_b32_e32 v52, v2
	v_mov_b32_e32 v53, v2
	v_mov_b32_e32 v54, v2
	v_mov_b32_e32 v55, v2
	v_mov_b32_e32 v56, v2
	v_mov_b32_e32 v57, v2
	v_mov_b32_e32 v58, v2
	v_mov_b32_e32 v59, v2
	v_mov_b32_e32 v60, v2
	v_mov_b32_e32 v61, v2
	v_mov_b32_e32 v62, v2
	v_mov_b32_e32 v63, v2
	v_mov_b32_e32 v64, v2
	v_mov_b32_e32 v65, v2
	v_mov_b32_e32 v66, v2
	v_mov_b32_e32 v67, v2
	s_waitcnt vmcnt(9)
	v_mov_b32_e32 v68, v2
	v_mov_b32_e32 v69, v2
	v_mov_b32_e32 v70, v2
	v_mov_b32_e32 v71, v2
	s_waitcnt vmcnt(8)
; #define WAIT_L(n) asm volatile("s_waitcnt lgkmcnt(" #n ")" ::: "memory")
; #define BAR __builtin_amdgcn_s_barrier()
; #define SCHED __builtin_amdgcn_sched_barrier(0)
; __device__ __forceinline__ void mainloop_8phase(const u16* __restrict__ A, const u16* __restrict__ Bt, int K,
;                                                 f32x4 (&acc)[2][2][4][2], int wid_s, int ld) {
;     ...
;   for (int t = 0; t < nt - 2; t += 2) {
;     LDB(B0, 0, 0); SCHED; LDA(At, 0, 0); STAGE(SA(1, 1), A, brow + G_HALF, t + 1);
;     WAIT_L(8); BAR; WAIT_L(0); MMA(0, 0, At, B0); BAR; SCHED;
;     LDB(B1, 0, 1); STAGE(SB(0, 0), Bt, bcol, t + 2);
;     BAR; WAIT_L(0); MMA(0, 1, At, B1); BAR;
;     LDA(At, 0, 1); STAGE(SA(0, 0), A, brow, t + 2);
;     BAR; WAIT_L(0); MMA(1, 0, At, B0); BAR; SCHED;
	v_mov_b32_e32 v72, v2
	v_mov_b32_e32 v73, v2
	v_mov_b32_e32 v74, v2
	v_mov_b32_e32 v75, v2
	s_waitcnt vmcnt(7)
	v_mov_b32_e32 v76, v2
	v_mov_b32_e32 v77, v2
	v_mov_b32_e32 v78, v2
	v_mov_b32_e32 v79, v2
	s_waitcnt vmcnt(6)
	v_mov_b32_e32 v80, v2
	v_mov_b32_e32 v81, v2
	v_mov_b32_e32 v82, v2
	v_mov_b32_e32 v83, v2
	v_mov_b32_e32 v84, v2
	v_mov_b32_e32 v85, v2
	v_mov_b32_e32 v86, v2
	v_mov_b32_e32 v87, v2
	v_mov_b32_e32 v88, v2
	v_mov_b32_e32 v89, v2
	v_mov_b32_e32 v90, v2
	v_mov_b32_e32 v91, v2
	v_mov_b32_e32 v92, v2
	v_mov_b32_e32 v93, v2
	v_mov_b32_e32 v94, v2
	v_mov_b32_e32 v95, v2
	v_mov_b32_e32 v96, v2
	v_mov_b32_e32 v97, v2
	v_mov_b32_e32 v98, v2
	v_mov_b32_e32 v99, v2
	v_mov_b32_e32 v100, v2
	v_mov_b32_e32 v101, v2
	v_mov_b32_e32 v102, v2
	v_mov_b32_e32 v103, v2
	v_mov_b32_e32 v104, v2
	v_mov_b32_e32 v105, v2
	v_mov_b32_e32 v106, v2
	v_mov_b32_e32 v107, v2
	v_mov_b32_e32 v108, v2
	v_mov_b32_e32 v109, v2
	v_mov_b32_e32 v110, v2
	v_mov_b32_e32 v111, v2
	v_mov_b32_e32 v112, v2
	v_mov_b32_e32 v113, v2
	v_mov_b32_e32 v114, v2
	v_mov_b32_e32 v115, v2
	v_mov_b32_e32 v116, v2
	v_mov_b32_e32 v117, v2
	v_mov_b32_e32 v118, v2
	v_mov_b32_e32 v119, v2
	v_mov_b32_e32 v120, v2
	v_mov_b32_e32 v121, v2
	v_mov_b32_e32 v122, v2
	v_mov_b32_e32 v123, v2
	v_mov_b32_e32 v124, v2
	v_mov_b32_e32 v125, v2
	v_mov_b32_e32 v126, v2
	v_mov_b32_e32 v127, v2
	v_mov_b32_e32 v128, v2
	v_mov_b32_e32 v129, v2
	v_add_u32_e32 v150, 0xc000, v140
	v_add_u32_e32 v149, 0xe000, v140
	v_add_u32_e32 v151, 0x2000, v146
	v_add_u32_e32 v152, 0x2000, v140
	v_add_u32_e32 v153, 0x2000, v147
	v_add_u32_e32 v154, 0x4000, v140
	v_add_u32_e32 v155, 0x6000, v140
	s_mov_b32 s7, s91
.LBB0_162:
	s_barrier
	ds_read_b128 v[156:159], v148
	ds_read_b128 v[160:163], v148 offset:1024
	ds_read_b128 v[164:167], v148 offset:2048
	ds_read_b128 v[168:171], v148 offset:3072
	s_add_i32 s6, s3, 0xffffff00
	s_add_i32 m0, s100, 0xc000
	ds_read_b128 v[172:175], v133
	ds_read_b128 v[176:179], v133 offset:1024
	ds_read_b128 v[180:183], v132
	ds_read_b128 v[184:187], v132 offset:1024
	ds_read_b128 v[188:191], v131
	ds_read_b128 v[192:195], v131 offset:1024
	ds_read_b128 v[196:199], v130
	buffer_load_dwordx4 v137, s[88:91], s6 offen lds
	s_add_i32 m0, s100, 0xe000
	ds_read_b128 v[200:203], v130 offset:1024
	buffer_load_dwordx4 v136, s[88:91], s6 offen lds
	s_waitcnt lgkmcnt(8)
	s_barrier
	s_waitcnt lgkmcnt(1)
	v_mfma_f32_16x16x32_bf16 v[126:129], v[172:175], v[156:159], v[126:129]
	v_mfma_f32_16x16x32_bf16 v[122:125], v[172:175], v[164:167], v[122:125]
	v_mfma_f32_16x16x32_bf16 v[118:121], v[180:183], v[156:159], v[118:121]
	v_mfma_f32_16x16x32_bf16 v[114:117], v[180:183], v[164:167], v[114:117]
	v_mfma_f32_16x16x32_bf16 v[110:113], v[188:191], v[156:159], v[110:113]
	v_mfma_f32_16x16x32_bf16 v[106:109], v[188:191], v[164:167], v[106:109]
	v_mfma_f32_16x16x32_bf16 v[102:105], v[196:199], v[156:159], v[102:105]
	v_mfma_f32_16x16x32_bf16 v[98:101], v[196:199], v[164:167], v[98:101]
	v_mfma_f32_16x16x32_bf16 v[126:129], v[176:179], v[160:163], v[126:129]
	v_mfma_f32_16x16x32_bf16 v[122:125], v[176:179], v[168:171], v[122:125]
	v_mfma_f32_16x16x32_bf16 v[118:121], v[184:187], v[160:163], v[118:121]
	v_mfma_f32_16x16x32_bf16 v[114:117], v[184:187], v[168:171], v[114:117]
	v_mfma_f32_16x16x32_bf16 v[110:113], v[192:195], v[160:163], v[110:113]
	v_mfma_f32_16x16x32_bf16 v[106:109], v[192:195], v[168:171], v[106:109]
	s_waitcnt lgkmcnt(0)
	v_mfma_f32_16x16x32_bf16 v[102:105], v[200:203], v[160:163], v[102:105]
	v_mfma_f32_16x16x32_bf16 v[98:101], v[200:203], v[168:171], v[98:101]
	s_barrier
	s_add_i32 s15, s3, 0xfff7ff80
	s_mov_b32 s6, s90
	s_add_i32 m0, s100, 0x10000
	ds_read_b128 v[204:207], v145
	ds_read_b128 v[208:211], v145 offset:1024
	ds_read_b128 v[212:215], v145 offset:2048
	buffer_load_dwordx4 v137, s[4:7], s15 offen lds
	s_add_i32 m0, s100, 0x12000
	ds_read_b128 v[216:219], v145 offset:3072
	buffer_load_dwordx4 v136, s[4:7], s15 offen lds
	s_barrier
	s_waitcnt lgkmcnt(1)
	v_mfma_f32_16x16x32_bf16 v[94:97], v[172:175], v[204:207], v[94:97]
	v_mfma_f32_16x16x32_bf16 v[90:93], v[172:175], v[212:215], v[90:93]
	v_mfma_f32_16x16x32_bf16 v[86:89], v[180:183], v[204:207], v[86:89]
	v_mfma_f32_16x16x32_bf16 v[82:85], v[180:183], v[212:215], v[82:85]
	v_mfma_f32_16x16x32_bf16 v[78:81], v[188:191], v[204:207], v[78:81]
	v_mfma_f32_16x16x32_bf16 v[74:77], v[188:191], v[212:215], v[74:77]
	v_mfma_f32_16x16x32_bf16 v[70:73], v[196:199], v[204:207], v[70:73]
	v_mfma_f32_16x16x32_bf16 v[66:69], v[196:199], v[212:215], v[66:69]
	v_mfma_f32_16x16x32_bf16 v[94:97], v[176:179], v[208:211], v[94:97]
	s_waitcnt lgkmcnt(0)
	v_mfma_f32_16x16x32_bf16 v[90:93], v[176:179], v[216:219], v[90:93]
	v_mfma_f32_16x16x32_bf16 v[86:89], v[184:187], v[208:211], v[86:89]
	v_mfma_f32_16x16x32_bf16 v[82:85], v[184:187], v[216:219], v[82:85]
	v_mfma_f32_16x16x32_bf16 v[78:81], v[192:195], v[208:211], v[78:81]
	v_mfma_f32_16x16x32_bf16 v[74:77], v[192:195], v[216:219], v[74:77]
	v_mfma_f32_16x16x32_bf16 v[70:73], v[200:203], v[208:211], v[70:73]
	v_mfma_f32_16x16x32_bf16 v[66:69], v[200:203], v[216:219], v[66:69]
	s_mov_b32 m0, s100
	s_barrier
	ds_read_b128 v[172:175], v133 offset:16384
	ds_read_b128 v[176:179], v133 offset:17408
	ds_read_b128 v[180:183], v132 offset:16384
	ds_read_b128 v[184:187], v132 offset:17408
	ds_read_b128 v[188:191], v131 offset:16384
	ds_read_b128 v[192:195], v131 offset:17408
	ds_read_b128 v[196:199], v130 offset:16384
	buffer_load_dwordx4 v137, s[88:91], s15 offen lds
	s_add_i32 m0, s100, 0x2000
	ds_read_b128 v[200:203], v130 offset:17408
	buffer_load_dwordx4 v136, s[88:91], s15 offen lds
	s_barrier
; #define WAIT_V(n) asm volatile("s_waitcnt vmcnt(" #n ")" ::: "memory")
; #define WAIT_L(n) asm volatile("s_waitcnt lgkmcnt(" #n ")" ::: "memory")
; #define BAR __builtin_amdgcn_s_barrier()
; #define SCHED __builtin_amdgcn_sched_barrier(0)
; __device__ __forceinline__ void mainloop_8phase(const u16* __restrict__ A, const u16* __restrict__ Bt, int K,
;                                                 f32x4 (&acc)[2][2][4][2], int wid_s, int ld) {
;     ...
;     BAR; WAIT_L(0); MMA(1, 0, At, B0); BAR; SCHED;
;     STAGE(SB(0, 1), Bt, bcol + G_HALF, t + 2);
;     WAIT_V(6); BAR; MMA(1, 1, At, B1); BAR;
;     LDB(B0, 1, 0); SCHED; LDA(At, 1, 0); STAGE(SA(0, 1), A, brow + G_HALF, t + 2);
;     WAIT_L(8); BAR; WAIT_L(0); MMA(0, 0, At, B0); BAR; SCHED;
;     LDB(B1, 1, 1); STAGE(SB(1, 0), Bt, bcol, t + 3);
;     BAR; WAIT_L(0); MMA(0, 1, At, B1); BAR;
	s_waitcnt lgkmcnt(1)
	v_mfma_f32_16x16x32_bf16 v[62:65], v[172:175], v[156:159], v[62:65]
	v_mfma_f32_16x16x32_bf16 v[58:61], v[172:175], v[164:167], v[58:61]
	v_mfma_f32_16x16x32_bf16 v[54:57], v[180:183], v[156:159], v[54:57]
	v_mfma_f32_16x16x32_bf16 v[50:53], v[180:183], v[164:167], v[50:53]
	v_mfma_f32_16x16x32_bf16 v[46:49], v[188:191], v[156:159], v[46:49]
	v_mfma_f32_16x16x32_bf16 v[42:45], v[188:191], v[164:167], v[42:45]
	v_mfma_f32_16x16x32_bf16 v[38:41], v[196:199], v[156:159], v[38:41]
	v_mfma_f32_16x16x32_bf16 v[34:37], v[196:199], v[164:167], v[34:37]
	v_mfma_f32_16x16x32_bf16 v[62:65], v[176:179], v[160:163], v[62:65]
	v_mfma_f32_16x16x32_bf16 v[58:61], v[176:179], v[168:171], v[58:61]
	v_mfma_f32_16x16x32_bf16 v[54:57], v[184:187], v[160:163], v[54:57]
	v_mfma_f32_16x16x32_bf16 v[50:53], v[184:187], v[168:171], v[50:53]
	v_mfma_f32_16x16x32_bf16 v[46:49], v[192:195], v[160:163], v[46:49]
	v_mfma_f32_16x16x32_bf16 v[42:45], v[192:195], v[168:171], v[42:45]
	s_waitcnt lgkmcnt(0)
	v_mfma_f32_16x16x32_bf16 v[38:41], v[200:203], v[160:163], v[38:41]
	v_mfma_f32_16x16x32_bf16 v[34:37], v[200:203], v[168:171], v[34:37]
	s_barrier
	s_add_i32 m0, s100, 0x14000
	s_add_i32 s15, s3, 0xffffff80
	buffer_load_dwordx4 v137, s[4:7], s15 offen lds
	s_add_i32 m0, s100, 0x16000
	s_nop 0
	buffer_load_dwordx4 v136, s[4:7], s15 offen lds
	s_waitcnt vmcnt(6)
	s_barrier
	v_mfma_f32_16x16x32_bf16 v[30:33], v[172:175], v[204:207], v[30:33]
	v_mfma_f32_16x16x32_bf16 v[26:29], v[172:175], v[212:215], v[26:29]
	v_mfma_f32_16x16x32_bf16 v[22:25], v[180:183], v[204:207], v[22:25]
	v_mfma_f32_16x16x32_bf16 v[18:21], v[180:183], v[212:215], v[18:21]
	v_mfma_f32_16x16x32_bf16 v[14:17], v[188:191], v[204:207], v[14:17]
	v_mfma_f32_16x16x32_bf16 v[10:13], v[188:191], v[212:215], v[10:13]
	v_mfma_f32_16x16x32_bf16 v[6:9], v[196:199], v[204:207], v[6:9]
	v_mfma_f32_16x16x32_bf16 v[2:5], v[196:199], v[212:215], v[2:5]
	v_mfma_f32_16x16x32_bf16 v[30:33], v[176:179], v[208:211], v[30:33]
	v_mfma_f32_16x16x32_bf16 v[26:29], v[176:179], v[216:219], v[26:29]
	v_mfma_f32_16x16x32_bf16 v[22:25], v[184:187], v[208:211], v[22:25]
	v_mfma_f32_16x16x32_bf16 v[18:21], v[184:187], v[216:219], v[18:21]
	v_mfma_f32_16x16x32_bf16 v[14:17], v[192:195], v[208:211], v[14:17]
	v_mfma_f32_16x16x32_bf16 v[10:13], v[192:195], v[216:219], v[10:13]
	v_mfma_f32_16x16x32_bf16 v[6:9], v[200:203], v[208:211], v[6:9]
	v_mfma_f32_16x16x32_bf16 v[2:5], v[200:203], v[216:219], v[2:5]
	s_barrier
	ds_read_b128 v[156:159], v135
	ds_read_b128 v[160:163], v135 offset:1024
	ds_read_b128 v[164:167], v135 offset:2048
	ds_read_b128 v[168:171], v135 offset:3072
	s_add_i32 m0, s100, 0x4000
	ds_read_b128 v[172:175], v133 offset:32768
	ds_read_b128 v[176:179], v133 offset:33792
	ds_read_b128 v[180:183], v132 offset:32768
	ds_read_b128 v[184:187], v132 offset:33792
	ds_read_b128 v[188:191], v131 offset:32768
	ds_read_b128 v[192:195], v131 offset:33792
	ds_read_b128 v[196:199], v130 offset:32768
	buffer_load_dwordx4 v137, s[88:91], s15 offen lds
	s_add_i32 m0, s100, 0x6000
	ds_read_b128 v[200:203], v130 offset:33792
	buffer_load_dwordx4 v136, s[88:91], s15 offen lds
	s_waitcnt lgkmcnt(8)
	s_barrier
	s_waitcnt lgkmcnt(1)
	v_mfma_f32_16x16x32_bf16 v[126:129], v[172:175], v[156:159], v[126:129]
	v_mfma_f32_16x16x32_bf16 v[122:125], v[172:175], v[164:167], v[122:125]
	v_mfma_f32_16x16x32_bf16 v[118:121], v[180:183], v[156:159], v[118:121]
	v_mfma_f32_16x16x32_bf16 v[114:117], v[180:183], v[164:167], v[114:117]
	v_mfma_f32_16x16x32_bf16 v[110:113], v[188:191], v[156:159], v[110:113]
	v_mfma_f32_16x16x32_bf16 v[106:109], v[188:191], v[164:167], v[106:109]
	v_mfma_f32_16x16x32_bf16 v[102:105], v[196:199], v[156:159], v[102:105]
	v_mfma_f32_16x16x32_bf16 v[98:101], v[196:199], v[164:167], v[98:101]
	v_mfma_f32_16x16x32_bf16 v[126:129], v[176:179], v[160:163], v[126:129]
	v_mfma_f32_16x16x32_bf16 v[122:125], v[176:179], v[168:171], v[122:125]
	v_mfma_f32_16x16x32_bf16 v[118:121], v[184:187], v[160:163], v[118:121]
	v_mfma_f32_16x16x32_bf16 v[114:117], v[184:187], v[168:171], v[114:117]
	v_mfma_f32_16x16x32_bf16 v[110:113], v[192:195], v[160:163], v[110:113]
	v_mfma_f32_16x16x32_bf16 v[106:109], v[192:195], v[168:171], v[106:109]
	s_waitcnt lgkmcnt(0)
	v_mfma_f32_16x16x32_bf16 v[102:105], v[200:203], v[160:163], v[102:105]
	v_mfma_f32_16x16x32_bf16 v[98:101], v[200:203], v[168:171], v[98:101]
	s_barrier
	s_add_i32 s15, s3, 0xfff80000
	s_add_i32 m0, s100, 0x18000
	ds_read_b128 v[204:207], v134
	ds_read_b128 v[208:211], v134 offset:1024
	ds_read_b128 v[212:215], v134 offset:2048
	buffer_load_dwordx4 v137, s[4:7], s15 offen lds
	s_add_i32 m0, s100, 0x1a000
	ds_read_b128 v[216:219], v134 offset:3072
	buffer_load_dwordx4 v136, s[4:7], s15 offen lds
	s_barrier
	s_waitcnt lgkmcnt(1)
	v_mfma_f32_16x16x32_bf16 v[94:97], v[172:175], v[204:207], v[94:97]
	v_mfma_f32_16x16x32_bf16 v[90:93], v[172:175], v[212:215], v[90:93]
	v_mfma_f32_16x16x32_bf16 v[86:89], v[180:183], v[204:207], v[86:89]
	v_mfma_f32_16x16x32_bf16 v[82:85], v[180:183], v[212:215], v[82:85]
	v_mfma_f32_16x16x32_bf16 v[78:81], v[188:191], v[204:207], v[78:81]
	v_mfma_f32_16x16x32_bf16 v[74:77], v[188:191], v[212:215], v[74:77]
	v_mfma_f32_16x16x32_bf16 v[70:73], v[196:199], v[204:207], v[70:73]
	v_mfma_f32_16x16x32_bf16 v[66:69], v[196:199], v[212:215], v[66:69]
	v_mfma_f32_16x16x32_bf16 v[94:97], v[176:179], v[208:211], v[94:97]
	s_waitcnt lgkmcnt(0)
	v_mfma_f32_16x16x32_bf16 v[90:93], v[176:179], v[216:219], v[90:93]
	v_mfma_f32_16x16x32_bf16 v[86:89], v[184:187], v[208:211], v[86:89]
	v_mfma_f32_16x16x32_bf16 v[82:85], v[184:187], v[216:219], v[82:85]
	v_mfma_f32_16x16x32_bf16 v[78:81], v[192:195], v[208:211], v[78:81]
	v_mfma_f32_16x16x32_bf16 v[74:77], v[192:195], v[216:219], v[74:77]
	v_mfma_f32_16x16x32_bf16 v[70:73], v[200:203], v[208:211], v[70:73]
	v_mfma_f32_16x16x32_bf16 v[66:69], v[200:203], v[216:219], v[66:69]
	s_add_i32 m0, s100, 0x8000
	s_barrier
; #define WAIT_V(n) asm volatile("s_waitcnt vmcnt(" #n ")" ::: "memory")
; #define WAIT_L(n) asm volatile("s_waitcnt lgkmcnt(" #n ")" ::: "memory")
; #define BAR __builtin_amdgcn_s_barrier()
; #define SCHED __builtin_amdgcn_sched_barrier(0)
; __device__ __forceinline__ void mainloop_8phase(const u16* __restrict__ A, const u16* __restrict__ Bt, int K,
;                                                 f32x4 (&acc)[2][2][4][2], int wid_s, int ld) {
;     ...
;     LDA(At, 1, 1); STAGE(SA(1, 0), A, brow, t + 3);
;     BAR; WAIT_L(0); MMA(1, 0, At, B0); BAR; SCHED;
;     STAGE(SB(1, 1), Bt, bcol + G_HALF, t + 3);
;     WAIT_V(6); BAR; MMA(1, 1, At, B1); BAR;
;   }
;   { LDB(B0, 0, 0); LDA(At, 0, 0); STAGE(SA(1, 1), A, brow + G_HALF, nt - 1);
;     BAR; WAIT_L(0); MMA(0, 0, At, B0); BAR;
;     LDB(B1, 0, 1); BAR; WAIT_L(0); MMA(0, 1, At, B1); BAR;
	ds_read_b128 v[172:175], v133 offset:49152
	ds_read_b128 v[176:179], v133 offset:50176
	ds_read_b128 v[180:183], v132 offset:49152
	ds_read_b128 v[184:187], v132 offset:50176
	ds_read_b128 v[188:191], v131 offset:49152
	ds_read_b128 v[192:195], v131 offset:50176
	ds_read_b128 v[196:199], v130 offset:49152
	buffer_load_dwordx4 v137, s[88:91], s15 offen lds
	s_add_i32 m0, s100, 0xa000
	ds_read_b128 v[200:203], v130 offset:50176
	buffer_load_dwordx4 v136, s[88:91], s15 offen lds
	s_barrier
	s_waitcnt lgkmcnt(1)
	v_mfma_f32_16x16x32_bf16 v[62:65], v[172:175], v[156:159], v[62:65]
	v_mfma_f32_16x16x32_bf16 v[58:61], v[172:175], v[164:167], v[58:61]
	v_mfma_f32_16x16x32_bf16 v[54:57], v[180:183], v[156:159], v[54:57]
	v_mfma_f32_16x16x32_bf16 v[50:53], v[180:183], v[164:167], v[50:53]
	v_mfma_f32_16x16x32_bf16 v[46:49], v[188:191], v[156:159], v[46:49]
	v_mfma_f32_16x16x32_bf16 v[42:45], v[188:191], v[164:167], v[42:45]
	v_mfma_f32_16x16x32_bf16 v[38:41], v[196:199], v[156:159], v[38:41]
	v_mfma_f32_16x16x32_bf16 v[34:37], v[196:199], v[164:167], v[34:37]
	v_mfma_f32_16x16x32_bf16 v[62:65], v[176:179], v[160:163], v[62:65]
	v_mfma_f32_16x16x32_bf16 v[58:61], v[176:179], v[168:171], v[58:61]
	v_mfma_f32_16x16x32_bf16 v[54:57], v[184:187], v[160:163], v[54:57]
	v_mfma_f32_16x16x32_bf16 v[50:53], v[184:187], v[168:171], v[50:53]
	v_mfma_f32_16x16x32_bf16 v[46:49], v[192:195], v[160:163], v[46:49]
	v_mfma_f32_16x16x32_bf16 v[42:45], v[192:195], v[168:171], v[42:45]
	s_waitcnt lgkmcnt(0)
	v_mfma_f32_16x16x32_bf16 v[38:41], v[200:203], v[160:163], v[38:41]
	v_mfma_f32_16x16x32_bf16 v[34:37], v[200:203], v[168:171], v[34:37]
	s_barrier
	s_add_i32 m0, s100, 0x1c000
	s_nop 0
	buffer_load_dwordx4 v137, s[4:7], s3 offen lds
	s_add_i32 m0, s100, 0x1e000
	s_nop 0
	buffer_load_dwordx4 v136, s[4:7], s3 offen lds
	s_waitcnt vmcnt(6)
	s_barrier
	v_mfma_f32_16x16x32_bf16 v[30:33], v[172:175], v[204:207], v[30:33]
	v_mfma_f32_16x16x32_bf16 v[26:29], v[172:175], v[212:215], v[26:29]
	v_mfma_f32_16x16x32_bf16 v[22:25], v[180:183], v[204:207], v[22:25]
	v_mfma_f32_16x16x32_bf16 v[18:21], v[180:183], v[212:215], v[18:21]
	v_mfma_f32_16x16x32_bf16 v[14:17], v[188:191], v[204:207], v[14:17]
	v_mfma_f32_16x16x32_bf16 v[10:13], v[188:191], v[212:215], v[10:13]
	v_mfma_f32_16x16x32_bf16 v[6:9], v[196:199], v[204:207], v[6:9]
	v_mfma_f32_16x16x32_bf16 v[2:5], v[196:199], v[212:215], v[2:5]
	v_mfma_f32_16x16x32_bf16 v[30:33], v[176:179], v[208:211], v[30:33]
	v_mfma_f32_16x16x32_bf16 v[26:29], v[176:179], v[216:219], v[26:29]
	v_mfma_f32_16x16x32_bf16 v[22:25], v[184:187], v[208:211], v[22:25]
	v_mfma_f32_16x16x32_bf16 v[18:21], v[184:187], v[216:219], v[18:21]
	v_mfma_f32_16x16x32_bf16 v[14:17], v[192:195], v[208:211], v[14:17]
	v_mfma_f32_16x16x32_bf16 v[10:13], v[192:195], v[216:219], v[10:13]
	v_mfma_f32_16x16x32_bf16 v[6:9], v[200:203], v[208:211], v[6:9]
	v_mfma_f32_16x16x32_bf16 v[2:5], v[200:203], v[216:219], v[2:5]
	s_add_i32 s2, s2, 2
	s_addk_i32 s3, 0x100
	s_cmp_lt_u32 s2, 28
	s_cbranch_scc1 .LBB0_162
	s_barrier
	v_readfirstlane_b32 s2, v150
	s_mov_b32 m0, s2
	s_mov_b32 s3, 0x80f80
	v_readfirstlane_b32 s2, v149
	ds_read_b128 v[138:141], v148
	ds_read_b128 v[152:155], v148 offset:1024
	ds_read_b128 v[156:159], v148 offset:2048
	ds_read_b128 v[160:163], v148 offset:3072
	ds_read_b128 v[164:167], v133
	ds_read_b128 v[168:171], v133 offset:1024
	ds_read_b128 v[172:175], v132
	ds_read_b128 v[176:179], v132 offset:1024
	ds_read_b128 v[180:183], v131
	ds_read_b128 v[184:187], v131 offset:1024
	ds_read_b128 v[188:191], v130
	ds_read_b128 v[192:195], v130 offset:1024
	buffer_load_dwordx4 v137, s[88:91], s3 offen lds
	s_mov_b32 m0, s2
	s_nop 0
	buffer_load_dwordx4 v136, s[88:91], s3 offen lds
	s_barrier
	s_waitcnt lgkmcnt(0)
	v_mfma_f32_16x16x32_bf16 v[126:129], v[164:167], v[138:141], v[126:129]
	v_mfma_f32_16x16x32_bf16 v[118:121], v[172:175], v[138:141], v[118:121]
	v_mfma_f32_16x16x32_bf16 v[110:113], v[180:183], v[138:141], v[110:113]
	v_mfma_f32_16x16x32_bf16 v[102:105], v[188:191], v[138:141], v[102:105]
	v_mfma_f32_16x16x32_bf16 v[126:129], v[168:171], v[152:155], v[126:129]
	v_mfma_f32_16x16x32_bf16 v[122:125], v[164:167], v[156:159], v[122:125]
	v_mfma_f32_16x16x32_bf16 v[118:121], v[176:179], v[152:155], v[118:121]
	v_mfma_f32_16x16x32_bf16 v[114:117], v[172:175], v[156:159], v[114:117]
	v_mfma_f32_16x16x32_bf16 v[110:113], v[184:187], v[152:155], v[110:113]
	v_mfma_f32_16x16x32_bf16 v[106:109], v[180:183], v[156:159], v[106:109]
	v_mfma_f32_16x16x32_bf16 v[102:105], v[192:195], v[152:155], v[102:105]
	v_mfma_f32_16x16x32_bf16 v[98:101], v[188:191], v[156:159], v[98:101]
	v_mfma_f32_16x16x32_bf16 v[146:149], v[168:171], v[160:163], v[122:125]
	v_mfma_f32_16x16x32_bf16 v[196:199], v[176:179], v[160:163], v[114:117]
	v_mfma_f32_16x16x32_bf16 v[200:203], v[184:187], v[160:163], v[106:109]
	v_mfma_f32_16x16x32_bf16 v[204:207], v[192:195], v[160:163], v[98:101]
	s_barrier
	s_nop 1
	ds_read_b128 v[98:101], v145
	ds_read_b128 v[106:109], v145 offset:1024
	ds_read_b128 v[114:117], v145 offset:2048
	ds_read_b128 v[122:125], v145 offset:3072
	s_barrier
; #define WAIT_V(n) asm volatile("s_waitcnt vmcnt(" #n ")" ::: "memory")
; #define WAIT_L(n) asm volatile("s_waitcnt lgkmcnt(" #n ")" ::: "memory")
; #define BAR __builtin_amdgcn_s_barrier()
; __device__ __forceinline__ void mainloop_8phase(const u16* __restrict__ A, const u16* __restrict__ Bt, int K,
;                                                 f32x4 (&acc)[2][2][4][2], int wid_s, int ld) {
;     ...
;     BAR; WAIT_L(0); MMA(0, 0, At, B0); BAR;
;     LDB(B1, 0, 1); BAR; WAIT_L(0); MMA(0, 1, At, B1); BAR;
;     LDA(At, 0, 1); WAIT_V(4); BAR; WAIT_L(0); MMA(1, 0, At, B0); MMA(1, 1, At, B1); BAR; }
;   { LDB(B0, 1, 0); LDA(At, 1, 0); WAIT_V(2); BAR; WAIT_L(0); MMA(0, 0, At, B0); BAR;
	s_waitcnt lgkmcnt(0)
	v_mfma_f32_16x16x32_bf16 v[94:97], v[164:167], v[98:101], v[94:97]
	v_mfma_f32_16x16x32_bf16 v[90:93], v[164:167], v[114:117], v[90:93]
	v_mfma_f32_16x16x32_bf16 v[86:89], v[172:175], v[98:101], v[86:89]
	v_mfma_f32_16x16x32_bf16 v[82:85], v[172:175], v[114:117], v[82:85]
	v_mfma_f32_16x16x32_bf16 v[78:81], v[180:183], v[98:101], v[78:81]
	v_mfma_f32_16x16x32_bf16 v[74:77], v[180:183], v[114:117], v[74:77]
	v_mfma_f32_16x16x32_bf16 v[70:73], v[188:191], v[98:101], v[70:73]
	v_mfma_f32_16x16x32_bf16 v[66:69], v[188:191], v[114:117], v[66:69]
	v_mfma_f32_16x16x32_bf16 v[94:97], v[168:171], v[106:109], v[94:97]
	v_mfma_f32_16x16x32_bf16 v[90:93], v[168:171], v[122:125], v[90:93]
	v_mfma_f32_16x16x32_bf16 v[86:89], v[176:179], v[106:109], v[86:89]
	v_mfma_f32_16x16x32_bf16 v[82:85], v[176:179], v[122:125], v[82:85]
	v_mfma_f32_16x16x32_bf16 v[78:81], v[184:187], v[106:109], v[78:81]
	v_mfma_f32_16x16x32_bf16 v[74:77], v[184:187], v[122:125], v[74:77]
	v_mfma_f32_16x16x32_bf16 v[70:73], v[192:195], v[106:109], v[70:73]
	v_mfma_f32_16x16x32_bf16 v[66:69], v[192:195], v[122:125], v[66:69]
	s_barrier
	ds_read_b128 v[142:145], v133 offset:16384
	ds_read_b128 v[164:167], v133 offset:17408
	ds_read_b128 v[168:171], v132 offset:16384
	ds_read_b128 v[172:175], v132 offset:17408
	ds_read_b128 v[176:179], v131 offset:16384
	ds_read_b128 v[180:183], v131 offset:17408
	ds_read_b128 v[184:187], v130 offset:16384
	ds_read_b128 v[188:191], v130 offset:17408
	s_waitcnt vmcnt(4)
	s_barrier
	s_waitcnt lgkmcnt(0)
	v_mfma_f32_16x16x32_bf16 v[62:65], v[142:145], v[138:141], v[62:65]
	v_mfma_f32_16x16x32_bf16 v[58:61], v[142:145], v[156:159], v[58:61]
	v_mfma_f32_16x16x32_bf16 v[54:57], v[168:171], v[138:141], v[54:57]
	v_mfma_f32_16x16x32_bf16 v[50:53], v[168:171], v[156:159], v[50:53]
	v_mfma_f32_16x16x32_bf16 v[46:49], v[176:179], v[138:141], v[46:49]
	v_mfma_f32_16x16x32_bf16 v[42:45], v[176:179], v[156:159], v[42:45]
	v_mfma_f32_16x16x32_bf16 v[38:41], v[184:187], v[138:141], v[38:41]
	v_mfma_f32_16x16x32_bf16 v[34:37], v[184:187], v[156:159], v[34:37]
	v_mfma_f32_16x16x32_bf16 v[192:195], v[164:167], v[152:155], v[62:65]
	v_mfma_f32_16x16x32_bf16 v[208:211], v[164:167], v[160:163], v[58:61]
	v_mfma_f32_16x16x32_bf16 v[212:215], v[172:175], v[152:155], v[54:57]
	v_mfma_f32_16x16x32_bf16 v[216:219], v[172:175], v[160:163], v[50:53]
	v_mfma_f32_16x16x32_bf16 v[220:223], v[180:183], v[152:155], v[46:49]
	v_mfma_f32_16x16x32_bf16 v[224:227], v[180:183], v[160:163], v[42:45]
	v_mfma_f32_16x16x32_bf16 v[136:139], v[188:191], v[152:155], v[38:41]
	v_mfma_f32_16x16x32_bf16 v[150:153], v[188:191], v[160:163], v[34:37]
	v_mfma_f32_16x16x32_bf16 v[30:33], v[142:145], v[98:101], v[30:33]
	v_mfma_f32_16x16x32_bf16 v[22:25], v[168:171], v[98:101], v[22:25]
	v_mfma_f32_16x16x32_bf16 v[14:17], v[176:179], v[98:101], v[14:17]
	v_mfma_f32_16x16x32_bf16 v[6:9], v[184:187], v[98:101], v[6:9]
	v_mfma_f32_16x16x32_bf16 v[30:33], v[164:167], v[106:109], v[30:33]
	v_mfma_f32_16x16x32_bf16 v[26:29], v[142:145], v[114:117], v[26:29]
	v_mfma_f32_16x16x32_bf16 v[22:25], v[172:175], v[106:109], v[22:25]
	v_mfma_f32_16x16x32_bf16 v[18:21], v[168:171], v[114:117], v[18:21]
	v_mfma_f32_16x16x32_bf16 v[14:17], v[180:183], v[106:109], v[14:17]
	v_mfma_f32_16x16x32_bf16 v[10:13], v[176:179], v[114:117], v[10:13]
	v_mfma_f32_16x16x32_bf16 v[6:9], v[188:191], v[106:109], v[6:9]
	v_mfma_f32_16x16x32_bf16 v[2:5], v[184:187], v[114:117], v[2:5]
	v_mfma_f32_16x16x32_bf16 v[140:143], v[164:167], v[122:125], v[26:29]
	v_mfma_f32_16x16x32_bf16 v[154:157], v[172:175], v[122:125], v[18:21]
	v_mfma_f32_16x16x32_bf16 v[158:161], v[180:183], v[122:125], v[10:13]
	v_mfma_f32_16x16x32_bf16 v[162:165], v[188:191], v[122:125], v[2:5]
	s_barrier
	s_nop 1
	ds_read_b128 v[2:5], v135
	ds_read_b128 v[166:169], v135 offset:1024
	ds_read_b128 v[170:173], v135 offset:2048
	ds_read_b128 v[174:177], v135 offset:3072
	ds_read_b128 v[10:13], v133 offset:32768
	ds_read_b128 v[18:21], v133 offset:33792
	ds_read_b128 v[26:29], v132 offset:32768
	ds_read_b128 v[38:41], v132 offset:33792
	ds_read_b128 v[46:49], v131 offset:32768
	ds_read_b128 v[178:181], v131 offset:33792
	ds_read_b128 v[182:185], v130 offset:32768
	ds_read_b128 v[186:189], v130 offset:33792
	s_waitcnt vmcnt(2)
	s_barrier
; #define WAIT_V(n) asm volatile("s_waitcnt vmcnt(" #n ")" ::: "memory")
; #define WAIT_L(n) asm volatile("s_waitcnt lgkmcnt(" #n ")" ::: "memory")
; #define BAR __builtin_amdgcn_s_barrier()
; __device__ __forceinline__ void mainloop_8phase(const u16* __restrict__ A, const u16* __restrict__ Bt, int K,
;                                                 f32x4 (&acc)[2][2][4][2], int wid_s, int ld) {
;     ...
;     LDA(At, 0, 1); WAIT_V(4); BAR; WAIT_L(0); MMA(1, 0, At, B0); MMA(1, 1, At, B1); BAR; }
;   { LDB(B0, 1, 0); LDA(At, 1, 0); WAIT_V(2); BAR; WAIT_L(0); MMA(0, 0, At, B0); BAR;
;     LDB(B1, 1, 1); WAIT_V(0); BAR; WAIT_L(0); MMA(0, 1, At, B1); BAR;
;     LDA(At, 1, 1); BAR; WAIT_L(0); MMA(1, 0, At, B0); MMA(1, 1, At, B1); BAR; }
;   if (wr == 0) BAR;
	s_waitcnt lgkmcnt(0)
	v_mfma_f32_16x16x32_bf16 v[34:37], v[10:13], v[2:5], v[126:129]
	v_mfma_f32_16x16x32_bf16 v[122:125], v[18:21], v[166:169], v[34:37]
	v_mfma_f32_16x16x32_bf16 v[34:37], v[10:13], v[170:173], v[146:149]
	v_mfma_f32_16x16x32_bf16 v[58:61], v[18:21], v[174:177], v[34:37]
	v_mfma_f32_16x16x32_bf16 v[34:37], v[26:29], v[2:5], v[118:121]
	v_mfma_f32_16x16x32_bf16 v[114:117], v[38:41], v[166:169], v[34:37]
	v_mfma_f32_16x16x32_bf16 v[34:37], v[26:29], v[170:173], v[196:199]
	v_mfma_f32_16x16x32_bf16 v[50:53], v[38:41], v[174:177], v[34:37]
	v_mfma_f32_16x16x32_bf16 v[34:37], v[46:49], v[2:5], v[110:113]
	v_mfma_f32_16x16x32_bf16 v[106:109], v[178:181], v[166:169], v[34:37]
	v_mfma_f32_16x16x32_bf16 v[34:37], v[46:49], v[170:173], v[200:203]
	v_mfma_f32_16x16x32_bf16 v[42:45], v[178:181], v[174:177], v[34:37]
	v_mfma_f32_16x16x32_bf16 v[34:37], v[182:185], v[2:5], v[102:105]
	v_mfma_f32_16x16x32_bf16 v[98:101], v[186:189], v[166:169], v[34:37]
	v_mfma_f32_16x16x32_bf16 v[34:37], v[182:185], v[170:173], v[204:207]
	v_mfma_f32_16x16x32_bf16 v[34:37], v[186:189], v[174:177], v[34:37]
	s_barrier
	ds_read_b128 v[144:147], v134
	ds_read_b128 v[196:199], v134 offset:1024
	ds_read_b128 v[200:203], v134 offset:2048
	ds_read_b128 v[204:207], v134 offset:3072
	s_waitcnt vmcnt(0)
	s_barrier
	s_waitcnt lgkmcnt(0)
	v_mfma_f32_16x16x32_bf16 v[54:57], v[10:13], v[144:147], v[94:97]
	v_mfma_f32_16x16x32_bf16 v[10:13], v[10:13], v[200:203], v[90:93]
	v_mfma_f32_16x16x32_bf16 v[62:65], v[18:21], v[204:207], v[10:13]
	v_mfma_f32_16x16x32_bf16 v[10:13], v[26:29], v[144:147], v[86:89]
	v_mfma_f32_16x16x32_bf16 v[118:121], v[38:41], v[196:199], v[10:13]
	v_mfma_f32_16x16x32_bf16 v[10:13], v[26:29], v[200:203], v[82:85]
	v_mfma_f32_16x16x32_bf16 v[126:129], v[18:21], v[196:199], v[54:57]
	v_mfma_f32_16x16x32_bf16 v[54:57], v[38:41], v[204:207], v[10:13]
	v_mfma_f32_16x16x32_bf16 v[10:13], v[46:49], v[144:147], v[78:81]
	v_mfma_f32_16x16x32_bf16 v[110:113], v[178:181], v[196:199], v[10:13]
	v_mfma_f32_16x16x32_bf16 v[10:13], v[46:49], v[200:203], v[74:77]
	v_mfma_f32_16x16x32_bf16 v[46:49], v[178:181], v[204:207], v[10:13]
	v_mfma_f32_16x16x32_bf16 v[10:13], v[182:185], v[144:147], v[70:73]
	v_mfma_f32_16x16x32_bf16 v[102:105], v[186:189], v[196:199], v[10:13]
	v_mfma_f32_16x16x32_bf16 v[10:13], v[182:185], v[200:203], v[66:69]
	v_mfma_f32_16x16x32_bf16 v[38:41], v[186:189], v[204:207], v[10:13]
	s_barrier
	ds_read_b128 v[70:73], v133 offset:49152
	ds_read_b128 v[78:81], v133 offset:50176
	ds_read_b128 v[178:181], v132 offset:49152
	ds_read_b128 v[132:135], v132 offset:50176
	ds_read_b128 v[182:185], v131 offset:49152
	ds_read_b128 v[186:189], v131 offset:50176
	ds_read_b128 v[228:231], v130 offset:49152
	ds_read_b128 v[232:235], v130 offset:50176
	s_barrier
	s_waitcnt lgkmcnt(0)
	v_mfma_f32_16x16x32_bf16 v[10:13], v[70:73], v[2:5], v[192:195]
	v_mfma_f32_16x16x32_bf16 v[90:93], v[78:81], v[166:169], v[10:13]
	v_mfma_f32_16x16x32_bf16 v[10:13], v[70:73], v[170:173], v[208:211]
	v_mfma_f32_16x16x32_bf16 v[26:29], v[78:81], v[174:177], v[10:13]
	v_mfma_f32_16x16x32_bf16 v[10:13], v[178:181], v[2:5], v[212:215]
	v_mfma_f32_16x16x32_bf16 v[82:85], v[132:135], v[166:169], v[10:13]
	v_mfma_f32_16x16x32_bf16 v[10:13], v[178:181], v[170:173], v[216:219]
	v_mfma_f32_16x16x32_bf16 v[18:21], v[132:135], v[174:177], v[10:13]
	v_mfma_f32_16x16x32_bf16 v[10:13], v[182:185], v[2:5], v[220:223]
	v_mfma_f32_16x16x32_bf16 v[2:5], v[228:231], v[2:5], v[136:139]
	v_mfma_f32_16x16x32_bf16 v[74:77], v[186:189], v[166:169], v[10:13]
	v_mfma_f32_16x16x32_bf16 v[10:13], v[182:185], v[170:173], v[224:227]
	v_mfma_f32_16x16x32_bf16 v[66:69], v[232:235], v[166:169], v[2:5]
	v_mfma_f32_16x16x32_bf16 v[2:5], v[228:231], v[170:173], v[150:153]
	v_mfma_f32_16x16x32_bf16 v[10:13], v[186:189], v[174:177], v[10:13]
	v_mfma_f32_16x16x32_bf16 v[2:5], v[232:235], v[174:177], v[2:5]
	v_mfma_f32_16x16x32_bf16 v[30:33], v[70:73], v[144:147], v[30:33]
	v_mfma_f32_16x16x32_bf16 v[94:97], v[78:81], v[196:199], v[30:33]
	v_mfma_f32_16x16x32_bf16 v[30:33], v[70:73], v[200:203], v[140:143]
	v_mfma_f32_16x16x32_bf16 v[22:25], v[178:181], v[144:147], v[22:25]
	v_mfma_f32_16x16x32_bf16 v[14:17], v[182:185], v[144:147], v[14:17]
	v_mfma_f32_16x16x32_bf16 v[6:9], v[228:231], v[144:147], v[6:9]
	v_mfma_f32_16x16x32_bf16 v[30:33], v[78:81], v[204:207], v[30:33]
	v_mfma_f32_16x16x32_bf16 v[86:89], v[132:135], v[196:199], v[22:25]
	v_mfma_f32_16x16x32_bf16 v[22:25], v[178:181], v[200:203], v[154:157]
	v_mfma_f32_16x16x32_bf16 v[78:81], v[186:189], v[196:199], v[14:17]
	v_mfma_f32_16x16x32_bf16 v[14:17], v[182:185], v[200:203], v[158:161]
	v_mfma_f32_16x16x32_bf16 v[70:73], v[232:235], v[196:199], v[6:9]
	v_mfma_f32_16x16x32_bf16 v[6:9], v[228:231], v[200:203], v[162:165]
	v_mfma_f32_16x16x32_bf16 v[22:25], v[132:135], v[204:207], v[22:25]
	v_mfma_f32_16x16x32_bf16 v[14:17], v[186:189], v[204:207], v[14:17]
	v_mfma_f32_16x16x32_bf16 v[6:9], v[232:235], v[204:207], v[6:9]
	s_movk_i32 s2, 0x100
	v_cmp_gt_u32_e32 vcc, s2, v0
	s_barrier
	s_and_saveexec_b64 s[2:3], vcc
	s_cbranch_execz .LBB0_165
	s_barrier

; #define WAIT_V(n) asm volatile("s_waitcnt vmcnt(" #n ")" ::: "memory")
; #define BAR __builtin_amdgcn_s_barrier()
; __device__ __forceinline__ void mainloop_8phase(const u16* __restrict__ A, const u16* __restrict__ Bt, int K,
;                                                 f32x4 (&acc)[2][2][4][2], int wid_s, int ld) {
;     ...
;   int tid = get_tid(wid_s), wid = tid >> 6, lane = tid & 63, wr = wid >> 2, wc = wid & 3, fr = lane & 15, fq = lane >> 4;
;   unsigned goff0, goff1;
;   {
;     int r0, c0, r1, c1;
;     stage_rc(tid * 16, r0, c0);
;     stage_rc(tid * 16 + 8192, r1, c1);
;     goff0 = (unsigned)(r0 * ld + c0) * 2u;
;     goff1 = (unsigned)(r1 * ld + c1) * 2u;
;   }
;   __amdgpu_buffer_rsrc_t rs_A, rs_Bt;
;   {
;     unsigned long ua = (unsigned long)A, ub = (unsigned long)Bt;
;     unsigned alo = __builtin_amdgcn_readfirstlane((unsigned)ua), ahi = __builtin_amdgcn_readfirstlane((unsigned)(ua >> 32));
;     unsigned blo = __builtin_amdgcn_readfirstlane((unsigned)ub), bhi = __builtin_amdgcn_readfirstlane((unsigned)(ub >> 32));
;     rs_A = __builtin_amdgcn_make_buffer_rsrc((void*)(((unsigned long)ahi << 32) | alo), (short)0, 0x7ffffff0, 0x00020000);
;     rs_Bt = __builtin_amdgcn_make_buffer_rsrc((void*)(((unsigned long)bhi << 32) | blo), (short)0, 0x7ffffff0, 0x00020000);
;   }
;   bf16x8 At[4][2], B0[2][2], B1[2][2];
;   const int brow = 0, bcol = 0;
;   int nt = K / G_BK;
;   if (wr == 1) BAR;
;   WAIT_V(0); BAR;
;   STAGE(SB(1, 0), Bt, bcol, 1); STAGE(SA(1, 0), A, brow, 1); STAGE(SB(1, 1), Bt, bcol + G_HALF, 1);
;   WAIT_V(6); BAR;
;     ...
;     f32x4 acc[2][2][4][2];
; #pragma unroll
;     for (int a = 0; a < 2; ++a)
; #pragma unroll
;       for (int b = 0; b < 2; ++b)
; #pragma unroll
;         for (int c = 0; c < 4; ++c)
; #pragma unroll
;           for (int d = 0; d < 2; ++d) acc[a][b][c][d] = f32x4{0.f, 0.f, 0.f, 0.f};
.LBB0_246:
	s_or_b64 exec, exec, s[0:1]
	v_bfe_i32 v8, v0, 27, 1
	v_lshlrev_b32_e32 v6, 4, v0
	v_lshrrev_b32_e32 v8, 22, v8
	v_add_u32_e32 v8, v6, v8
	v_and_b32_e32 v8, 0xfffffc00, v8
	v_sub_u32_e32 v8, v6, v8
	v_lshrrev_b32_e32 v9, 4, v8
	v_ashrrev_i32_e32 v7, 31, v0
	v_bitop3_b32 v8, v9, v8, 32 bitop3:0x6c
	v_lshrrev_b32_e32 v7, 26, v7
	v_ashrrev_i32_e32 v10, 31, v8
	v_add_u32_e32 v7, v0, v7
	v_lshrrev_b32_e32 v10, 26, v10
	v_ashrrev_i32_e32 v7, 6, v7
	v_add_u32_e32 v10, v8, v10
	v_lshlrev_b32_e32 v9, 3, v7
	v_lshrrev_b32_e32 v11, 6, v10
	v_and_b32_e32 v10, 0xc0, v10
	v_and_b32_e32 v9, 0xffff0, v9
	v_sub_u32_e32 v8, v8, v10
	v_add_u32_e32 v10, 0x2000, v6
	v_add_u32_e32 v9, v11, v9
	v_ashrrev_i32_e32 v11, 31, v10
	v_lshrrev_b32_e32 v11, 22, v11
	v_add_u32_e32 v11, v10, v11
	v_ashrrev_i32_e32 v11, 10, v11
	v_mul_i32_i24_e32 v12, 0x400, v11
	v_sub_u32_e32 v10, v10, v12
	v_lshrrev_b32_e32 v12, 4, v10
	v_bitop3_b32 v10, v12, v10, 32 bitop3:0x6c
	v_ashrrev_i32_e32 v13, 31, v10
	v_lshrrev_b32_e32 v13, 26, v13
	v_add_u32_e32 v13, v10, v13
	v_lshlrev_b32_e32 v7, 5, v7
	v_lshlrev_b32_e32 v12, 3, v11
	v_lshrrev_b32_e32 v14, 6, v13
	v_and_b32_e32 v13, 0xc0, v13
	v_readlane_b32 s3, v254, 43
	v_and_b32_e32 v7, 32, v7
	v_ashrrev_i16_sdwa v8, v244, sext(v8) dst_sel:DWORD dst_unused:UNUSED_PAD src0_sel:DWORD src1_sel:BYTE_0
	v_and_b32_e32 v12, 0xffff0, v12
	v_lshlrev_b32_e32 v11, 5, v11
	v_sub_u32_e32 v10, v10, v13
	s_waitcnt vmcnt(7)
	v_add_u32_e32 v138, s3, v6
	v_bfe_i32 v8, v8, 0, 16
	v_add_u32_e32 v12, v14, v12
	v_and_b32_e32 v11, 32, v11
	v_ashrrev_i16_sdwa v10, v244, sext(v10) dst_sel:DWORD dst_unused:UNUSED_PAD src0_sel:DWORD src1_sel:BYTE_0
	v_lshl_or_b32 v7, v9, 11, v7
	s_and_b32 s5, s13, 0xffff
	v_readfirstlane_b32 s0, v138
	v_add_u32_e32 v139, 0x2000, v138
	v_add_u32_e32 v140, 16, v6
	v_bfe_i32 v10, v10, 0, 16
	v_add_lshl_u32 v137, v7, v8, 1
	v_lshl_or_b32 v7, v12, 11, v11
	s_mov_b32 s24, s12
	s_mov_b32 s25, s5
	s_mov_b32 s26, s90
	s_mov_b32 s27, s91
	s_mov_b32 m0, s0
	s_movk_i32 s1, 0x80
	v_readfirstlane_b32 s0, v139
	v_add_u32_e32 v141, 0x8000, v140
	v_add_lshl_u32 v136, v7, v10, 1
	s_and_b32 s89, s11, 0xffff
	s_waitcnt vmcnt(0)
	s_barrier
	buffer_load_dwordx4 v137, s[24:27], s1 offen lds
	s_mov_b32 m0, s0
	v_readfirstlane_b32 s0, v141
	v_add_u32_e32 v142, 0xa000, v140
	v_readlane_b32 s6, v254, 44
	s_mov_b32 s20, s10
	s_mov_b32 s21, s89
	s_mov_b32 s22, s90
	s_mov_b32 s23, s91
	buffer_load_dwordx4 v136, s[24:27], s1 offen lds
	s_mov_b32 m0, s0
	v_readfirstlane_b32 s0, v142
	v_add_u32_e32 v143, s6, v6
	buffer_load_dwordx4 v137, s[20:23], s1 offen lds
	s_mov_b32 m0, s0
	v_readfirstlane_b32 s0, v143
	v_add_u32_e32 v146, 0x2000, v143
	buffer_load_dwordx4 v136, s[20:23], s1 offen lds
	s_mov_b32 m0, s0
	s_mov_b32 s1, 0x80080
	v_readfirstlane_b32 s0, v146
	buffer_load_dwordx4 v137, s[24:27], s1 offen lds
	s_mov_b32 m0, s0
	v_and_b32_e32 v4, 15, v2
	buffer_load_dwordx4 v136, s[24:27], s1 offen lds
	v_lshlrev_b32_e32 v7, 2, v2
	v_and_b32_e32 v5, 48, v2
	v_lshlrev_b32_e32 v4, 6, v4
	v_and_b32_e32 v7, 32, v7
	v_bitop3_b32 v4, v4, v7, v5 bitop3:0x36
	v_readlane_b32 s0, v254, 41
	v_lshlrev_b32_e32 v2, 6, v2
	s_waitcnt vmcnt(6)
	v_readlane_b32 s1, v254, 42
	v_add_u32_e32 v8, s0, v4
	v_add_u32_e32 v148, s0, v6
	s_movk_i32 s0, 0x3c0
	v_lshlrev_b32_e32 v11, 6, v0
	v_lshlrev_b32_e32 v3, 13, v3
	v_and_or_b32 v2, v2, s0, v5
	v_add_u32_e32 v9, s1, v4
	v_add_u32_e32 v151, s1, v6
	v_add_u32_e32 v6, s3, v4
	v_add_u32_e32 v10, s6, v4
	v_and_b32_e32 v11, 0x3000, v11
	v_add_u32_e32 v4, 16, v4
	v_xad_u32 v5, v2, v7, 16
	v_or_b32_e32 v7, 0x800, v3
	v_or_b32_e32 v12, 0x1000, v3
	v_or_b32_e32 v13, 0x1800, v3
	v_mov_b32_e32 v2, 0
	s_mov_b32 s88, s10
	s_mov_b32 s4, s12
	v_add_u32_e32 v145, 0xc000, v140
	v_add_u32_e32 v144, 0xe000, v140
	v_add_u32_e32 v149, 0x2000, v148
	v_add_u32_e32 v150, 0x2000, v140
	v_add_u32_e32 v152, 0x2000, v151
	v_add_u32_e32 v153, 0x4000, v140
	v_add_u32_e32 v154, 0x6000, v140
	s_mov_b32 s0, -2
	s_mov_b32 s1, 0x80180
	v_add_u32_e32 v155, v8, v11
	s_waitcnt lgkmcnt(0)
	v_add_u32_e32 v133, v4, v3
	v_add_u32_e32 v132, v5, v7
	v_add_u32_e32 v131, v5, v12
	v_add_u32_e32 v130, v5, v13
	v_add_u32_e32 v147, v9, v11
	v_add_u32_e32 v135, v6, v11
	v_add_u32_e32 v134, v10, v11
	v_mov_b32_e32 v3, v2
	v_mov_b32_e32 v4, v2
	v_mov_b32_e32 v5, v2
	v_mov_b32_e32 v6, v2
	v_mov_b32_e32 v7, v2
	v_mov_b32_e32 v8, v2
	v_mov_b32_e32 v9, v2
	v_mov_b32_e32 v10, v2
	v_mov_b32_e32 v11, v2
	v_mov_b32_e32 v12, v2
	v_mov_b32_e32 v13, v2
	v_mov_b32_e32 v14, v2
	v_mov_b32_e32 v15, v2
	v_mov_b32_e32 v16, v2
	v_mov_b32_e32 v17, v2
	v_mov_b32_e32 v18, v2
	v_mov_b32_e32 v19, v2
	v_mov_b32_e32 v20, v2
	v_mov_b32_e32 v21, v2
	v_mov_b32_e32 v22, v2
	v_mov_b32_e32 v23, v2
	v_mov_b32_e32 v24, v2
	v_mov_b32_e32 v25, v2
	v_mov_b32_e32 v26, v2
	v_mov_b32_e32 v27, v2
	v_mov_b32_e32 v28, v2
	v_mov_b32_e32 v29, v2
	v_mov_b32_e32 v30, v2
	v_mov_b32_e32 v31, v2
	v_mov_b32_e32 v32, v2
	v_mov_b32_e32 v33, v2
	v_mov_b32_e32 v34, v2
	v_mov_b32_e32 v35, v2
	v_mov_b32_e32 v36, v2
	v_mov_b32_e32 v37, v2
	v_mov_b32_e32 v38, v2
	v_mov_b32_e32 v39, v2
	v_mov_b32_e32 v40, v2
	v_mov_b32_e32 v41, v2
	v_mov_b32_e32 v42, v2
	v_mov_b32_e32 v43, v2
	v_mov_b32_e32 v44, v2
	v_mov_b32_e32 v45, v2
	v_mov_b32_e32 v46, v2
	v_mov_b32_e32 v47, v2
	v_mov_b32_e32 v48, v2
	v_mov_b32_e32 v49, v2
	v_mov_b32_e32 v50, v2
	v_mov_b32_e32 v51, v2
	v_mov_b32_e32 v52, v2
	v_mov_b32_e32 v53, v2
	v_mov_b32_e32 v54, v2
	v_mov_b32_e32 v55, v2
	v_mov_b32_e32 v56, v2
	v_mov_b32_e32 v57, v2
	v_mov_b32_e32 v58, v2
	v_mov_b32_e32 v59, v2
	v_mov_b32_e32 v60, v2
	v_mov_b32_e32 v61, v2
	v_mov_b32_e32 v62, v2
	v_mov_b32_e32 v63, v2
	v_mov_b32_e32 v64, v2
	v_mov_b32_e32 v65, v2
	v_mov_b32_e32 v66, v2
	v_mov_b32_e32 v67, v2
	s_waitcnt vmcnt(9)
; #define WAIT_L(n) asm volatile("s_waitcnt lgkmcnt(" #n ")" ::: "memory")
; #define BAR __builtin_amdgcn_s_barrier()
; #define SCHED __builtin_amdgcn_sched_barrier(0)
; __device__ __forceinline__ void mainloop_8phase(const u16* __restrict__ A, const u16* __restrict__ Bt, int K,
;                                                 f32x4 (&acc)[2][2][4][2], int wid_s, int ld) {
;     ...
;   for (int t = 0; t < nt - 2; t += 2) {
;     LDB(B0, 0, 0); SCHED; LDA(At, 0, 0); STAGE(SA(1, 1), A, brow + G_HALF, t + 1);
;     WAIT_L(8); BAR; WAIT_L(0); MMA(0, 0, At, B0); BAR; SCHED;
;     LDB(B1, 0, 1); STAGE(SB(0, 0), Bt, bcol, t + 2);
;     BAR; WAIT_L(0); MMA(0, 1, At, B1); BAR;
;     LDA(At, 0, 1); STAGE(SA(0, 0), A, brow, t + 2);
;     BAR; WAIT_L(0); MMA(1, 0, At, B0); BAR; SCHED;
	v_mov_b32_e32 v68, v2
	v_mov_b32_e32 v69, v2
	v_mov_b32_e32 v70, v2
	v_mov_b32_e32 v71, v2
	s_waitcnt vmcnt(8)
	v_mov_b32_e32 v72, v2
	v_mov_b32_e32 v73, v2
	v_mov_b32_e32 v74, v2
	v_mov_b32_e32 v75, v2
	s_waitcnt vmcnt(7)
	v_mov_b32_e32 v76, v2
	v_mov_b32_e32 v77, v2
	v_mov_b32_e32 v78, v2
	v_mov_b32_e32 v79, v2
	s_waitcnt vmcnt(6)
	v_mov_b32_e32 v80, v2
	v_mov_b32_e32 v81, v2
	v_mov_b32_e32 v82, v2
	v_mov_b32_e32 v83, v2
	v_mov_b32_e32 v84, v2
	v_mov_b32_e32 v85, v2
	v_mov_b32_e32 v86, v2
	v_mov_b32_e32 v87, v2
	v_mov_b32_e32 v88, v2
	v_mov_b32_e32 v89, v2
	v_mov_b32_e32 v90, v2
	v_mov_b32_e32 v91, v2
	v_mov_b32_e32 v92, v2
	v_mov_b32_e32 v93, v2
	v_mov_b32_e32 v94, v2
	v_mov_b32_e32 v95, v2
	v_mov_b32_e32 v96, v2
	v_mov_b32_e32 v97, v2
	v_mov_b32_e32 v98, v2
	v_mov_b32_e32 v99, v2
	v_mov_b32_e32 v100, v2
	v_mov_b32_e32 v101, v2
	v_mov_b32_e32 v102, v2
	v_mov_b32_e32 v103, v2
	v_mov_b32_e32 v104, v2
	v_mov_b32_e32 v105, v2
	v_mov_b32_e32 v106, v2
	v_mov_b32_e32 v107, v2
	v_mov_b32_e32 v108, v2
	v_mov_b32_e32 v109, v2
	v_mov_b32_e32 v110, v2
	v_mov_b32_e32 v111, v2
	v_mov_b32_e32 v112, v2
	v_mov_b32_e32 v113, v2
	v_mov_b32_e32 v114, v2
	v_mov_b32_e32 v115, v2
	v_mov_b32_e32 v116, v2
	v_mov_b32_e32 v117, v2
	v_mov_b32_e32 v118, v2
	v_mov_b32_e32 v119, v2
	v_mov_b32_e32 v120, v2
	v_mov_b32_e32 v121, v2
	v_mov_b32_e32 v122, v2
	v_mov_b32_e32 v123, v2
	v_mov_b32_e32 v124, v2
	v_mov_b32_e32 v125, v2
	v_mov_b32_e32 v126, v2
	v_mov_b32_e32 v127, v2
	v_mov_b32_e32 v128, v2
	v_mov_b32_e32 v129, v2
	s_mov_b32 s6, s90
	s_mov_b32 s7, s91
.LBB0_247:
	s_barrier
	ds_read_b128 v[156:159], v155
	ds_read_b128 v[160:163], v155 offset:1024
	ds_read_b128 v[164:167], v155 offset:2048
	ds_read_b128 v[168:171], v155 offset:3072
	s_add_i32 s3, s1, 0xffffff00
	s_add_i32 m0, s100, 0xc000
	ds_read_b128 v[172:175], v133
	ds_read_b128 v[176:179], v133 offset:1024
	ds_read_b128 v[180:183], v132
	ds_read_b128 v[184:187], v132 offset:1024
	ds_read_b128 v[188:191], v131
	ds_read_b128 v[192:195], v131 offset:1024
	ds_read_b128 v[196:199], v130
	buffer_load_dwordx4 v137, s[88:91], s3 offen lds
	s_add_i32 m0, s100, 0xe000
	ds_read_b128 v[200:203], v130 offset:1024
	buffer_load_dwordx4 v136, s[88:91], s3 offen lds
	s_waitcnt lgkmcnt(8)
	s_barrier
	s_waitcnt lgkmcnt(1)
	v_mfma_f32_16x16x32_bf16 v[126:129], v[172:175], v[156:159], v[126:129]
	v_mfma_f32_16x16x32_bf16 v[122:125], v[172:175], v[164:167], v[122:125]
	v_mfma_f32_16x16x32_bf16 v[118:121], v[180:183], v[156:159], v[118:121]
	v_mfma_f32_16x16x32_bf16 v[114:117], v[180:183], v[164:167], v[114:117]
	v_mfma_f32_16x16x32_bf16 v[110:113], v[188:191], v[156:159], v[110:113]
	v_mfma_f32_16x16x32_bf16 v[106:109], v[188:191], v[164:167], v[106:109]
	v_mfma_f32_16x16x32_bf16 v[102:105], v[196:199], v[156:159], v[102:105]
	v_mfma_f32_16x16x32_bf16 v[98:101], v[196:199], v[164:167], v[98:101]
	v_mfma_f32_16x16x32_bf16 v[126:129], v[176:179], v[160:163], v[126:129]
	v_mfma_f32_16x16x32_bf16 v[122:125], v[176:179], v[168:171], v[122:125]
	v_mfma_f32_16x16x32_bf16 v[118:121], v[184:187], v[160:163], v[118:121]
	v_mfma_f32_16x16x32_bf16 v[114:117], v[184:187], v[168:171], v[114:117]
	v_mfma_f32_16x16x32_bf16 v[110:113], v[192:195], v[160:163], v[110:113]
	v_mfma_f32_16x16x32_bf16 v[106:109], v[192:195], v[168:171], v[106:109]
	s_waitcnt lgkmcnt(0)
	v_mfma_f32_16x16x32_bf16 v[102:105], v[200:203], v[160:163], v[102:105]
	v_mfma_f32_16x16x32_bf16 v[98:101], v[200:203], v[168:171], v[98:101]
	s_barrier
	s_add_i32 s3, s1, 0xfff7ff80
	s_add_i32 m0, s100, 0x10000
	ds_read_b128 v[204:207], v147
	ds_read_b128 v[208:211], v147 offset:1024
	ds_read_b128 v[212:215], v147 offset:2048
	buffer_load_dwordx4 v137, s[4:7], s3 offen lds
	s_add_i32 m0, s100, 0x12000
	ds_read_b128 v[216:219], v147 offset:3072
	buffer_load_dwordx4 v136, s[4:7], s3 offen lds
	s_barrier
	s_waitcnt lgkmcnt(1)
	v_mfma_f32_16x16x32_bf16 v[94:97], v[172:175], v[204:207], v[94:97]
	v_mfma_f32_16x16x32_bf16 v[90:93], v[172:175], v[212:215], v[90:93]
	v_mfma_f32_16x16x32_bf16 v[86:89], v[180:183], v[204:207], v[86:89]
	v_mfma_f32_16x16x32_bf16 v[82:85], v[180:183], v[212:215], v[82:85]
	v_mfma_f32_16x16x32_bf16 v[78:81], v[188:191], v[204:207], v[78:81]
	v_mfma_f32_16x16x32_bf16 v[74:77], v[188:191], v[212:215], v[74:77]
	v_mfma_f32_16x16x32_bf16 v[70:73], v[196:199], v[204:207], v[70:73]
	v_mfma_f32_16x16x32_bf16 v[66:69], v[196:199], v[212:215], v[66:69]
	v_mfma_f32_16x16x32_bf16 v[94:97], v[176:179], v[208:211], v[94:97]
	s_waitcnt lgkmcnt(0)
	v_mfma_f32_16x16x32_bf16 v[90:93], v[176:179], v[216:219], v[90:93]
	v_mfma_f32_16x16x32_bf16 v[86:89], v[184:187], v[208:211], v[86:89]
	v_mfma_f32_16x16x32_bf16 v[82:85], v[184:187], v[216:219], v[82:85]
	v_mfma_f32_16x16x32_bf16 v[78:81], v[192:195], v[208:211], v[78:81]
	v_mfma_f32_16x16x32_bf16 v[74:77], v[192:195], v[216:219], v[74:77]
	v_mfma_f32_16x16x32_bf16 v[70:73], v[200:203], v[208:211], v[70:73]
	v_mfma_f32_16x16x32_bf16 v[66:69], v[200:203], v[216:219], v[66:69]
	s_mov_b32 m0, s100
	s_barrier
	ds_read_b128 v[172:175], v133 offset:16384
	ds_read_b128 v[176:179], v133 offset:17408
	ds_read_b128 v[180:183], v132 offset:16384
	ds_read_b128 v[184:187], v132 offset:17408
	ds_read_b128 v[188:191], v131 offset:16384
	ds_read_b128 v[192:195], v131 offset:17408
	ds_read_b128 v[196:199], v130 offset:16384
	buffer_load_dwordx4 v137, s[88:91], s3 offen lds
	s_add_i32 m0, s100, 0x2000
	ds_read_b128 v[200:203], v130 offset:17408
	buffer_load_dwordx4 v136, s[88:91], s3 offen lds
	s_barrier
; #define WAIT_V(n) asm volatile("s_waitcnt vmcnt(" #n ")" ::: "memory")
; #define WAIT_L(n) asm volatile("s_waitcnt lgkmcnt(" #n ")" ::: "memory")
; #define BAR __builtin_amdgcn_s_barrier()
; #define SCHED __builtin_amdgcn_sched_barrier(0)
; __device__ __forceinline__ void mainloop_8phase(const u16* __restrict__ A, const u16* __restrict__ Bt, int K,
;                                                 f32x4 (&acc)[2][2][4][2], int wid_s, int ld) {
;     ...
;     BAR; WAIT_L(0); MMA(1, 0, At, B0); BAR; SCHED;
;     STAGE(SB(0, 1), Bt, bcol + G_HALF, t + 2);
;     WAIT_V(6); BAR; MMA(1, 1, At, B1); BAR;
;     LDB(B0, 1, 0); SCHED; LDA(At, 1, 0); STAGE(SA(0, 1), A, brow + G_HALF, t + 2);
;     WAIT_L(8); BAR; WAIT_L(0); MMA(0, 0, At, B0); BAR; SCHED;
;     LDB(B1, 1, 1); STAGE(SB(1, 0), Bt, bcol, t + 3);
;     BAR; WAIT_L(0); MMA(0, 1, At, B1); BAR;
	s_waitcnt lgkmcnt(1)
	v_mfma_f32_16x16x32_bf16 v[62:65], v[172:175], v[156:159], v[62:65]
	v_mfma_f32_16x16x32_bf16 v[58:61], v[172:175], v[164:167], v[58:61]
	v_mfma_f32_16x16x32_bf16 v[54:57], v[180:183], v[156:159], v[54:57]
	v_mfma_f32_16x16x32_bf16 v[50:53], v[180:183], v[164:167], v[50:53]
	v_mfma_f32_16x16x32_bf16 v[46:49], v[188:191], v[156:159], v[46:49]
	v_mfma_f32_16x16x32_bf16 v[42:45], v[188:191], v[164:167], v[42:45]
	v_mfma_f32_16x16x32_bf16 v[38:41], v[196:199], v[156:159], v[38:41]
	v_mfma_f32_16x16x32_bf16 v[34:37], v[196:199], v[164:167], v[34:37]
	v_mfma_f32_16x16x32_bf16 v[62:65], v[176:179], v[160:163], v[62:65]
	v_mfma_f32_16x16x32_bf16 v[58:61], v[176:179], v[168:171], v[58:61]
	v_mfma_f32_16x16x32_bf16 v[54:57], v[184:187], v[160:163], v[54:57]
	v_mfma_f32_16x16x32_bf16 v[50:53], v[184:187], v[168:171], v[50:53]
	v_mfma_f32_16x16x32_bf16 v[46:49], v[192:195], v[160:163], v[46:49]
	v_mfma_f32_16x16x32_bf16 v[42:45], v[192:195], v[168:171], v[42:45]
	s_waitcnt lgkmcnt(0)
	v_mfma_f32_16x16x32_bf16 v[38:41], v[200:203], v[160:163], v[38:41]
	v_mfma_f32_16x16x32_bf16 v[34:37], v[200:203], v[168:171], v[34:37]
	s_barrier
	s_add_i32 m0, s100, 0x14000
	s_add_i32 s3, s1, 0xffffff80
	buffer_load_dwordx4 v137, s[4:7], s3 offen lds
	s_add_i32 m0, s100, 0x16000
	s_nop 0
	buffer_load_dwordx4 v136, s[4:7], s3 offen lds
	s_waitcnt vmcnt(6)
	s_barrier
	v_mfma_f32_16x16x32_bf16 v[30:33], v[172:175], v[204:207], v[30:33]
	v_mfma_f32_16x16x32_bf16 v[26:29], v[172:175], v[212:215], v[26:29]
	v_mfma_f32_16x16x32_bf16 v[22:25], v[180:183], v[204:207], v[22:25]
	v_mfma_f32_16x16x32_bf16 v[18:21], v[180:183], v[212:215], v[18:21]
	v_mfma_f32_16x16x32_bf16 v[14:17], v[188:191], v[204:207], v[14:17]
	v_mfma_f32_16x16x32_bf16 v[10:13], v[188:191], v[212:215], v[10:13]
	v_mfma_f32_16x16x32_bf16 v[6:9], v[196:199], v[204:207], v[6:9]
	v_mfma_f32_16x16x32_bf16 v[2:5], v[196:199], v[212:215], v[2:5]
	v_mfma_f32_16x16x32_bf16 v[30:33], v[176:179], v[208:211], v[30:33]
	v_mfma_f32_16x16x32_bf16 v[26:29], v[176:179], v[216:219], v[26:29]
	v_mfma_f32_16x16x32_bf16 v[22:25], v[184:187], v[208:211], v[22:25]
	v_mfma_f32_16x16x32_bf16 v[18:21], v[184:187], v[216:219], v[18:21]
	v_mfma_f32_16x16x32_bf16 v[14:17], v[192:195], v[208:211], v[14:17]
	v_mfma_f32_16x16x32_bf16 v[10:13], v[192:195], v[216:219], v[10:13]
	v_mfma_f32_16x16x32_bf16 v[6:9], v[200:203], v[208:211], v[6:9]
	v_mfma_f32_16x16x32_bf16 v[2:5], v[200:203], v[216:219], v[2:5]
	s_barrier
	ds_read_b128 v[156:159], v135
	ds_read_b128 v[160:163], v135 offset:1024
	ds_read_b128 v[164:167], v135 offset:2048
	ds_read_b128 v[168:171], v135 offset:3072
	s_add_i32 m0, s100, 0x4000
	ds_read_b128 v[172:175], v133 offset:32768
	ds_read_b128 v[176:179], v133 offset:33792
	ds_read_b128 v[180:183], v132 offset:32768
	ds_read_b128 v[184:187], v132 offset:33792
	ds_read_b128 v[188:191], v131 offset:32768
	ds_read_b128 v[192:195], v131 offset:33792
	ds_read_b128 v[196:199], v130 offset:32768
	buffer_load_dwordx4 v137, s[88:91], s3 offen lds
	s_add_i32 m0, s100, 0x6000
	ds_read_b128 v[200:203], v130 offset:33792
	buffer_load_dwordx4 v136, s[88:91], s3 offen lds
	s_waitcnt lgkmcnt(8)
	s_barrier
	s_waitcnt lgkmcnt(1)
	v_mfma_f32_16x16x32_bf16 v[126:129], v[172:175], v[156:159], v[126:129]
	v_mfma_f32_16x16x32_bf16 v[122:125], v[172:175], v[164:167], v[122:125]
	v_mfma_f32_16x16x32_bf16 v[118:121], v[180:183], v[156:159], v[118:121]
	v_mfma_f32_16x16x32_bf16 v[114:117], v[180:183], v[164:167], v[114:117]
	v_mfma_f32_16x16x32_bf16 v[110:113], v[188:191], v[156:159], v[110:113]
	v_mfma_f32_16x16x32_bf16 v[106:109], v[188:191], v[164:167], v[106:109]
	v_mfma_f32_16x16x32_bf16 v[102:105], v[196:199], v[156:159], v[102:105]
	v_mfma_f32_16x16x32_bf16 v[98:101], v[196:199], v[164:167], v[98:101]
	v_mfma_f32_16x16x32_bf16 v[126:129], v[176:179], v[160:163], v[126:129]
	v_mfma_f32_16x16x32_bf16 v[122:125], v[176:179], v[168:171], v[122:125]
	v_mfma_f32_16x16x32_bf16 v[118:121], v[184:187], v[160:163], v[118:121]
	v_mfma_f32_16x16x32_bf16 v[114:117], v[184:187], v[168:171], v[114:117]
	v_mfma_f32_16x16x32_bf16 v[110:113], v[192:195], v[160:163], v[110:113]
	v_mfma_f32_16x16x32_bf16 v[106:109], v[192:195], v[168:171], v[106:109]
	s_waitcnt lgkmcnt(0)
	v_mfma_f32_16x16x32_bf16 v[102:105], v[200:203], v[160:163], v[102:105]
	v_mfma_f32_16x16x32_bf16 v[98:101], v[200:203], v[168:171], v[98:101]
	s_barrier
	s_add_i32 s3, s1, 0xfff80000
	s_add_i32 m0, s100, 0x18000
	ds_read_b128 v[204:207], v134
	ds_read_b128 v[208:211], v134 offset:1024
	ds_read_b128 v[212:215], v134 offset:2048
	buffer_load_dwordx4 v137, s[4:7], s3 offen lds
	s_add_i32 m0, s100, 0x1a000
	ds_read_b128 v[216:219], v134 offset:3072
	buffer_load_dwordx4 v136, s[4:7], s3 offen lds
	s_barrier
	s_waitcnt lgkmcnt(1)
	v_mfma_f32_16x16x32_bf16 v[94:97], v[172:175], v[204:207], v[94:97]
	v_mfma_f32_16x16x32_bf16 v[90:93], v[172:175], v[212:215], v[90:93]
	v_mfma_f32_16x16x32_bf16 v[86:89], v[180:183], v[204:207], v[86:89]
	v_mfma_f32_16x16x32_bf16 v[82:85], v[180:183], v[212:215], v[82:85]
	v_mfma_f32_16x16x32_bf16 v[78:81], v[188:191], v[204:207], v[78:81]
	v_mfma_f32_16x16x32_bf16 v[74:77], v[188:191], v[212:215], v[74:77]
	v_mfma_f32_16x16x32_bf16 v[70:73], v[196:199], v[204:207], v[70:73]
	v_mfma_f32_16x16x32_bf16 v[66:69], v[196:199], v[212:215], v[66:69]
	v_mfma_f32_16x16x32_bf16 v[94:97], v[176:179], v[208:211], v[94:97]
	s_waitcnt lgkmcnt(0)
	v_mfma_f32_16x16x32_bf16 v[90:93], v[176:179], v[216:219], v[90:93]
	v_mfma_f32_16x16x32_bf16 v[86:89], v[184:187], v[208:211], v[86:89]
	v_mfma_f32_16x16x32_bf16 v[82:85], v[184:187], v[216:219], v[82:85]
	v_mfma_f32_16x16x32_bf16 v[78:81], v[192:195], v[208:211], v[78:81]
	v_mfma_f32_16x16x32_bf16 v[74:77], v[192:195], v[216:219], v[74:77]
	v_mfma_f32_16x16x32_bf16 v[70:73], v[200:203], v[208:211], v[70:73]
	v_mfma_f32_16x16x32_bf16 v[66:69], v[200:203], v[216:219], v[66:69]
	s_add_i32 m0, s100, 0x8000
	s_barrier
; #define WAIT_V(n) asm volatile("s_waitcnt vmcnt(" #n ")" ::: "memory")
; #define WAIT_L(n) asm volatile("s_waitcnt lgkmcnt(" #n ")" ::: "memory")
; #define BAR __builtin_amdgcn_s_barrier()
; #define SCHED __builtin_amdgcn_sched_barrier(0)
; __device__ __forceinline__ void mainloop_8phase(const u16* __restrict__ A, const u16* __restrict__ Bt, int K,
;                                                 f32x4 (&acc)[2][2][4][2], int wid_s, int ld) {
;     ...
;     LDA(At, 1, 1); STAGE(SA(1, 0), A, brow, t + 3);
;     BAR; WAIT_L(0); MMA(1, 0, At, B0); BAR; SCHED;
;     STAGE(SB(1, 1), Bt, bcol + G_HALF, t + 3);
;     WAIT_V(6); BAR; MMA(1, 1, At, B1); BAR;
;   }
;   { LDB(B0, 0, 0); LDA(At, 0, 0); STAGE(SA(1, 1), A, brow + G_HALF, nt - 1);
;     BAR; WAIT_L(0); MMA(0, 0, At, B0); BAR;
;     LDB(B1, 0, 1); BAR; WAIT_L(0); MMA(0, 1, At, B1); BAR;
	ds_read_b128 v[172:175], v133 offset:49152
	ds_read_b128 v[176:179], v133 offset:50176
	ds_read_b128 v[180:183], v132 offset:49152
	ds_read_b128 v[184:187], v132 offset:50176
	ds_read_b128 v[188:191], v131 offset:49152
	ds_read_b128 v[192:195], v131 offset:50176
	ds_read_b128 v[196:199], v130 offset:49152
	buffer_load_dwordx4 v137, s[88:91], s3 offen lds
	s_add_i32 m0, s100, 0xa000
	ds_read_b128 v[200:203], v130 offset:50176
	buffer_load_dwordx4 v136, s[88:91], s3 offen lds
	s_barrier
	s_waitcnt lgkmcnt(1)
	v_mfma_f32_16x16x32_bf16 v[62:65], v[172:175], v[156:159], v[62:65]
	v_mfma_f32_16x16x32_bf16 v[58:61], v[172:175], v[164:167], v[58:61]
	v_mfma_f32_16x16x32_bf16 v[54:57], v[180:183], v[156:159], v[54:57]
	v_mfma_f32_16x16x32_bf16 v[50:53], v[180:183], v[164:167], v[50:53]
	v_mfma_f32_16x16x32_bf16 v[46:49], v[188:191], v[156:159], v[46:49]
	v_mfma_f32_16x16x32_bf16 v[42:45], v[188:191], v[164:167], v[42:45]
	v_mfma_f32_16x16x32_bf16 v[38:41], v[196:199], v[156:159], v[38:41]
	v_mfma_f32_16x16x32_bf16 v[34:37], v[196:199], v[164:167], v[34:37]
	v_mfma_f32_16x16x32_bf16 v[62:65], v[176:179], v[160:163], v[62:65]
	v_mfma_f32_16x16x32_bf16 v[58:61], v[176:179], v[168:171], v[58:61]
	v_mfma_f32_16x16x32_bf16 v[54:57], v[184:187], v[160:163], v[54:57]
	v_mfma_f32_16x16x32_bf16 v[50:53], v[184:187], v[168:171], v[50:53]
	v_mfma_f32_16x16x32_bf16 v[46:49], v[192:195], v[160:163], v[46:49]
	v_mfma_f32_16x16x32_bf16 v[42:45], v[192:195], v[168:171], v[42:45]
	s_waitcnt lgkmcnt(0)
	v_mfma_f32_16x16x32_bf16 v[38:41], v[200:203], v[160:163], v[38:41]
	v_mfma_f32_16x16x32_bf16 v[34:37], v[200:203], v[168:171], v[34:37]
	s_barrier
	s_add_i32 m0, s100, 0x1c000
	s_nop 0
	buffer_load_dwordx4 v137, s[4:7], s1 offen lds
	s_add_i32 m0, s100, 0x1e000
	s_nop 0
	buffer_load_dwordx4 v136, s[4:7], s1 offen lds
	s_waitcnt vmcnt(6)
	s_barrier
	v_mfma_f32_16x16x32_bf16 v[30:33], v[172:175], v[204:207], v[30:33]
	v_mfma_f32_16x16x32_bf16 v[26:29], v[172:175], v[212:215], v[26:29]
	v_mfma_f32_16x16x32_bf16 v[22:25], v[180:183], v[204:207], v[22:25]
	v_mfma_f32_16x16x32_bf16 v[18:21], v[180:183], v[212:215], v[18:21]
	v_mfma_f32_16x16x32_bf16 v[14:17], v[188:191], v[204:207], v[14:17]
	v_mfma_f32_16x16x32_bf16 v[10:13], v[188:191], v[212:215], v[10:13]
	v_mfma_f32_16x16x32_bf16 v[6:9], v[196:199], v[204:207], v[6:9]
	v_mfma_f32_16x16x32_bf16 v[2:5], v[196:199], v[212:215], v[2:5]
	v_mfma_f32_16x16x32_bf16 v[30:33], v[176:179], v[208:211], v[30:33]
	v_mfma_f32_16x16x32_bf16 v[26:29], v[176:179], v[216:219], v[26:29]
	v_mfma_f32_16x16x32_bf16 v[22:25], v[184:187], v[208:211], v[22:25]
	v_mfma_f32_16x16x32_bf16 v[18:21], v[184:187], v[216:219], v[18:21]
	v_mfma_f32_16x16x32_bf16 v[14:17], v[192:195], v[208:211], v[14:17]
	v_mfma_f32_16x16x32_bf16 v[10:13], v[192:195], v[216:219], v[10:13]
	v_mfma_f32_16x16x32_bf16 v[6:9], v[200:203], v[208:211], v[6:9]
	v_mfma_f32_16x16x32_bf16 v[2:5], v[200:203], v[216:219], v[2:5]
	s_add_i32 s0, s0, 2
	s_addk_i32 s1, 0x100
	s_cmp_lt_u32 s0, 28
	s_cbranch_scc1 .LBB0_247
	s_barrier
	v_readfirstlane_b32 s0, v145
	s_mov_b32 m0, s0
	s_mov_b32 s1, 0x80f80
	v_readfirstlane_b32 s0, v144
	ds_read_b128 v[138:141], v155
	ds_read_b128 v[148:151], v155 offset:1024
	ds_read_b128 v[156:159], v155 offset:2048
	ds_read_b128 v[152:155], v155 offset:3072
	ds_read_b128 v[160:163], v133
	ds_read_b128 v[164:167], v133 offset:1024
	ds_read_b128 v[168:171], v132
	ds_read_b128 v[172:175], v132 offset:1024
	ds_read_b128 v[176:179], v131
	ds_read_b128 v[180:183], v131 offset:1024
	ds_read_b128 v[184:187], v130
	ds_read_b128 v[188:191], v130 offset:1024
	buffer_load_dwordx4 v137, s[88:91], s1 offen lds
	s_mov_b32 m0, s0
	s_nop 0
	buffer_load_dwordx4 v136, s[88:91], s1 offen lds
	s_barrier
	s_waitcnt lgkmcnt(0)
	v_mfma_f32_16x16x32_bf16 v[126:129], v[160:163], v[138:141], v[126:129]
	v_mfma_f32_16x16x32_bf16 v[118:121], v[168:171], v[138:141], v[118:121]
	v_mfma_f32_16x16x32_bf16 v[110:113], v[176:179], v[138:141], v[110:113]
	v_mfma_f32_16x16x32_bf16 v[102:105], v[184:187], v[138:141], v[102:105]
	v_mfma_f32_16x16x32_bf16 v[126:129], v[164:167], v[148:151], v[126:129]
	v_mfma_f32_16x16x32_bf16 v[122:125], v[160:163], v[156:159], v[122:125]
	v_mfma_f32_16x16x32_bf16 v[118:121], v[172:175], v[148:151], v[118:121]
	v_mfma_f32_16x16x32_bf16 v[114:117], v[168:171], v[156:159], v[114:117]
	v_mfma_f32_16x16x32_bf16 v[110:113], v[180:183], v[148:151], v[110:113]
	v_mfma_f32_16x16x32_bf16 v[106:109], v[176:179], v[156:159], v[106:109]
	v_mfma_f32_16x16x32_bf16 v[102:105], v[188:191], v[148:151], v[102:105]
	v_mfma_f32_16x16x32_bf16 v[98:101], v[184:187], v[156:159], v[98:101]
	v_mfma_f32_16x16x32_bf16 v[142:145], v[164:167], v[152:155], v[122:125]
	v_mfma_f32_16x16x32_bf16 v[192:195], v[172:175], v[152:155], v[114:117]
	v_mfma_f32_16x16x32_bf16 v[196:199], v[180:183], v[152:155], v[106:109]
	v_mfma_f32_16x16x32_bf16 v[200:203], v[188:191], v[152:155], v[98:101]
	s_barrier
	s_nop 1
	ds_read_b128 v[98:101], v147
	ds_read_b128 v[106:109], v147 offset:1024
	ds_read_b128 v[114:117], v147 offset:2048
	ds_read_b128 v[122:125], v147 offset:3072
	s_barrier
; #define WAIT_V(n) asm volatile("s_waitcnt vmcnt(" #n ")" ::: "memory")
; #define WAIT_L(n) asm volatile("s_waitcnt lgkmcnt(" #n ")" ::: "memory")
; #define BAR __builtin_amdgcn_s_barrier()
; __device__ __forceinline__ void mainloop_8phase(const u16* __restrict__ A, const u16* __restrict__ Bt, int K,
;                                                 f32x4 (&acc)[2][2][4][2], int wid_s, int ld) {
;     ...
;     BAR; WAIT_L(0); MMA(0, 0, At, B0); BAR;
;     LDB(B1, 0, 1); BAR; WAIT_L(0); MMA(0, 1, At, B1); BAR;
;     LDA(At, 0, 1); WAIT_V(4); BAR; WAIT_L(0); MMA(1, 0, At, B0); MMA(1, 1, At, B1); BAR; }
;   { LDB(B0, 1, 0); LDA(At, 1, 0); WAIT_V(2); BAR; WAIT_L(0); MMA(0, 0, At, B0); BAR;
	s_waitcnt lgkmcnt(0)
	v_mfma_f32_16x16x32_bf16 v[94:97], v[160:163], v[98:101], v[94:97]
	v_mfma_f32_16x16x32_bf16 v[90:93], v[160:163], v[114:117], v[90:93]
	v_mfma_f32_16x16x32_bf16 v[86:89], v[168:171], v[98:101], v[86:89]
	v_mfma_f32_16x16x32_bf16 v[82:85], v[168:171], v[114:117], v[82:85]
	v_mfma_f32_16x16x32_bf16 v[78:81], v[176:179], v[98:101], v[78:81]
	v_mfma_f32_16x16x32_bf16 v[74:77], v[176:179], v[114:117], v[74:77]
	v_mfma_f32_16x16x32_bf16 v[70:73], v[184:187], v[98:101], v[70:73]
	v_mfma_f32_16x16x32_bf16 v[66:69], v[184:187], v[114:117], v[66:69]
	v_mfma_f32_16x16x32_bf16 v[94:97], v[164:167], v[106:109], v[94:97]
	v_mfma_f32_16x16x32_bf16 v[90:93], v[164:167], v[122:125], v[90:93]
	v_mfma_f32_16x16x32_bf16 v[86:89], v[172:175], v[106:109], v[86:89]
	v_mfma_f32_16x16x32_bf16 v[82:85], v[172:175], v[122:125], v[82:85]
	v_mfma_f32_16x16x32_bf16 v[78:81], v[180:183], v[106:109], v[78:81]
	v_mfma_f32_16x16x32_bf16 v[74:77], v[180:183], v[122:125], v[74:77]
	v_mfma_f32_16x16x32_bf16 v[70:73], v[188:191], v[106:109], v[70:73]
	v_mfma_f32_16x16x32_bf16 v[66:69], v[188:191], v[122:125], v[66:69]
	s_barrier
	ds_read_b128 v[160:163], v133 offset:16384
	ds_read_b128 v[164:167], v133 offset:17408
	ds_read_b128 v[168:171], v132 offset:16384
	ds_read_b128 v[172:175], v132 offset:17408
	ds_read_b128 v[176:179], v131 offset:16384
	ds_read_b128 v[180:183], v131 offset:17408
	ds_read_b128 v[184:187], v130 offset:16384
	ds_read_b128 v[188:191], v130 offset:17408
	s_waitcnt vmcnt(4)
	s_barrier
	s_waitcnt lgkmcnt(0)
	v_mfma_f32_16x16x32_bf16 v[62:65], v[160:163], v[138:141], v[62:65]
	v_mfma_f32_16x16x32_bf16 v[58:61], v[160:163], v[156:159], v[58:61]
	v_mfma_f32_16x16x32_bf16 v[54:57], v[168:171], v[138:141], v[54:57]
	v_mfma_f32_16x16x32_bf16 v[50:53], v[168:171], v[156:159], v[50:53]
	v_mfma_f32_16x16x32_bf16 v[46:49], v[176:179], v[138:141], v[46:49]
	v_mfma_f32_16x16x32_bf16 v[42:45], v[176:179], v[156:159], v[42:45]
	v_mfma_f32_16x16x32_bf16 v[38:41], v[184:187], v[138:141], v[38:41]
	v_mfma_f32_16x16x32_bf16 v[34:37], v[184:187], v[156:159], v[34:37]
	v_mfma_f32_16x16x32_bf16 v[204:207], v[164:167], v[148:151], v[62:65]
	v_mfma_f32_16x16x32_bf16 v[208:211], v[164:167], v[152:155], v[58:61]
	v_mfma_f32_16x16x32_bf16 v[212:215], v[172:175], v[148:151], v[54:57]
	v_mfma_f32_16x16x32_bf16 v[216:219], v[172:175], v[152:155], v[50:53]
	v_mfma_f32_16x16x32_bf16 v[220:223], v[180:183], v[148:151], v[46:49]
	v_mfma_f32_16x16x32_bf16 v[224:227], v[180:183], v[152:155], v[42:45]
	v_mfma_f32_16x16x32_bf16 v[136:139], v[188:191], v[148:151], v[38:41]
	v_mfma_f32_16x16x32_bf16 v[146:149], v[188:191], v[152:155], v[34:37]
	v_mfma_f32_16x16x32_bf16 v[30:33], v[160:163], v[98:101], v[30:33]
	v_mfma_f32_16x16x32_bf16 v[22:25], v[168:171], v[98:101], v[22:25]
	v_mfma_f32_16x16x32_bf16 v[14:17], v[176:179], v[98:101], v[14:17]
	v_mfma_f32_16x16x32_bf16 v[6:9], v[184:187], v[98:101], v[6:9]
	v_mfma_f32_16x16x32_bf16 v[30:33], v[164:167], v[106:109], v[30:33]
	v_mfma_f32_16x16x32_bf16 v[26:29], v[160:163], v[114:117], v[26:29]
	v_mfma_f32_16x16x32_bf16 v[22:25], v[172:175], v[106:109], v[22:25]
	v_mfma_f32_16x16x32_bf16 v[18:21], v[168:171], v[114:117], v[18:21]
	v_mfma_f32_16x16x32_bf16 v[14:17], v[180:183], v[106:109], v[14:17]
	v_mfma_f32_16x16x32_bf16 v[10:13], v[176:179], v[114:117], v[10:13]
	v_mfma_f32_16x16x32_bf16 v[6:9], v[188:191], v[106:109], v[6:9]
	v_mfma_f32_16x16x32_bf16 v[2:5], v[184:187], v[114:117], v[2:5]
	v_mfma_f32_16x16x32_bf16 v[150:153], v[164:167], v[122:125], v[26:29]
	v_mfma_f32_16x16x32_bf16 v[154:157], v[172:175], v[122:125], v[18:21]
	v_mfma_f32_16x16x32_bf16 v[158:161], v[180:183], v[122:125], v[10:13]
	v_mfma_f32_16x16x32_bf16 v[162:165], v[188:191], v[122:125], v[2:5]
	s_barrier
	s_nop 1
	ds_read_b128 v[2:5], v135
	ds_read_b128 v[10:13], v135 offset:1024
	ds_read_b128 v[18:21], v135 offset:2048
	ds_read_b128 v[26:29], v135 offset:3072
	ds_read_b128 v[34:37], v133 offset:32768
	ds_read_b128 v[38:41], v133 offset:33792
	ds_read_b128 v[42:45], v132 offset:32768
	ds_read_b128 v[46:49], v132 offset:33792
	ds_read_b128 v[166:169], v131 offset:32768
	ds_read_b128 v[170:173], v131 offset:33792
	ds_read_b128 v[174:177], v130 offset:32768
	ds_read_b128 v[178:181], v130 offset:33792
	s_waitcnt vmcnt(2)
	s_barrier
; #define WAIT_V(n) asm volatile("s_waitcnt vmcnt(" #n ")" ::: "memory")
; #define WAIT_L(n) asm volatile("s_waitcnt lgkmcnt(" #n ")" ::: "memory")
; #define BAR __builtin_amdgcn_s_barrier()
; __device__ __forceinline__ void mainloop_8phase(const u16* __restrict__ A, const u16* __restrict__ Bt, int K,
;                                                 f32x4 (&acc)[2][2][4][2], int wid_s, int ld) {
;     ...
;     LDA(At, 0, 1); WAIT_V(4); BAR; WAIT_L(0); MMA(1, 0, At, B0); MMA(1, 1, At, B1); BAR; }
;   { LDB(B0, 1, 0); LDA(At, 1, 0); WAIT_V(2); BAR; WAIT_L(0); MMA(0, 0, At, B0); BAR;
;     LDB(B1, 1, 1); WAIT_V(0); BAR; WAIT_L(0); MMA(0, 1, At, B1); BAR;
;     LDA(At, 1, 1); BAR; WAIT_L(0); MMA(1, 0, At, B0); MMA(1, 1, At, B1); BAR; }
;   if (wr == 0) BAR;
	s_waitcnt lgkmcnt(0)
	v_mfma_f32_16x16x32_bf16 v[50:53], v[34:37], v[2:5], v[126:129]
	v_mfma_f32_16x16x32_bf16 v[122:125], v[38:41], v[10:13], v[50:53]
	v_mfma_f32_16x16x32_bf16 v[50:53], v[34:37], v[18:21], v[142:145]
	v_mfma_f32_16x16x32_bf16 v[126:129], v[38:41], v[26:29], v[50:53]
	v_mfma_f32_16x16x32_bf16 v[50:53], v[42:45], v[2:5], v[118:121]
	v_mfma_f32_16x16x32_bf16 v[114:117], v[46:49], v[10:13], v[50:53]
	v_mfma_f32_16x16x32_bf16 v[50:53], v[42:45], v[18:21], v[192:195]
	v_mfma_f32_16x16x32_bf16 v[118:121], v[46:49], v[26:29], v[50:53]
	v_mfma_f32_16x16x32_bf16 v[50:53], v[166:169], v[2:5], v[110:113]
	v_mfma_f32_16x16x32_bf16 v[106:109], v[170:173], v[10:13], v[50:53]
	v_mfma_f32_16x16x32_bf16 v[50:53], v[166:169], v[18:21], v[196:199]
	v_mfma_f32_16x16x32_bf16 v[110:113], v[170:173], v[26:29], v[50:53]
	v_mfma_f32_16x16x32_bf16 v[50:53], v[174:177], v[2:5], v[102:105]
	v_mfma_f32_16x16x32_bf16 v[98:101], v[178:181], v[10:13], v[50:53]
	v_mfma_f32_16x16x32_bf16 v[50:53], v[174:177], v[18:21], v[200:203]
	v_mfma_f32_16x16x32_bf16 v[102:105], v[178:181], v[26:29], v[50:53]
	s_barrier
	ds_read_b128 v[140:143], v134
	ds_read_b128 v[182:185], v134 offset:1024
	ds_read_b128 v[186:189], v134 offset:2048
	ds_read_b128 v[190:193], v134 offset:3072
	s_waitcnt vmcnt(0)
	s_barrier
	s_waitcnt lgkmcnt(0)
	v_mfma_f32_16x16x32_bf16 v[50:53], v[34:37], v[140:143], v[94:97]
	v_mfma_f32_16x16x32_bf16 v[34:37], v[34:37], v[186:189], v[90:93]
	v_mfma_f32_16x16x32_bf16 v[62:65], v[38:41], v[190:193], v[34:37]
	v_mfma_f32_16x16x32_bf16 v[34:37], v[42:45], v[140:143], v[86:89]
	v_mfma_f32_16x16x32_bf16 v[58:61], v[38:41], v[182:185], v[50:53]
	v_mfma_f32_16x16x32_bf16 v[50:53], v[46:49], v[182:185], v[34:37]
	v_mfma_f32_16x16x32_bf16 v[34:37], v[42:45], v[186:189], v[82:85]
	v_mfma_f32_16x16x32_bf16 v[54:57], v[46:49], v[190:193], v[34:37]
	v_mfma_f32_16x16x32_bf16 v[34:37], v[166:169], v[140:143], v[78:81]
	v_mfma_f32_16x16x32_bf16 v[42:45], v[170:173], v[182:185], v[34:37]
	v_mfma_f32_16x16x32_bf16 v[34:37], v[166:169], v[186:189], v[74:77]
	v_mfma_f32_16x16x32_bf16 v[46:49], v[170:173], v[190:193], v[34:37]
	v_mfma_f32_16x16x32_bf16 v[34:37], v[174:177], v[140:143], v[70:73]
	v_mfma_f32_16x16x32_bf16 v[38:41], v[174:177], v[186:189], v[66:69]
	v_mfma_f32_16x16x32_bf16 v[34:37], v[178:181], v[182:185], v[34:37]
	v_mfma_f32_16x16x32_bf16 v[38:41], v[178:181], v[190:193], v[38:41]
	s_barrier
	ds_read_b128 v[166:169], v133 offset:49152
	ds_read_b128 v[170:173], v133 offset:50176
	ds_read_b128 v[174:177], v132 offset:49152
	ds_read_b128 v[132:135], v132 offset:50176
	ds_read_b128 v[178:181], v131 offset:49152
	ds_read_b128 v[194:197], v131 offset:50176
	ds_read_b128 v[198:201], v130 offset:49152
	ds_read_b128 v[228:231], v130 offset:50176
	s_barrier
	s_waitcnt lgkmcnt(0)
	v_mfma_f32_16x16x32_bf16 v[66:69], v[166:169], v[2:5], v[204:207]
	v_mfma_f32_16x16x32_bf16 v[90:93], v[170:173], v[10:13], v[66:69]
	v_mfma_f32_16x16x32_bf16 v[66:69], v[166:169], v[18:21], v[208:211]
	v_mfma_f32_16x16x32_bf16 v[94:97], v[170:173], v[26:29], v[66:69]
	v_mfma_f32_16x16x32_bf16 v[66:69], v[174:177], v[2:5], v[212:215]
	v_mfma_f32_16x16x32_bf16 v[82:85], v[132:135], v[10:13], v[66:69]
	v_mfma_f32_16x16x32_bf16 v[66:69], v[174:177], v[18:21], v[216:219]
	v_mfma_f32_16x16x32_bf16 v[86:89], v[132:135], v[26:29], v[66:69]
	v_mfma_f32_16x16x32_bf16 v[66:69], v[178:181], v[2:5], v[220:223]
	v_mfma_f32_16x16x32_bf16 v[74:77], v[194:197], v[10:13], v[66:69]
	v_mfma_f32_16x16x32_bf16 v[66:69], v[178:181], v[18:21], v[224:227]
	v_mfma_f32_16x16x32_bf16 v[2:5], v[198:201], v[2:5], v[136:139]
	v_mfma_f32_16x16x32_bf16 v[78:81], v[194:197], v[26:29], v[66:69]
	v_mfma_f32_16x16x32_bf16 v[66:69], v[228:231], v[10:13], v[2:5]
	v_mfma_f32_16x16x32_bf16 v[2:5], v[198:201], v[18:21], v[146:149]
	v_mfma_f32_16x16x32_bf16 v[70:73], v[228:231], v[26:29], v[2:5]
	v_mfma_f32_16x16x32_bf16 v[2:5], v[166:169], v[140:143], v[30:33]
	v_mfma_f32_16x16x32_bf16 v[26:29], v[170:173], v[182:185], v[2:5]
	v_mfma_f32_16x16x32_bf16 v[2:5], v[166:169], v[186:189], v[150:153]
	v_mfma_f32_16x16x32_bf16 v[30:33], v[170:173], v[190:193], v[2:5]
	v_mfma_f32_16x16x32_bf16 v[2:5], v[174:177], v[140:143], v[22:25]
	v_mfma_f32_16x16x32_bf16 v[18:21], v[132:135], v[182:185], v[2:5]
	v_mfma_f32_16x16x32_bf16 v[2:5], v[174:177], v[186:189], v[154:157]
	v_mfma_f32_16x16x32_bf16 v[22:25], v[132:135], v[190:193], v[2:5]
	v_mfma_f32_16x16x32_bf16 v[2:5], v[178:181], v[140:143], v[14:17]
	v_mfma_f32_16x16x32_bf16 v[10:13], v[194:197], v[182:185], v[2:5]
	v_mfma_f32_16x16x32_bf16 v[2:5], v[178:181], v[186:189], v[158:161]
	v_mfma_f32_16x16x32_bf16 v[14:17], v[194:197], v[190:193], v[2:5]
	v_mfma_f32_16x16x32_bf16 v[2:5], v[198:201], v[140:143], v[6:9]
	v_mfma_f32_16x16x32_bf16 v[6:9], v[198:201], v[186:189], v[162:165]
	v_mfma_f32_16x16x32_bf16 v[2:5], v[228:231], v[182:185], v[2:5]
	v_mfma_f32_16x16x32_bf16 v[6:9], v[228:231], v[190:193], v[6:9]
	s_movk_i32 s0, 0x100
	v_cmp_gt_u32_e32 vcc, s0, v0
	s_barrier
	s_and_saveexec_b64 s[0:1], vcc
	s_cbranch_execz .LBB0_250
	s_barrier

; #define WAIT_V(n) asm volatile("s_waitcnt vmcnt(" #n ")" ::: "memory")
; #define BAR __builtin_amdgcn_s_barrier()
; __device__ __forceinline__ void mainloop_8phase(const u16* __restrict__ A, const u16* __restrict__ Bt, int K,
;                                                 f32x4 (&acc)[2][2][4][2], int wid_s, int ld) {
;     ...
;   int tid = get_tid(wid_s), wid = tid >> 6, lane = tid & 63, wr = wid >> 2, wc = wid & 3, fr = lane & 15, fq = lane >> 4;
;   unsigned goff0, goff1;
;   {
;     int r0, c0, r1, c1;
;     stage_rc(tid * 16, r0, c0);
;     stage_rc(tid * 16 + 8192, r1, c1);
;     goff0 = (unsigned)(r0 * ld + c0) * 2u;
;     goff1 = (unsigned)(r1 * ld + c1) * 2u;
;   }
;   __amdgpu_buffer_rsrc_t rs_A, rs_Bt;
;   {
;     unsigned long ua = (unsigned long)A, ub = (unsigned long)Bt;
;     unsigned alo = __builtin_amdgcn_readfirstlane((unsigned)ua), ahi = __builtin_amdgcn_readfirstlane((unsigned)(ua >> 32));
;     unsigned blo = __builtin_amdgcn_readfirstlane((unsigned)ub), bhi = __builtin_amdgcn_readfirstlane((unsigned)(ub >> 32));
;     rs_A = __builtin_amdgcn_make_buffer_rsrc((void*)(((unsigned long)ahi << 32) | alo), (short)0, 0x7ffffff0, 0x00020000);
;     rs_Bt = __builtin_amdgcn_make_buffer_rsrc((void*)(((unsigned long)bhi << 32) | blo), (short)0, 0x7ffffff0, 0x00020000);
;   }
;   bf16x8 At[4][2], B0[2][2], B1[2][2];
;   const int brow = 0, bcol = 0;
;   int nt = K / G_BK;
;   if (wr == 1) BAR;
;   WAIT_V(0); BAR;
;   STAGE(SB(1, 0), Bt, bcol, 1); STAGE(SA(1, 0), A, brow, 1); STAGE(SB(1, 1), Bt, bcol + G_HALF, 1);
;   WAIT_V(6); BAR;
;     ...
;     f32x4 acc[2][2][4][2];
; #pragma unroll
;     for (int a = 0; a < 2; ++a)
; #pragma unroll
;       for (int b = 0; b < 2; ++b)
; #pragma unroll
;         for (int c = 0; c < 4; ++c)
; #pragma unroll
;           for (int d = 0; d < 2; ++d) acc[a][b][c][d] = f32x4{0.f, 0.f, 0.f, 0.f};
.LBB0_341:
	s_or_b64 exec, exec, s[2:3]
	v_bfe_i32 v8, v0, 27, 1
	v_lshlrev_b32_e32 v6, 4, v0
	v_lshrrev_b32_e32 v8, 22, v8
	v_add_u32_e32 v8, v6, v8
	v_and_b32_e32 v8, 0xfffffc00, v8
	v_sub_u32_e32 v8, v6, v8
	v_lshrrev_b32_e32 v9, 4, v8
	v_ashrrev_i32_e32 v7, 31, v0
	v_bitop3_b32 v8, v9, v8, 32 bitop3:0x6c
	v_lshrrev_b32_e32 v7, 26, v7
	v_ashrrev_i32_e32 v10, 31, v8
	v_add_u32_e32 v7, v0, v7
	v_lshrrev_b32_e32 v10, 26, v10
	v_ashrrev_i32_e32 v7, 6, v7
	v_add_u32_e32 v10, v8, v10
	v_lshlrev_b32_e32 v9, 3, v7
	v_lshrrev_b32_e32 v11, 6, v10
	v_and_b32_e32 v10, 0xc0, v10
	v_and_b32_e32 v9, 0xffff0, v9
	v_sub_u32_e32 v8, v8, v10
	v_add_u32_e32 v10, 0x2000, v6
	v_add_u32_e32 v9, v11, v9
	v_ashrrev_i32_e32 v11, 31, v10
	v_lshrrev_b32_e32 v11, 22, v11
	v_add_u32_e32 v11, v10, v11
	v_ashrrev_i32_e32 v11, 10, v11
	v_mul_i32_i24_e32 v12, 0x400, v11
	v_sub_u32_e32 v10, v10, v12
	v_lshrrev_b32_e32 v12, 4, v10
	v_bitop3_b32 v10, v12, v10, 32 bitop3:0x6c
	v_readlane_b32 s2, v254, 62
	v_ashrrev_i32_e32 v13, 31, v10
	v_readlane_b32 s3, v254, 63
	v_lshrrev_b32_e32 v13, 26, v13
	s_and_b32 s89, s3, 0xffff
	s_mov_b32 s88, s2
	s_mov_b32 s12, s2
	v_readlane_b32 s2, v255, 0
	v_add_u32_e32 v13, v10, v13
	v_readlane_b32 s3, v255, 1
	v_lshlrev_b32_e32 v7, 5, v7
	v_lshlrev_b32_e32 v12, 3, v11
	v_lshrrev_b32_e32 v14, 6, v13
	v_and_b32_e32 v13, 0xc0, v13
	s_and_b32 s5, s3, 0xffff
	v_readlane_b32 s3, v254, 43
	v_and_b32_e32 v7, 32, v7
	v_ashrrev_i16_sdwa v8, v244, sext(v8) dst_sel:DWORD dst_unused:UNUSED_PAD src0_sel:DWORD src1_sel:BYTE_0
	v_and_b32_e32 v12, 0xffff0, v12
	v_lshlrev_b32_e32 v11, 5, v11
	v_sub_u32_e32 v10, v10, v13
	s_waitcnt vmcnt(7)
	v_add_u32_e32 v138, s3, v6
	v_bfe_i32 v8, v8, 0, 16
	v_add_u32_e32 v12, v14, v12
	v_and_b32_e32 v11, 32, v11
	v_ashrrev_i16_sdwa v10, v244, sext(v10) dst_sel:DWORD dst_unused:UNUSED_PAD src0_sel:DWORD src1_sel:BYTE_0
	v_lshl_or_b32 v7, v9, 11, v7
	v_readfirstlane_b32 s1, v138
	v_add_u32_e32 v139, 0x2000, v138
	v_add_u32_e32 v140, 16, v6
	v_bfe_i32 v10, v10, 0, 16
	v_add_lshl_u32 v136, v7, v8, 1
	v_lshl_or_b32 v7, v12, 11, v11
	s_mov_b32 s4, s2
	s_mov_b32 s16, s2
	s_mov_b32 s17, s5
	s_mov_b32 s18, s90
	s_mov_b32 s19, s91
	s_mov_b32 m0, s1
	s_movk_i32 s2, 0x80
	v_readfirstlane_b32 s1, v139
	v_add_u32_e32 v141, 0x8000, v140
	v_add_lshl_u32 v135, v7, v10, 1
	s_waitcnt vmcnt(0)
	s_barrier
	buffer_load_dwordx4 v136, s[16:19], s2 offen lds
	s_mov_b32 m0, s1
	v_readfirstlane_b32 s1, v141
	v_add_u32_e32 v142, 0xa000, v140
	v_readlane_b32 s6, v254, 44
	s_mov_b32 s13, s89
	s_mov_b32 s14, s90
	s_mov_b32 s15, s91
	buffer_load_dwordx4 v135, s[16:19], s2 offen lds
	s_mov_b32 m0, s1
	v_readfirstlane_b32 s1, v142
	v_add_u32_e32 v143, s6, v6
	buffer_load_dwordx4 v136, s[12:15], s2 offen lds
	s_mov_b32 m0, s1
	v_readfirstlane_b32 s1, v143
	v_add_u32_e32 v146, 0x2000, v143
	buffer_load_dwordx4 v135, s[12:15], s2 offen lds
	s_mov_b32 m0, s1
	s_mov_b32 s2, 0x80080
	v_readfirstlane_b32 s1, v146
	buffer_load_dwordx4 v136, s[16:19], s2 offen lds
	s_mov_b32 m0, s1
	v_and_b32_e32 v4, 15, v2
	buffer_load_dwordx4 v135, s[16:19], s2 offen lds
	v_lshlrev_b32_e32 v7, 2, v2
	v_and_b32_e32 v5, 48, v2
	v_lshlrev_b32_e32 v4, 6, v4
	v_and_b32_e32 v7, 32, v7
	v_bitop3_b32 v4, v4, v7, v5 bitop3:0x36
	v_readlane_b32 s1, v254, 41
	v_lshlrev_b32_e32 v2, 6, v2
	s_waitcnt vmcnt(6)
	v_readlane_b32 s2, v254, 42
	v_add_u32_e32 v8, s1, v4
	v_add_u32_e32 v148, s1, v6
	s_movk_i32 s1, 0x3c0
	v_lshlrev_b32_e32 v11, 6, v0
	v_lshlrev_b32_e32 v3, 13, v3
	v_and_or_b32 v2, v2, s1, v5
	v_add_u32_e32 v9, s2, v4
	v_add_u32_e32 v151, s2, v6
	v_add_u32_e32 v6, s3, v4
	v_add_u32_e32 v10, s6, v4
	v_and_b32_e32 v11, 0x3000, v11
	v_add_u32_e32 v4, 16, v4
	v_xad_u32 v5, v2, v7, 16
	v_or_b32_e32 v7, 0x800, v3
	v_or_b32_e32 v12, 0x1000, v3
	v_or_b32_e32 v13, 0x1800, v3
	v_mov_b32_e32 v2, 0
	v_add_u32_e32 v145, 0xc000, v140
	v_add_u32_e32 v144, 0xe000, v140
	v_add_u32_e32 v149, 0x2000, v148
	v_add_u32_e32 v150, 0x2000, v140
	v_add_u32_e32 v152, 0x2000, v151
	v_add_u32_e32 v153, 0x4000, v140
	v_add_u32_e32 v154, 0x6000, v140
	s_mov_b32 s1, -2
	s_mov_b32 s2, 0x80180
	v_add_u32_e32 v155, v8, v11
	s_waitcnt lgkmcnt(0)
	v_add_u32_e32 v133, v4, v3
	v_add_u32_e32 v132, v5, v7
	v_add_u32_e32 v131, v5, v12
	v_add_u32_e32 v130, v5, v13
	v_add_u32_e32 v147, v9, v11
	v_add_u32_e32 v137, v6, v11
	v_add_u32_e32 v134, v10, v11
	v_mov_b32_e32 v3, v2
	v_mov_b32_e32 v4, v2
	v_mov_b32_e32 v5, v2
	v_mov_b32_e32 v6, v2
	v_mov_b32_e32 v7, v2
	v_mov_b32_e32 v8, v2
	v_mov_b32_e32 v9, v2
	v_mov_b32_e32 v10, v2
	v_mov_b32_e32 v11, v2
	v_mov_b32_e32 v12, v2
	v_mov_b32_e32 v13, v2
	v_mov_b32_e32 v14, v2
	v_mov_b32_e32 v15, v2
	v_mov_b32_e32 v16, v2
	v_mov_b32_e32 v17, v2
	v_mov_b32_e32 v18, v2
	v_mov_b32_e32 v19, v2
	v_mov_b32_e32 v20, v2
	v_mov_b32_e32 v21, v2
	v_mov_b32_e32 v22, v2
	v_mov_b32_e32 v23, v2
	v_mov_b32_e32 v24, v2
	v_mov_b32_e32 v25, v2
	v_mov_b32_e32 v26, v2
	v_mov_b32_e32 v27, v2
	v_mov_b32_e32 v28, v2
	v_mov_b32_e32 v29, v2
	v_mov_b32_e32 v30, v2
	v_mov_b32_e32 v31, v2
	v_mov_b32_e32 v32, v2
	v_mov_b32_e32 v33, v2
	v_mov_b32_e32 v34, v2
	v_mov_b32_e32 v35, v2
	v_mov_b32_e32 v36, v2
	v_mov_b32_e32 v37, v2
	v_mov_b32_e32 v38, v2
	v_mov_b32_e32 v39, v2
	v_mov_b32_e32 v40, v2
	v_mov_b32_e32 v41, v2
	v_mov_b32_e32 v42, v2
	v_mov_b32_e32 v43, v2
	v_mov_b32_e32 v44, v2
	v_mov_b32_e32 v45, v2
	v_mov_b32_e32 v46, v2
	v_mov_b32_e32 v47, v2
	v_mov_b32_e32 v48, v2
	v_mov_b32_e32 v49, v2
	v_mov_b32_e32 v50, v2
	v_mov_b32_e32 v51, v2
	v_mov_b32_e32 v52, v2
	v_mov_b32_e32 v53, v2
	v_mov_b32_e32 v54, v2
	v_mov_b32_e32 v55, v2
	v_mov_b32_e32 v56, v2
	v_mov_b32_e32 v57, v2
	v_mov_b32_e32 v58, v2
	v_mov_b32_e32 v59, v2
	v_mov_b32_e32 v60, v2
	v_mov_b32_e32 v61, v2
	v_mov_b32_e32 v62, v2
	v_mov_b32_e32 v63, v2
	v_mov_b32_e32 v64, v2
	v_mov_b32_e32 v65, v2
	v_mov_b32_e32 v66, v2
	v_mov_b32_e32 v67, v2
	s_waitcnt vmcnt(9)
; #define WAIT_L(n) asm volatile("s_waitcnt lgkmcnt(" #n ")" ::: "memory")
; #define BAR __builtin_amdgcn_s_barrier()
; #define SCHED __builtin_amdgcn_sched_barrier(0)
; __device__ __forceinline__ void mainloop_8phase(const u16* __restrict__ A, const u16* __restrict__ Bt, int K,
;                                                 f32x4 (&acc)[2][2][4][2], int wid_s, int ld) {
;     ...
;   for (int t = 0; t < nt - 2; t += 2) {
;     LDB(B0, 0, 0); SCHED; LDA(At, 0, 0); STAGE(SA(1, 1), A, brow + G_HALF, t + 1);
;     WAIT_L(8); BAR; WAIT_L(0); MMA(0, 0, At, B0); BAR; SCHED;
;     LDB(B1, 0, 1); STAGE(SB(0, 0), Bt, bcol, t + 2);
;     BAR; WAIT_L(0); MMA(0, 1, At, B1); BAR;
;     LDA(At, 0, 1); STAGE(SA(0, 0), A, brow, t + 2);
;     BAR; WAIT_L(0); MMA(1, 0, At, B0); BAR; SCHED;
	v_mov_b32_e32 v68, v2
	v_mov_b32_e32 v69, v2
	v_mov_b32_e32 v70, v2
	v_mov_b32_e32 v71, v2
	s_waitcnt vmcnt(8)
	v_mov_b32_e32 v72, v2
	v_mov_b32_e32 v73, v2
	v_mov_b32_e32 v74, v2
	v_mov_b32_e32 v75, v2
	s_waitcnt vmcnt(7)
	v_mov_b32_e32 v76, v2
	v_mov_b32_e32 v77, v2
	v_mov_b32_e32 v78, v2
	v_mov_b32_e32 v79, v2
	s_waitcnt vmcnt(6)
	v_mov_b32_e32 v80, v2
	v_mov_b32_e32 v81, v2
	v_mov_b32_e32 v82, v2
	v_mov_b32_e32 v83, v2
	v_mov_b32_e32 v84, v2
	v_mov_b32_e32 v85, v2
	v_mov_b32_e32 v86, v2
	v_mov_b32_e32 v87, v2
	v_mov_b32_e32 v88, v2
	v_mov_b32_e32 v89, v2
	v_mov_b32_e32 v90, v2
	v_mov_b32_e32 v91, v2
	v_mov_b32_e32 v92, v2
	v_mov_b32_e32 v93, v2
	v_mov_b32_e32 v94, v2
	v_mov_b32_e32 v95, v2
	v_mov_b32_e32 v96, v2
	v_mov_b32_e32 v97, v2
	v_mov_b32_e32 v98, v2
	v_mov_b32_e32 v99, v2
	v_mov_b32_e32 v100, v2
	v_mov_b32_e32 v101, v2
	v_mov_b32_e32 v102, v2
	v_mov_b32_e32 v103, v2
	v_mov_b32_e32 v104, v2
	v_mov_b32_e32 v105, v2
	v_mov_b32_e32 v106, v2
	v_mov_b32_e32 v107, v2
	v_mov_b32_e32 v108, v2
	v_mov_b32_e32 v109, v2
	v_mov_b32_e32 v110, v2
	v_mov_b32_e32 v111, v2
	v_mov_b32_e32 v112, v2
	v_mov_b32_e32 v113, v2
	v_mov_b32_e32 v114, v2
	v_mov_b32_e32 v115, v2
	v_mov_b32_e32 v116, v2
	v_mov_b32_e32 v117, v2
	v_mov_b32_e32 v118, v2
	v_mov_b32_e32 v119, v2
	v_mov_b32_e32 v120, v2
	v_mov_b32_e32 v121, v2
	v_mov_b32_e32 v122, v2
	v_mov_b32_e32 v123, v2
	v_mov_b32_e32 v124, v2
	v_mov_b32_e32 v125, v2
	v_mov_b32_e32 v126, v2
	v_mov_b32_e32 v127, v2
	v_mov_b32_e32 v128, v2
	v_mov_b32_e32 v129, v2
	s_mov_b32 s6, s90
	s_mov_b32 s7, s91
.LBB0_342:
	s_barrier
	ds_read_b128 v[156:159], v155
	ds_read_b128 v[160:163], v155 offset:1024
	ds_read_b128 v[164:167], v155 offset:2048
	ds_read_b128 v[168:171], v155 offset:3072
	s_add_i32 s3, s2, 0xffffff00
	s_add_i32 m0, s100, 0xc000
	ds_read_b128 v[172:175], v133
	ds_read_b128 v[176:179], v133 offset:1024
	ds_read_b128 v[180:183], v132
	ds_read_b128 v[184:187], v132 offset:1024
	ds_read_b128 v[188:191], v131
	ds_read_b128 v[192:195], v131 offset:1024
	ds_read_b128 v[196:199], v130
	buffer_load_dwordx4 v136, s[88:91], s3 offen lds
	s_add_i32 m0, s100, 0xe000
	ds_read_b128 v[200:203], v130 offset:1024
	buffer_load_dwordx4 v135, s[88:91], s3 offen lds
	s_waitcnt lgkmcnt(8)
	s_barrier
	s_waitcnt lgkmcnt(1)
	v_mfma_f32_16x16x32_bf16 v[126:129], v[172:175], v[156:159], v[126:129]
	v_mfma_f32_16x16x32_bf16 v[122:125], v[172:175], v[164:167], v[122:125]
	v_mfma_f32_16x16x32_bf16 v[118:121], v[180:183], v[156:159], v[118:121]
	v_mfma_f32_16x16x32_bf16 v[114:117], v[180:183], v[164:167], v[114:117]
	v_mfma_f32_16x16x32_bf16 v[110:113], v[188:191], v[156:159], v[110:113]
	v_mfma_f32_16x16x32_bf16 v[106:109], v[188:191], v[164:167], v[106:109]
	v_mfma_f32_16x16x32_bf16 v[102:105], v[196:199], v[156:159], v[102:105]
	v_mfma_f32_16x16x32_bf16 v[98:101], v[196:199], v[164:167], v[98:101]
	v_mfma_f32_16x16x32_bf16 v[126:129], v[176:179], v[160:163], v[126:129]
	v_mfma_f32_16x16x32_bf16 v[122:125], v[176:179], v[168:171], v[122:125]
	v_mfma_f32_16x16x32_bf16 v[118:121], v[184:187], v[160:163], v[118:121]
	v_mfma_f32_16x16x32_bf16 v[114:117], v[184:187], v[168:171], v[114:117]
	v_mfma_f32_16x16x32_bf16 v[110:113], v[192:195], v[160:163], v[110:113]
	v_mfma_f32_16x16x32_bf16 v[106:109], v[192:195], v[168:171], v[106:109]
	s_waitcnt lgkmcnt(0)
	v_mfma_f32_16x16x32_bf16 v[102:105], v[200:203], v[160:163], v[102:105]
	v_mfma_f32_16x16x32_bf16 v[98:101], v[200:203], v[168:171], v[98:101]
	s_barrier
	s_add_i32 s3, s2, 0xfff7ff80
	s_add_i32 m0, s100, 0x10000
	ds_read_b128 v[204:207], v147
	ds_read_b128 v[208:211], v147 offset:1024
	ds_read_b128 v[212:215], v147 offset:2048
	buffer_load_dwordx4 v136, s[4:7], s3 offen lds
	s_add_i32 m0, s100, 0x12000
	ds_read_b128 v[216:219], v147 offset:3072
	buffer_load_dwordx4 v135, s[4:7], s3 offen lds
	s_barrier
	s_waitcnt lgkmcnt(1)
	v_mfma_f32_16x16x32_bf16 v[94:97], v[172:175], v[204:207], v[94:97]
	v_mfma_f32_16x16x32_bf16 v[90:93], v[172:175], v[212:215], v[90:93]
	v_mfma_f32_16x16x32_bf16 v[86:89], v[180:183], v[204:207], v[86:89]
	v_mfma_f32_16x16x32_bf16 v[82:85], v[180:183], v[212:215], v[82:85]
	v_mfma_f32_16x16x32_bf16 v[78:81], v[188:191], v[204:207], v[78:81]
	v_mfma_f32_16x16x32_bf16 v[74:77], v[188:191], v[212:215], v[74:77]
	v_mfma_f32_16x16x32_bf16 v[70:73], v[196:199], v[204:207], v[70:73]
	v_mfma_f32_16x16x32_bf16 v[66:69], v[196:199], v[212:215], v[66:69]
	v_mfma_f32_16x16x32_bf16 v[94:97], v[176:179], v[208:211], v[94:97]
	s_waitcnt lgkmcnt(0)
	v_mfma_f32_16x16x32_bf16 v[90:93], v[176:179], v[216:219], v[90:93]
	v_mfma_f32_16x16x32_bf16 v[86:89], v[184:187], v[208:211], v[86:89]
	v_mfma_f32_16x16x32_bf16 v[82:85], v[184:187], v[216:219], v[82:85]
	v_mfma_f32_16x16x32_bf16 v[78:81], v[192:195], v[208:211], v[78:81]
	v_mfma_f32_16x16x32_bf16 v[74:77], v[192:195], v[216:219], v[74:77]
	v_mfma_f32_16x16x32_bf16 v[70:73], v[200:203], v[208:211], v[70:73]
	v_mfma_f32_16x16x32_bf16 v[66:69], v[200:203], v[216:219], v[66:69]
	s_mov_b32 m0, s100
	s_barrier
	ds_read_b128 v[172:175], v133 offset:16384
	ds_read_b128 v[176:179], v133 offset:17408
	ds_read_b128 v[180:183], v132 offset:16384
	ds_read_b128 v[184:187], v132 offset:17408
	ds_read_b128 v[188:191], v131 offset:16384
	ds_read_b128 v[192:195], v131 offset:17408
	ds_read_b128 v[196:199], v130 offset:16384
	buffer_load_dwordx4 v136, s[88:91], s3 offen lds
	s_add_i32 m0, s100, 0x2000
	ds_read_b128 v[200:203], v130 offset:17408
	buffer_load_dwordx4 v135, s[88:91], s3 offen lds
	s_barrier
; #define WAIT_V(n) asm volatile("s_waitcnt vmcnt(" #n ")" ::: "memory")
; #define WAIT_L(n) asm volatile("s_waitcnt lgkmcnt(" #n ")" ::: "memory")
; #define BAR __builtin_amdgcn_s_barrier()
; #define SCHED __builtin_amdgcn_sched_barrier(0)
; __device__ __forceinline__ void mainloop_8phase(const u16* __restrict__ A, const u16* __restrict__ Bt, int K,
;                                                 f32x4 (&acc)[2][2][4][2], int wid_s, int ld) {
;     ...
;     BAR; WAIT_L(0); MMA(1, 0, At, B0); BAR; SCHED;
;     STAGE(SB(0, 1), Bt, bcol + G_HALF, t + 2);
;     WAIT_V(6); BAR; MMA(1, 1, At, B1); BAR;
;     LDB(B0, 1, 0); SCHED; LDA(At, 1, 0); STAGE(SA(0, 1), A, brow + G_HALF, t + 2);
;     WAIT_L(8); BAR; WAIT_L(0); MMA(0, 0, At, B0); BAR; SCHED;
;     LDB(B1, 1, 1); STAGE(SB(1, 0), Bt, bcol, t + 3);
;     BAR; WAIT_L(0); MMA(0, 1, At, B1); BAR;
	s_waitcnt lgkmcnt(1)
	v_mfma_f32_16x16x32_bf16 v[62:65], v[172:175], v[156:159], v[62:65]
	v_mfma_f32_16x16x32_bf16 v[58:61], v[172:175], v[164:167], v[58:61]
	v_mfma_f32_16x16x32_bf16 v[54:57], v[180:183], v[156:159], v[54:57]
	v_mfma_f32_16x16x32_bf16 v[50:53], v[180:183], v[164:167], v[50:53]
	v_mfma_f32_16x16x32_bf16 v[46:49], v[188:191], v[156:159], v[46:49]
	v_mfma_f32_16x16x32_bf16 v[42:45], v[188:191], v[164:167], v[42:45]
	v_mfma_f32_16x16x32_bf16 v[38:41], v[196:199], v[156:159], v[38:41]
	v_mfma_f32_16x16x32_bf16 v[34:37], v[196:199], v[164:167], v[34:37]
	v_mfma_f32_16x16x32_bf16 v[62:65], v[176:179], v[160:163], v[62:65]
	v_mfma_f32_16x16x32_bf16 v[58:61], v[176:179], v[168:171], v[58:61]
	v_mfma_f32_16x16x32_bf16 v[54:57], v[184:187], v[160:163], v[54:57]
	v_mfma_f32_16x16x32_bf16 v[50:53], v[184:187], v[168:171], v[50:53]
	v_mfma_f32_16x16x32_bf16 v[46:49], v[192:195], v[160:163], v[46:49]
	v_mfma_f32_16x16x32_bf16 v[42:45], v[192:195], v[168:171], v[42:45]
	s_waitcnt lgkmcnt(0)
	v_mfma_f32_16x16x32_bf16 v[38:41], v[200:203], v[160:163], v[38:41]
	v_mfma_f32_16x16x32_bf16 v[34:37], v[200:203], v[168:171], v[34:37]
	s_barrier
	s_add_i32 m0, s100, 0x14000
	s_add_i32 s3, s2, 0xffffff80
	buffer_load_dwordx4 v136, s[4:7], s3 offen lds
	s_add_i32 m0, s100, 0x16000
	s_nop 0
	buffer_load_dwordx4 v135, s[4:7], s3 offen lds
	s_waitcnt vmcnt(6)
	s_barrier
	v_mfma_f32_16x16x32_bf16 v[30:33], v[172:175], v[204:207], v[30:33]
	v_mfma_f32_16x16x32_bf16 v[26:29], v[172:175], v[212:215], v[26:29]
	v_mfma_f32_16x16x32_bf16 v[22:25], v[180:183], v[204:207], v[22:25]
	v_mfma_f32_16x16x32_bf16 v[18:21], v[180:183], v[212:215], v[18:21]
	v_mfma_f32_16x16x32_bf16 v[14:17], v[188:191], v[204:207], v[14:17]
	v_mfma_f32_16x16x32_bf16 v[10:13], v[188:191], v[212:215], v[10:13]
	v_mfma_f32_16x16x32_bf16 v[6:9], v[196:199], v[204:207], v[6:9]
	v_mfma_f32_16x16x32_bf16 v[2:5], v[196:199], v[212:215], v[2:5]
	v_mfma_f32_16x16x32_bf16 v[30:33], v[176:179], v[208:211], v[30:33]
	v_mfma_f32_16x16x32_bf16 v[26:29], v[176:179], v[216:219], v[26:29]
	v_mfma_f32_16x16x32_bf16 v[22:25], v[184:187], v[208:211], v[22:25]
	v_mfma_f32_16x16x32_bf16 v[18:21], v[184:187], v[216:219], v[18:21]
	v_mfma_f32_16x16x32_bf16 v[14:17], v[192:195], v[208:211], v[14:17]
	v_mfma_f32_16x16x32_bf16 v[10:13], v[192:195], v[216:219], v[10:13]
	v_mfma_f32_16x16x32_bf16 v[6:9], v[200:203], v[208:211], v[6:9]
	v_mfma_f32_16x16x32_bf16 v[2:5], v[200:203], v[216:219], v[2:5]
	s_barrier
	ds_read_b128 v[156:159], v137
	ds_read_b128 v[160:163], v137 offset:1024
	ds_read_b128 v[164:167], v137 offset:2048
	ds_read_b128 v[168:171], v137 offset:3072
	s_add_i32 m0, s100, 0x4000
	ds_read_b128 v[172:175], v133 offset:32768
	ds_read_b128 v[176:179], v133 offset:33792
	ds_read_b128 v[180:183], v132 offset:32768
	ds_read_b128 v[184:187], v132 offset:33792
	ds_read_b128 v[188:191], v131 offset:32768
	ds_read_b128 v[192:195], v131 offset:33792
	ds_read_b128 v[196:199], v130 offset:32768
	buffer_load_dwordx4 v136, s[88:91], s3 offen lds
	s_add_i32 m0, s100, 0x6000
	ds_read_b128 v[200:203], v130 offset:33792
	buffer_load_dwordx4 v135, s[88:91], s3 offen lds
	s_waitcnt lgkmcnt(8)
	s_barrier
	s_waitcnt lgkmcnt(1)
	v_mfma_f32_16x16x32_bf16 v[126:129], v[172:175], v[156:159], v[126:129]
	v_mfma_f32_16x16x32_bf16 v[122:125], v[172:175], v[164:167], v[122:125]
	v_mfma_f32_16x16x32_bf16 v[118:121], v[180:183], v[156:159], v[118:121]
	v_mfma_f32_16x16x32_bf16 v[114:117], v[180:183], v[164:167], v[114:117]
	v_mfma_f32_16x16x32_bf16 v[110:113], v[188:191], v[156:159], v[110:113]
	v_mfma_f32_16x16x32_bf16 v[106:109], v[188:191], v[164:167], v[106:109]
	v_mfma_f32_16x16x32_bf16 v[102:105], v[196:199], v[156:159], v[102:105]
	v_mfma_f32_16x16x32_bf16 v[98:101], v[196:199], v[164:167], v[98:101]
	v_mfma_f32_16x16x32_bf16 v[126:129], v[176:179], v[160:163], v[126:129]
	v_mfma_f32_16x16x32_bf16 v[122:125], v[176:179], v[168:171], v[122:125]
	v_mfma_f32_16x16x32_bf16 v[118:121], v[184:187], v[160:163], v[118:121]
	v_mfma_f32_16x16x32_bf16 v[114:117], v[184:187], v[168:171], v[114:117]
	v_mfma_f32_16x16x32_bf16 v[110:113], v[192:195], v[160:163], v[110:113]
	v_mfma_f32_16x16x32_bf16 v[106:109], v[192:195], v[168:171], v[106:109]
	s_waitcnt lgkmcnt(0)
	v_mfma_f32_16x16x32_bf16 v[102:105], v[200:203], v[160:163], v[102:105]
	v_mfma_f32_16x16x32_bf16 v[98:101], v[200:203], v[168:171], v[98:101]
	s_barrier
	s_add_i32 s3, s2, 0xfff80000
	s_add_i32 m0, s100, 0x18000
	ds_read_b128 v[204:207], v134
	ds_read_b128 v[208:211], v134 offset:1024
	ds_read_b128 v[212:215], v134 offset:2048
	buffer_load_dwordx4 v136, s[4:7], s3 offen lds
	s_add_i32 m0, s100, 0x1a000
	ds_read_b128 v[216:219], v134 offset:3072
	buffer_load_dwordx4 v135, s[4:7], s3 offen lds
	s_barrier
	s_waitcnt lgkmcnt(1)
	v_mfma_f32_16x16x32_bf16 v[94:97], v[172:175], v[204:207], v[94:97]
	v_mfma_f32_16x16x32_bf16 v[90:93], v[172:175], v[212:215], v[90:93]
	v_mfma_f32_16x16x32_bf16 v[86:89], v[180:183], v[204:207], v[86:89]
	v_mfma_f32_16x16x32_bf16 v[82:85], v[180:183], v[212:215], v[82:85]
	v_mfma_f32_16x16x32_bf16 v[78:81], v[188:191], v[204:207], v[78:81]
	v_mfma_f32_16x16x32_bf16 v[74:77], v[188:191], v[212:215], v[74:77]
	v_mfma_f32_16x16x32_bf16 v[70:73], v[196:199], v[204:207], v[70:73]
	v_mfma_f32_16x16x32_bf16 v[66:69], v[196:199], v[212:215], v[66:69]
	v_mfma_f32_16x16x32_bf16 v[94:97], v[176:179], v[208:211], v[94:97]
	s_waitcnt lgkmcnt(0)
	v_mfma_f32_16x16x32_bf16 v[90:93], v[176:179], v[216:219], v[90:93]
	v_mfma_f32_16x16x32_bf16 v[86:89], v[184:187], v[208:211], v[86:89]
	v_mfma_f32_16x16x32_bf16 v[82:85], v[184:187], v[216:219], v[82:85]
	v_mfma_f32_16x16x32_bf16 v[78:81], v[192:195], v[208:211], v[78:81]
	v_mfma_f32_16x16x32_bf16 v[74:77], v[192:195], v[216:219], v[74:77]
	v_mfma_f32_16x16x32_bf16 v[70:73], v[200:203], v[208:211], v[70:73]
	v_mfma_f32_16x16x32_bf16 v[66:69], v[200:203], v[216:219], v[66:69]
	s_add_i32 m0, s100, 0x8000
	s_barrier
; #define WAIT_V(n) asm volatile("s_waitcnt vmcnt(" #n ")" ::: "memory")
; #define WAIT_L(n) asm volatile("s_waitcnt lgkmcnt(" #n ")" ::: "memory")
; #define BAR __builtin_amdgcn_s_barrier()
; #define SCHED __builtin_amdgcn_sched_barrier(0)
; __device__ __forceinline__ void mainloop_8phase(const u16* __restrict__ A, const u16* __restrict__ Bt, int K,
;                                                 f32x4 (&acc)[2][2][4][2], int wid_s, int ld) {
;     ...
;     LDA(At, 1, 1); STAGE(SA(1, 0), A, brow, t + 3);
;     BAR; WAIT_L(0); MMA(1, 0, At, B0); BAR; SCHED;
;     STAGE(SB(1, 1), Bt, bcol + G_HALF, t + 3);
;     WAIT_V(6); BAR; MMA(1, 1, At, B1); BAR;
;   }
;   { LDB(B0, 0, 0); LDA(At, 0, 0); STAGE(SA(1, 1), A, brow + G_HALF, nt - 1);
;     BAR; WAIT_L(0); MMA(0, 0, At, B0); BAR;
;     LDB(B1, 0, 1); BAR; WAIT_L(0); MMA(0, 1, At, B1); BAR;
	ds_read_b128 v[172:175], v133 offset:49152
	ds_read_b128 v[176:179], v133 offset:50176
	ds_read_b128 v[180:183], v132 offset:49152
	ds_read_b128 v[184:187], v132 offset:50176
	ds_read_b128 v[188:191], v131 offset:49152
	ds_read_b128 v[192:195], v131 offset:50176
	ds_read_b128 v[196:199], v130 offset:49152
	buffer_load_dwordx4 v136, s[88:91], s3 offen lds
	s_add_i32 m0, s100, 0xa000
	ds_read_b128 v[200:203], v130 offset:50176
	buffer_load_dwordx4 v135, s[88:91], s3 offen lds
	s_barrier
	s_waitcnt lgkmcnt(1)
	v_mfma_f32_16x16x32_bf16 v[62:65], v[172:175], v[156:159], v[62:65]
	v_mfma_f32_16x16x32_bf16 v[58:61], v[172:175], v[164:167], v[58:61]
	v_mfma_f32_16x16x32_bf16 v[54:57], v[180:183], v[156:159], v[54:57]
	v_mfma_f32_16x16x32_bf16 v[50:53], v[180:183], v[164:167], v[50:53]
	v_mfma_f32_16x16x32_bf16 v[46:49], v[188:191], v[156:159], v[46:49]
	v_mfma_f32_16x16x32_bf16 v[42:45], v[188:191], v[164:167], v[42:45]
	v_mfma_f32_16x16x32_bf16 v[38:41], v[196:199], v[156:159], v[38:41]
	v_mfma_f32_16x16x32_bf16 v[34:37], v[196:199], v[164:167], v[34:37]
	v_mfma_f32_16x16x32_bf16 v[62:65], v[176:179], v[160:163], v[62:65]
	v_mfma_f32_16x16x32_bf16 v[58:61], v[176:179], v[168:171], v[58:61]
	v_mfma_f32_16x16x32_bf16 v[54:57], v[184:187], v[160:163], v[54:57]
	v_mfma_f32_16x16x32_bf16 v[50:53], v[184:187], v[168:171], v[50:53]
	v_mfma_f32_16x16x32_bf16 v[46:49], v[192:195], v[160:163], v[46:49]
	v_mfma_f32_16x16x32_bf16 v[42:45], v[192:195], v[168:171], v[42:45]
	s_waitcnt lgkmcnt(0)
	v_mfma_f32_16x16x32_bf16 v[38:41], v[200:203], v[160:163], v[38:41]
	v_mfma_f32_16x16x32_bf16 v[34:37], v[200:203], v[168:171], v[34:37]
	s_barrier
	s_add_i32 m0, s100, 0x1c000
	s_nop 0
	buffer_load_dwordx4 v136, s[4:7], s2 offen lds
	s_add_i32 m0, s100, 0x1e000
	s_nop 0
	buffer_load_dwordx4 v135, s[4:7], s2 offen lds
	s_waitcnt vmcnt(6)
	s_barrier
	v_mfma_f32_16x16x32_bf16 v[30:33], v[172:175], v[204:207], v[30:33]
	v_mfma_f32_16x16x32_bf16 v[26:29], v[172:175], v[212:215], v[26:29]
	v_mfma_f32_16x16x32_bf16 v[22:25], v[180:183], v[204:207], v[22:25]
	v_mfma_f32_16x16x32_bf16 v[18:21], v[180:183], v[212:215], v[18:21]
	v_mfma_f32_16x16x32_bf16 v[14:17], v[188:191], v[204:207], v[14:17]
	v_mfma_f32_16x16x32_bf16 v[10:13], v[188:191], v[212:215], v[10:13]
	v_mfma_f32_16x16x32_bf16 v[6:9], v[196:199], v[204:207], v[6:9]
	v_mfma_f32_16x16x32_bf16 v[2:5], v[196:199], v[212:215], v[2:5]
	v_mfma_f32_16x16x32_bf16 v[30:33], v[176:179], v[208:211], v[30:33]
	v_mfma_f32_16x16x32_bf16 v[26:29], v[176:179], v[216:219], v[26:29]
	v_mfma_f32_16x16x32_bf16 v[22:25], v[184:187], v[208:211], v[22:25]
	v_mfma_f32_16x16x32_bf16 v[18:21], v[184:187], v[216:219], v[18:21]
	v_mfma_f32_16x16x32_bf16 v[14:17], v[192:195], v[208:211], v[14:17]
	v_mfma_f32_16x16x32_bf16 v[10:13], v[192:195], v[216:219], v[10:13]
	v_mfma_f32_16x16x32_bf16 v[6:9], v[200:203], v[208:211], v[6:9]
	v_mfma_f32_16x16x32_bf16 v[2:5], v[200:203], v[216:219], v[2:5]
	s_add_i32 s1, s1, 2
	s_addk_i32 s2, 0x100
	s_cmp_lt_u32 s1, 28
	s_cbranch_scc1 .LBB0_342
	s_barrier
	v_readfirstlane_b32 s1, v145
	s_mov_b32 m0, s1
	s_mov_b32 s2, 0x80f80
	v_readfirstlane_b32 s1, v144
	ds_read_b128 v[138:141], v155
	ds_read_b128 v[148:151], v155 offset:1024
	ds_read_b128 v[156:159], v155 offset:2048
	ds_read_b128 v[152:155], v155 offset:3072
	ds_read_b128 v[160:163], v133
	ds_read_b128 v[164:167], v133 offset:1024
	ds_read_b128 v[168:171], v132
	ds_read_b128 v[172:175], v132 offset:1024
	ds_read_b128 v[176:179], v131
	ds_read_b128 v[180:183], v131 offset:1024
	ds_read_b128 v[184:187], v130
	ds_read_b128 v[188:191], v130 offset:1024
	buffer_load_dwordx4 v136, s[88:91], s2 offen lds
	s_mov_b32 m0, s1
	s_nop 0
	buffer_load_dwordx4 v135, s[88:91], s2 offen lds
	s_barrier
	s_waitcnt lgkmcnt(0)
	v_mfma_f32_16x16x32_bf16 v[126:129], v[160:163], v[138:141], v[126:129]
	v_mfma_f32_16x16x32_bf16 v[118:121], v[168:171], v[138:141], v[118:121]
	v_mfma_f32_16x16x32_bf16 v[110:113], v[176:179], v[138:141], v[110:113]
	v_mfma_f32_16x16x32_bf16 v[102:105], v[184:187], v[138:141], v[102:105]
	v_mfma_f32_16x16x32_bf16 v[126:129], v[164:167], v[148:151], v[126:129]
	v_mfma_f32_16x16x32_bf16 v[122:125], v[160:163], v[156:159], v[122:125]
	v_mfma_f32_16x16x32_bf16 v[118:121], v[172:175], v[148:151], v[118:121]
	v_mfma_f32_16x16x32_bf16 v[114:117], v[168:171], v[156:159], v[114:117]
	v_mfma_f32_16x16x32_bf16 v[110:113], v[180:183], v[148:151], v[110:113]
	v_mfma_f32_16x16x32_bf16 v[106:109], v[176:179], v[156:159], v[106:109]
	v_mfma_f32_16x16x32_bf16 v[102:105], v[188:191], v[148:151], v[102:105]
	v_mfma_f32_16x16x32_bf16 v[98:101], v[184:187], v[156:159], v[98:101]
	v_mfma_f32_16x16x32_bf16 v[142:145], v[164:167], v[152:155], v[122:125]
	v_mfma_f32_16x16x32_bf16 v[192:195], v[172:175], v[152:155], v[114:117]
	v_mfma_f32_16x16x32_bf16 v[196:199], v[180:183], v[152:155], v[106:109]
	v_mfma_f32_16x16x32_bf16 v[200:203], v[188:191], v[152:155], v[98:101]
	s_barrier
	s_nop 1
	ds_read_b128 v[98:101], v147
	ds_read_b128 v[106:109], v147 offset:1024
	ds_read_b128 v[114:117], v147 offset:2048
	ds_read_b128 v[122:125], v147 offset:3072
	s_barrier
; #define WAIT_V(n) asm volatile("s_waitcnt vmcnt(" #n ")" ::: "memory")
; #define WAIT_L(n) asm volatile("s_waitcnt lgkmcnt(" #n ")" ::: "memory")
; #define BAR __builtin_amdgcn_s_barrier()
; __device__ __forceinline__ void mainloop_8phase(const u16* __restrict__ A, const u16* __restrict__ Bt, int K,
;                                                 f32x4 (&acc)[2][2][4][2], int wid_s, int ld) {
;     ...
;     BAR; WAIT_L(0); MMA(0, 0, At, B0); BAR;
;     LDB(B1, 0, 1); BAR; WAIT_L(0); MMA(0, 1, At, B1); BAR;
;     LDA(At, 0, 1); WAIT_V(4); BAR; WAIT_L(0); MMA(1, 0, At, B0); MMA(1, 1, At, B1); BAR; }
;   { LDB(B0, 1, 0); LDA(At, 1, 0); WAIT_V(2); BAR; WAIT_L(0); MMA(0, 0, At, B0); BAR;
	s_waitcnt lgkmcnt(0)
	v_mfma_f32_16x16x32_bf16 v[94:97], v[160:163], v[98:101], v[94:97]
	v_mfma_f32_16x16x32_bf16 v[90:93], v[160:163], v[114:117], v[90:93]
	v_mfma_f32_16x16x32_bf16 v[86:89], v[168:171], v[98:101], v[86:89]
	v_mfma_f32_16x16x32_bf16 v[82:85], v[168:171], v[114:117], v[82:85]
	v_mfma_f32_16x16x32_bf16 v[78:81], v[176:179], v[98:101], v[78:81]
	v_mfma_f32_16x16x32_bf16 v[74:77], v[176:179], v[114:117], v[74:77]
	v_mfma_f32_16x16x32_bf16 v[70:73], v[184:187], v[98:101], v[70:73]
	v_mfma_f32_16x16x32_bf16 v[66:69], v[184:187], v[114:117], v[66:69]
	v_mfma_f32_16x16x32_bf16 v[94:97], v[164:167], v[106:109], v[94:97]
	v_mfma_f32_16x16x32_bf16 v[90:93], v[164:167], v[122:125], v[90:93]
	v_mfma_f32_16x16x32_bf16 v[86:89], v[172:175], v[106:109], v[86:89]
	v_mfma_f32_16x16x32_bf16 v[82:85], v[172:175], v[122:125], v[82:85]
	v_mfma_f32_16x16x32_bf16 v[78:81], v[180:183], v[106:109], v[78:81]
	v_mfma_f32_16x16x32_bf16 v[74:77], v[180:183], v[122:125], v[74:77]
	v_mfma_f32_16x16x32_bf16 v[70:73], v[188:191], v[106:109], v[70:73]
	v_mfma_f32_16x16x32_bf16 v[66:69], v[188:191], v[122:125], v[66:69]
	s_barrier
	ds_read_b128 v[160:163], v133 offset:16384
	ds_read_b128 v[164:167], v133 offset:17408
	ds_read_b128 v[168:171], v132 offset:16384
	ds_read_b128 v[172:175], v132 offset:17408
	ds_read_b128 v[176:179], v131 offset:16384
	ds_read_b128 v[180:183], v131 offset:17408
	ds_read_b128 v[184:187], v130 offset:16384
	ds_read_b128 v[188:191], v130 offset:17408
	s_waitcnt vmcnt(4)
	s_barrier
	s_waitcnt lgkmcnt(0)
	v_mfma_f32_16x16x32_bf16 v[62:65], v[160:163], v[138:141], v[62:65]
	v_mfma_f32_16x16x32_bf16 v[58:61], v[160:163], v[156:159], v[58:61]
	v_mfma_f32_16x16x32_bf16 v[54:57], v[168:171], v[138:141], v[54:57]
	v_mfma_f32_16x16x32_bf16 v[50:53], v[168:171], v[156:159], v[50:53]
	v_mfma_f32_16x16x32_bf16 v[46:49], v[176:179], v[138:141], v[46:49]
	v_mfma_f32_16x16x32_bf16 v[42:45], v[176:179], v[156:159], v[42:45]
	v_mfma_f32_16x16x32_bf16 v[38:41], v[184:187], v[138:141], v[38:41]
	v_mfma_f32_16x16x32_bf16 v[34:37], v[184:187], v[156:159], v[34:37]
	v_mfma_f32_16x16x32_bf16 v[204:207], v[164:167], v[148:151], v[62:65]
	v_mfma_f32_16x16x32_bf16 v[208:211], v[164:167], v[152:155], v[58:61]
	v_mfma_f32_16x16x32_bf16 v[212:215], v[172:175], v[148:151], v[54:57]
	v_mfma_f32_16x16x32_bf16 v[216:219], v[172:175], v[152:155], v[50:53]
	v_mfma_f32_16x16x32_bf16 v[220:223], v[180:183], v[148:151], v[46:49]
	v_mfma_f32_16x16x32_bf16 v[224:227], v[180:183], v[152:155], v[42:45]
	v_mfma_f32_16x16x32_bf16 v[138:141], v[188:191], v[148:151], v[38:41]
	v_mfma_f32_16x16x32_bf16 v[146:149], v[188:191], v[152:155], v[34:37]
	v_mfma_f32_16x16x32_bf16 v[30:33], v[160:163], v[98:101], v[30:33]
	v_mfma_f32_16x16x32_bf16 v[22:25], v[168:171], v[98:101], v[22:25]
	v_mfma_f32_16x16x32_bf16 v[14:17], v[176:179], v[98:101], v[14:17]
	v_mfma_f32_16x16x32_bf16 v[6:9], v[184:187], v[98:101], v[6:9]
	v_mfma_f32_16x16x32_bf16 v[30:33], v[164:167], v[106:109], v[30:33]
	v_mfma_f32_16x16x32_bf16 v[26:29], v[160:163], v[114:117], v[26:29]
	v_mfma_f32_16x16x32_bf16 v[22:25], v[172:175], v[106:109], v[22:25]
	v_mfma_f32_16x16x32_bf16 v[18:21], v[168:171], v[114:117], v[18:21]
	v_mfma_f32_16x16x32_bf16 v[14:17], v[180:183], v[106:109], v[14:17]
	v_mfma_f32_16x16x32_bf16 v[10:13], v[176:179], v[114:117], v[10:13]
	v_mfma_f32_16x16x32_bf16 v[6:9], v[188:191], v[106:109], v[6:9]
	v_mfma_f32_16x16x32_bf16 v[2:5], v[184:187], v[114:117], v[2:5]
	v_mfma_f32_16x16x32_bf16 v[150:153], v[164:167], v[122:125], v[26:29]
	v_mfma_f32_16x16x32_bf16 v[154:157], v[172:175], v[122:125], v[18:21]
	v_mfma_f32_16x16x32_bf16 v[158:161], v[180:183], v[122:125], v[10:13]
	v_mfma_f32_16x16x32_bf16 v[162:165], v[188:191], v[122:125], v[2:5]
	s_barrier
	s_nop 1
	ds_read_b128 v[2:5], v137
	ds_read_b128 v[166:169], v137 offset:1024
	ds_read_b128 v[170:173], v137 offset:2048
	ds_read_b128 v[174:177], v137 offset:3072
	ds_read_b128 v[10:13], v133 offset:32768
	ds_read_b128 v[18:21], v133 offset:33792
	ds_read_b128 v[26:29], v132 offset:32768
	ds_read_b128 v[38:41], v132 offset:33792
	ds_read_b128 v[46:49], v131 offset:32768
	ds_read_b128 v[178:181], v131 offset:33792
	ds_read_b128 v[182:185], v130 offset:32768
	ds_read_b128 v[186:189], v130 offset:33792
	s_waitcnt vmcnt(2)
	s_barrier
; #define WAIT_V(n) asm volatile("s_waitcnt vmcnt(" #n ")" ::: "memory")
; #define WAIT_L(n) asm volatile("s_waitcnt lgkmcnt(" #n ")" ::: "memory")
; #define BAR __builtin_amdgcn_s_barrier()
; __device__ __forceinline__ void mainloop_8phase(const u16* __restrict__ A, const u16* __restrict__ Bt, int K,
;                                                 f32x4 (&acc)[2][2][4][2], int wid_s, int ld) {
;     ...
;     LDA(At, 0, 1); WAIT_V(4); BAR; WAIT_L(0); MMA(1, 0, At, B0); MMA(1, 1, At, B1); BAR; }
;   { LDB(B0, 1, 0); LDA(At, 1, 0); WAIT_V(2); BAR; WAIT_L(0); MMA(0, 0, At, B0); BAR;
;     LDB(B1, 1, 1); WAIT_V(0); BAR; WAIT_L(0); MMA(0, 1, At, B1); BAR;
;     LDA(At, 1, 1); BAR; WAIT_L(0); MMA(1, 0, At, B0); MMA(1, 1, At, B1); BAR; }
;   if (wr == 0) BAR;
	s_waitcnt lgkmcnt(0)
	v_mfma_f32_16x16x32_bf16 v[34:37], v[10:13], v[2:5], v[126:129]
	v_mfma_f32_16x16x32_bf16 v[122:125], v[18:21], v[166:169], v[34:37]
	v_mfma_f32_16x16x32_bf16 v[34:37], v[10:13], v[170:173], v[142:145]
	v_mfma_f32_16x16x32_bf16 v[58:61], v[18:21], v[174:177], v[34:37]
	v_mfma_f32_16x16x32_bf16 v[34:37], v[26:29], v[2:5], v[118:121]
	v_mfma_f32_16x16x32_bf16 v[114:117], v[38:41], v[166:169], v[34:37]
	v_mfma_f32_16x16x32_bf16 v[34:37], v[26:29], v[170:173], v[192:195]
	v_mfma_f32_16x16x32_bf16 v[50:53], v[38:41], v[174:177], v[34:37]
	v_mfma_f32_16x16x32_bf16 v[34:37], v[46:49], v[2:5], v[110:113]
	v_mfma_f32_16x16x32_bf16 v[106:109], v[178:181], v[166:169], v[34:37]
	v_mfma_f32_16x16x32_bf16 v[34:37], v[46:49], v[170:173], v[196:199]
	v_mfma_f32_16x16x32_bf16 v[42:45], v[178:181], v[174:177], v[34:37]
	v_mfma_f32_16x16x32_bf16 v[34:37], v[182:185], v[2:5], v[102:105]
	v_mfma_f32_16x16x32_bf16 v[98:101], v[186:189], v[166:169], v[34:37]
	v_mfma_f32_16x16x32_bf16 v[34:37], v[182:185], v[170:173], v[200:203]
	v_mfma_f32_16x16x32_bf16 v[34:37], v[186:189], v[174:177], v[34:37]
	s_barrier
	ds_read_b128 v[142:145], v134
	ds_read_b128 v[190:193], v134 offset:1024
	ds_read_b128 v[194:197], v134 offset:2048
	ds_read_b128 v[134:137], v134 offset:3072
	s_waitcnt vmcnt(0)
	s_barrier
	s_waitcnt lgkmcnt(0)
	v_mfma_f32_16x16x32_bf16 v[54:57], v[10:13], v[142:145], v[94:97]
	v_mfma_f32_16x16x32_bf16 v[10:13], v[10:13], v[194:197], v[90:93]
	v_mfma_f32_16x16x32_bf16 v[62:65], v[18:21], v[134:137], v[10:13]
	v_mfma_f32_16x16x32_bf16 v[10:13], v[26:29], v[142:145], v[86:89]
	v_mfma_f32_16x16x32_bf16 v[118:121], v[38:41], v[190:193], v[10:13]
	v_mfma_f32_16x16x32_bf16 v[10:13], v[26:29], v[194:197], v[82:85]
	v_mfma_f32_16x16x32_bf16 v[126:129], v[18:21], v[190:193], v[54:57]
	v_mfma_f32_16x16x32_bf16 v[54:57], v[38:41], v[134:137], v[10:13]
	v_mfma_f32_16x16x32_bf16 v[10:13], v[46:49], v[142:145], v[78:81]
	v_mfma_f32_16x16x32_bf16 v[110:113], v[178:181], v[190:193], v[10:13]
	v_mfma_f32_16x16x32_bf16 v[10:13], v[46:49], v[194:197], v[74:77]
	v_mfma_f32_16x16x32_bf16 v[46:49], v[178:181], v[134:137], v[10:13]
	v_mfma_f32_16x16x32_bf16 v[10:13], v[182:185], v[142:145], v[70:73]
	v_mfma_f32_16x16x32_bf16 v[102:105], v[186:189], v[190:193], v[10:13]
	v_mfma_f32_16x16x32_bf16 v[10:13], v[182:185], v[194:197], v[66:69]
	v_mfma_f32_16x16x32_bf16 v[38:41], v[186:189], v[134:137], v[10:13]
	s_barrier
	ds_read_b128 v[66:69], v133 offset:49152
	ds_read_b128 v[78:81], v133 offset:50176
	ds_read_b128 v[178:181], v132 offset:49152
	ds_read_b128 v[182:185], v132 offset:50176
	ds_read_b128 v[186:189], v131 offset:49152
	ds_read_b128 v[198:201], v131 offset:50176
	ds_read_b128 v[228:231], v130 offset:49152
	ds_read_b128 v[130:133], v130 offset:50176
	s_barrier
	s_waitcnt lgkmcnt(0)
	v_mfma_f32_16x16x32_bf16 v[10:13], v[66:69], v[2:5], v[204:207]
	v_mfma_f32_16x16x32_bf16 v[90:93], v[78:81], v[166:169], v[10:13]
	v_mfma_f32_16x16x32_bf16 v[10:13], v[66:69], v[170:173], v[208:211]
	v_mfma_f32_16x16x32_bf16 v[26:29], v[78:81], v[174:177], v[10:13]
	v_mfma_f32_16x16x32_bf16 v[10:13], v[178:181], v[2:5], v[212:215]
	v_mfma_f32_16x16x32_bf16 v[82:85], v[182:185], v[166:169], v[10:13]
	v_mfma_f32_16x16x32_bf16 v[10:13], v[178:181], v[170:173], v[216:219]
	v_mfma_f32_16x16x32_bf16 v[18:21], v[182:185], v[174:177], v[10:13]
	v_mfma_f32_16x16x32_bf16 v[10:13], v[186:189], v[2:5], v[220:223]
	v_mfma_f32_16x16x32_bf16 v[2:5], v[228:231], v[2:5], v[138:141]
	v_mfma_f32_16x16x32_bf16 v[74:77], v[198:201], v[166:169], v[10:13]
	v_mfma_f32_16x16x32_bf16 v[10:13], v[186:189], v[170:173], v[224:227]
	v_mfma_f32_16x16x32_bf16 v[70:73], v[130:133], v[166:169], v[2:5]
	v_mfma_f32_16x16x32_bf16 v[2:5], v[228:231], v[170:173], v[146:149]
	v_mfma_f32_16x16x32_bf16 v[10:13], v[198:201], v[174:177], v[10:13]
	v_mfma_f32_16x16x32_bf16 v[2:5], v[130:133], v[174:177], v[2:5]
	v_mfma_f32_16x16x32_bf16 v[30:33], v[66:69], v[142:145], v[30:33]
	v_mfma_f32_16x16x32_bf16 v[94:97], v[78:81], v[190:193], v[30:33]
	v_mfma_f32_16x16x32_bf16 v[30:33], v[66:69], v[194:197], v[150:153]
	v_mfma_f32_16x16x32_bf16 v[22:25], v[178:181], v[142:145], v[22:25]
	v_mfma_f32_16x16x32_bf16 v[14:17], v[186:189], v[142:145], v[14:17]
	v_mfma_f32_16x16x32_bf16 v[6:9], v[228:231], v[142:145], v[6:9]
	v_mfma_f32_16x16x32_bf16 v[30:33], v[78:81], v[134:137], v[30:33]
	v_mfma_f32_16x16x32_bf16 v[86:89], v[182:185], v[190:193], v[22:25]
	v_mfma_f32_16x16x32_bf16 v[22:25], v[178:181], v[194:197], v[154:157]
	v_mfma_f32_16x16x32_bf16 v[78:81], v[198:201], v[190:193], v[14:17]
	v_mfma_f32_16x16x32_bf16 v[14:17], v[186:189], v[194:197], v[158:161]
	v_mfma_f32_16x16x32_bf16 v[66:69], v[130:133], v[190:193], v[6:9]
	v_mfma_f32_16x16x32_bf16 v[6:9], v[228:231], v[194:197], v[162:165]
	v_mfma_f32_16x16x32_bf16 v[22:25], v[182:185], v[134:137], v[22:25]
	v_mfma_f32_16x16x32_bf16 v[14:17], v[198:201], v[134:137], v[14:17]
	v_mfma_f32_16x16x32_bf16 v[6:9], v[130:133], v[134:137], v[6:9]
	s_movk_i32 s1, 0x100
	v_cmp_gt_u32_e32 vcc, s1, v0
	s_barrier
	s_and_saveexec_b64 s[2:3], vcc
	s_cbranch_execz .LBB0_345
	s_barrier

; #define WAIT_L(n) asm volatile("s_waitcnt lgkmcnt(" #n ")" ::: "memory")
; #define BAR __builtin_amdgcn_s_barrier()
; #define SCHED __builtin_amdgcn_sched_barrier(0)
; __device__ __forceinline__ void mainloop_8phase(const u16* __restrict__ A, const u16* __restrict__ Bt, int K,
;                                                 f32x4 (&acc)[2][2][4][2], int wid_s, int ld) {
;     ...
;   for (int t = 0; t < nt - 2; t += 2) {
;     LDB(B0, 0, 0); SCHED; LDA(At, 0, 0); STAGE(SA(1, 1), A, brow + G_HALF, t + 1);
;     WAIT_L(8); BAR; WAIT_L(0); MMA(0, 0, At, B0); BAR; SCHED;
;     LDB(B1, 0, 1); STAGE(SB(0, 0), Bt, bcol, t + 2);
;     BAR; WAIT_L(0); MMA(0, 1, At, B1); BAR;
;     LDA(At, 0, 1); STAGE(SA(0, 0), A, brow, t + 2);
;     BAR; WAIT_L(0); MMA(1, 0, At, B0); BAR; SCHED;
.LBB0_565:
	s_barrier
	ds_read_b128 v[158:161], v156
	ds_read_b128 v[162:165], v156 offset:1024
	ds_read_b128 v[166:169], v156 offset:2048
	ds_read_b128 v[170:173], v156 offset:3072
	s_add_i32 s15, s27, s3
	s_add_i32 s6, s15, 0x80
	s_add_i32 m0, s100, 0xc000
	ds_read_b128 v[174:177], v134
	ds_read_b128 v[178:181], v134 offset:1024
	ds_read_b128 v[182:185], v133
	ds_read_b128 v[186:189], v133 offset:1024
	ds_read_b128 v[190:193], v132
	ds_read_b128 v[194:197], v132 offset:1024
	ds_read_b128 v[198:201], v131
	buffer_load_dwordx4 v137, s[76:79], s6 offen lds
	s_add_i32 m0, s100, 0xe000
	ds_read_b128 v[202:205], v131 offset:1024
	buffer_load_dwordx4 v138, s[76:79], s6 offen lds
	s_waitcnt lgkmcnt(8)
	s_barrier
	s_waitcnt lgkmcnt(1)
	v_mfma_f32_16x16x32_bf16 v[126:129], v[174:177], v[158:161], v[126:129]
	v_mfma_f32_16x16x32_bf16 v[122:125], v[174:177], v[166:169], v[122:125]
	v_mfma_f32_16x16x32_bf16 v[118:121], v[182:185], v[158:161], v[118:121]
	v_mfma_f32_16x16x32_bf16 v[114:117], v[182:185], v[166:169], v[114:117]
	v_mfma_f32_16x16x32_bf16 v[110:113], v[190:193], v[158:161], v[110:113]
	v_mfma_f32_16x16x32_bf16 v[106:109], v[190:193], v[166:169], v[106:109]
	v_mfma_f32_16x16x32_bf16 v[102:105], v[198:201], v[158:161], v[102:105]
	v_mfma_f32_16x16x32_bf16 v[98:101], v[198:201], v[166:169], v[98:101]
	v_mfma_f32_16x16x32_bf16 v[126:129], v[178:181], v[162:165], v[126:129]
	v_mfma_f32_16x16x32_bf16 v[122:125], v[178:181], v[170:173], v[122:125]
	v_mfma_f32_16x16x32_bf16 v[118:121], v[186:189], v[162:165], v[118:121]
	v_mfma_f32_16x16x32_bf16 v[114:117], v[186:189], v[170:173], v[114:117]
	v_mfma_f32_16x16x32_bf16 v[110:113], v[194:197], v[162:165], v[110:113]
	v_mfma_f32_16x16x32_bf16 v[106:109], v[194:197], v[170:173], v[106:109]
	s_waitcnt lgkmcnt(0)
	v_mfma_f32_16x16x32_bf16 v[102:105], v[202:205], v[162:165], v[102:105]
	v_mfma_f32_16x16x32_bf16 v[98:101], v[202:205], v[170:173], v[98:101]
	s_barrier
	s_add_i32 s14, s3, 0x100
	s_mov_b32 s6, s78
	s_mov_b32 s7, s79
	s_add_i32 m0, s100, 0x10000
	ds_read_b128 v[206:209], v148
	ds_read_b128 v[210:213], v148 offset:1024
	ds_read_b128 v[214:217], v148 offset:2048
	ds_read_b128 v[218:221], v148 offset:3072
	buffer_load_dwordx4 v137, s[4:7], s14 offen lds
	s_add_i32 m0, s100, 0x12000
	s_add_i32 s2, s2, 2
	buffer_load_dwordx4 v138, s[4:7], s14 offen lds
	s_barrier
	s_waitcnt lgkmcnt(0)
	v_mfma_f32_16x16x32_bf16 v[94:97], v[174:177], v[206:209], v[94:97]
	v_mfma_f32_16x16x32_bf16 v[90:93], v[174:177], v[214:217], v[90:93]
	v_mfma_f32_16x16x32_bf16 v[86:89], v[182:185], v[206:209], v[86:89]
	v_mfma_f32_16x16x32_bf16 v[82:85], v[182:185], v[214:217], v[82:85]
	v_mfma_f32_16x16x32_bf16 v[78:81], v[190:193], v[206:209], v[78:81]
	v_mfma_f32_16x16x32_bf16 v[74:77], v[190:193], v[214:217], v[74:77]
	v_mfma_f32_16x16x32_bf16 v[70:73], v[198:201], v[206:209], v[70:73]
	v_mfma_f32_16x16x32_bf16 v[66:69], v[198:201], v[214:217], v[66:69]
	v_mfma_f32_16x16x32_bf16 v[94:97], v[178:181], v[210:213], v[94:97]
	v_mfma_f32_16x16x32_bf16 v[90:93], v[178:181], v[218:221], v[90:93]
	v_mfma_f32_16x16x32_bf16 v[86:89], v[186:189], v[210:213], v[86:89]
	v_mfma_f32_16x16x32_bf16 v[82:85], v[186:189], v[218:221], v[82:85]
	v_mfma_f32_16x16x32_bf16 v[78:81], v[194:197], v[210:213], v[78:81]
	v_mfma_f32_16x16x32_bf16 v[74:77], v[194:197], v[218:221], v[74:77]
	v_mfma_f32_16x16x32_bf16 v[70:73], v[202:205], v[210:213], v[70:73]
	v_mfma_f32_16x16x32_bf16 v[66:69], v[202:205], v[218:221], v[66:69]
	s_mov_b32 m0, s100
	s_barrier
	ds_read_b128 v[174:177], v134 offset:16384
	ds_read_b128 v[178:181], v134 offset:17408
	ds_read_b128 v[182:185], v133 offset:16384
	ds_read_b128 v[186:189], v133 offset:17408
	ds_read_b128 v[190:193], v132 offset:16384
	ds_read_b128 v[194:197], v132 offset:17408
	ds_read_b128 v[198:201], v131 offset:16384
	buffer_load_dwordx4 v137, s[76:79], s14 offen lds
	s_add_i32 m0, s100, 0x2000
	ds_read_b128 v[202:205], v131 offset:17408
	buffer_load_dwordx4 v138, s[76:79], s14 offen lds
	s_barrier
	s_waitcnt lgkmcnt(1)
	v_mfma_f32_16x16x32_bf16 v[62:65], v[174:177], v[158:161], v[62:65]
	v_mfma_f32_16x16x32_bf16 v[58:61], v[174:177], v[166:169], v[58:61]
	v_mfma_f32_16x16x32_bf16 v[54:57], v[182:185], v[158:161], v[54:57]
	v_mfma_f32_16x16x32_bf16 v[50:53], v[182:185], v[166:169], v[50:53]
	v_mfma_f32_16x16x32_bf16 v[46:49], v[190:193], v[158:161], v[46:49]
	v_mfma_f32_16x16x32_bf16 v[42:45], v[190:193], v[166:169], v[42:45]
	v_mfma_f32_16x16x32_bf16 v[38:41], v[198:201], v[158:161], v[38:41]
	v_mfma_f32_16x16x32_bf16 v[34:37], v[198:201], v[166:169], v[34:37]
	v_mfma_f32_16x16x32_bf16 v[62:65], v[178:181], v[162:165], v[62:65]
	v_mfma_f32_16x16x32_bf16 v[58:61], v[178:181], v[170:173], v[58:61]
	v_mfma_f32_16x16x32_bf16 v[54:57], v[186:189], v[162:165], v[54:57]
	v_mfma_f32_16x16x32_bf16 v[50:53], v[186:189], v[170:173], v[50:53]
	v_mfma_f32_16x16x32_bf16 v[46:49], v[194:197], v[162:165], v[46:49]
	v_mfma_f32_16x16x32_bf16 v[42:45], v[194:197], v[170:173], v[42:45]
	s_waitcnt lgkmcnt(0)
	v_mfma_f32_16x16x32_bf16 v[38:41], v[202:205], v[162:165], v[38:41]
	v_mfma_f32_16x16x32_bf16 v[34:37], v[202:205], v[170:173], v[34:37]
	s_barrier
	s_add_i32 m0, s100, 0x14000
	s_add_i32 s34, s15, 0x100
	buffer_load_dwordx4 v137, s[4:7], s34 offen lds
	s_add_i32 m0, s100, 0x16000
	s_nop 0
	buffer_load_dwordx4 v138, s[4:7], s34 offen lds
	s_waitcnt vmcnt(6)
	s_barrier
; #define WAIT_V(n) asm volatile("s_waitcnt vmcnt(" #n ")" ::: "memory")
; #define WAIT_L(n) asm volatile("s_waitcnt lgkmcnt(" #n ")" ::: "memory")
; #define BAR __builtin_amdgcn_s_barrier()
; #define SCHED __builtin_amdgcn_sched_barrier(0)
; __device__ __forceinline__ void mainloop_8phase(const u16* __restrict__ A, const u16* __restrict__ Bt, int K,
;                                                 f32x4 (&acc)[2][2][4][2], int wid_s, int ld) {
;     ...
;     BAR; WAIT_L(0); MMA(1, 0, At, B0); BAR; SCHED;
;     STAGE(SB(0, 1), Bt, bcol + G_HALF, t + 2);
;     WAIT_V(6); BAR; MMA(1, 1, At, B1); BAR;
;     LDB(B0, 1, 0); SCHED; LDA(At, 1, 0); STAGE(SA(0, 1), A, brow + G_HALF, t + 2);
;     WAIT_L(8); BAR; WAIT_L(0); MMA(0, 0, At, B0); BAR; SCHED;
;     LDB(B1, 1, 1); STAGE(SB(1, 0), Bt, bcol, t + 3);
;     BAR; WAIT_L(0); MMA(0, 1, At, B1); BAR;
;     LDA(At, 1, 1); STAGE(SA(1, 0), A, brow, t + 3);
	v_mfma_f32_16x16x32_bf16 v[30:33], v[174:177], v[206:209], v[30:33]
	v_mfma_f32_16x16x32_bf16 v[26:29], v[174:177], v[214:217], v[26:29]
	v_mfma_f32_16x16x32_bf16 v[22:25], v[182:185], v[206:209], v[22:25]
	v_mfma_f32_16x16x32_bf16 v[18:21], v[182:185], v[214:217], v[18:21]
	v_mfma_f32_16x16x32_bf16 v[14:17], v[190:193], v[206:209], v[14:17]
	v_mfma_f32_16x16x32_bf16 v[10:13], v[190:193], v[214:217], v[10:13]
	v_mfma_f32_16x16x32_bf16 v[6:9], v[198:201], v[206:209], v[6:9]
	v_mfma_f32_16x16x32_bf16 v[2:5], v[198:201], v[214:217], v[2:5]
	v_mfma_f32_16x16x32_bf16 v[30:33], v[178:181], v[210:213], v[30:33]
	v_mfma_f32_16x16x32_bf16 v[26:29], v[178:181], v[218:221], v[26:29]
	v_mfma_f32_16x16x32_bf16 v[22:25], v[186:189], v[210:213], v[22:25]
	v_mfma_f32_16x16x32_bf16 v[18:21], v[186:189], v[218:221], v[18:21]
	v_mfma_f32_16x16x32_bf16 v[14:17], v[194:197], v[210:213], v[14:17]
	v_mfma_f32_16x16x32_bf16 v[10:13], v[194:197], v[218:221], v[10:13]
	v_mfma_f32_16x16x32_bf16 v[6:9], v[202:205], v[210:213], v[6:9]
	v_mfma_f32_16x16x32_bf16 v[2:5], v[202:205], v[218:221], v[2:5]
	s_barrier
	ds_read_b128 v[158:161], v136
	ds_read_b128 v[162:165], v136 offset:1024
	ds_read_b128 v[166:169], v136 offset:2048
	ds_read_b128 v[170:173], v136 offset:3072
	s_add_i32 m0, s100, 0x4000
	ds_read_b128 v[174:177], v134 offset:32768
	ds_read_b128 v[178:181], v134 offset:33792
	ds_read_b128 v[182:185], v133 offset:32768
	ds_read_b128 v[186:189], v133 offset:33792
	ds_read_b128 v[190:193], v132 offset:32768
	ds_read_b128 v[194:197], v132 offset:33792
	ds_read_b128 v[198:201], v131 offset:32768
	buffer_load_dwordx4 v137, s[76:79], s34 offen lds
	s_add_i32 m0, s100, 0x6000
	ds_read_b128 v[202:205], v131 offset:33792
	buffer_load_dwordx4 v138, s[76:79], s34 offen lds
	s_waitcnt lgkmcnt(8)
	s_barrier
	s_waitcnt lgkmcnt(1)
	v_mfma_f32_16x16x32_bf16 v[126:129], v[174:177], v[158:161], v[126:129]
	v_mfma_f32_16x16x32_bf16 v[122:125], v[174:177], v[166:169], v[122:125]
	v_mfma_f32_16x16x32_bf16 v[118:121], v[182:185], v[158:161], v[118:121]
	v_mfma_f32_16x16x32_bf16 v[114:117], v[182:185], v[166:169], v[114:117]
	v_mfma_f32_16x16x32_bf16 v[110:113], v[190:193], v[158:161], v[110:113]
	v_mfma_f32_16x16x32_bf16 v[106:109], v[190:193], v[166:169], v[106:109]
	v_mfma_f32_16x16x32_bf16 v[102:105], v[198:201], v[158:161], v[102:105]
	v_mfma_f32_16x16x32_bf16 v[98:101], v[198:201], v[166:169], v[98:101]
	v_mfma_f32_16x16x32_bf16 v[126:129], v[178:181], v[162:165], v[126:129]
	v_mfma_f32_16x16x32_bf16 v[122:125], v[178:181], v[170:173], v[122:125]
	v_mfma_f32_16x16x32_bf16 v[118:121], v[186:189], v[162:165], v[118:121]
	v_mfma_f32_16x16x32_bf16 v[114:117], v[186:189], v[170:173], v[114:117]
	v_mfma_f32_16x16x32_bf16 v[110:113], v[194:197], v[162:165], v[110:113]
	v_mfma_f32_16x16x32_bf16 v[106:109], v[194:197], v[170:173], v[106:109]
	s_waitcnt lgkmcnt(0)
	v_mfma_f32_16x16x32_bf16 v[102:105], v[202:205], v[162:165], v[102:105]
	v_mfma_f32_16x16x32_bf16 v[98:101], v[202:205], v[170:173], v[98:101]
	s_barrier
	s_addk_i32 s3, 0x180
	s_add_i32 m0, s100, 0x18000
	ds_read_b128 v[206:209], v135
	ds_read_b128 v[210:213], v135 offset:1024
	ds_read_b128 v[214:217], v135 offset:2048
	buffer_load_dwordx4 v137, s[4:7], s3 offen lds
	s_add_i32 m0, s100, 0x1a000
	ds_read_b128 v[218:221], v135 offset:3072
	buffer_load_dwordx4 v138, s[4:7], s3 offen lds
	s_barrier
	s_waitcnt lgkmcnt(1)
	v_mfma_f32_16x16x32_bf16 v[94:97], v[174:177], v[206:209], v[94:97]
	v_mfma_f32_16x16x32_bf16 v[90:93], v[174:177], v[214:217], v[90:93]
	v_mfma_f32_16x16x32_bf16 v[86:89], v[182:185], v[206:209], v[86:89]
	v_mfma_f32_16x16x32_bf16 v[82:85], v[182:185], v[214:217], v[82:85]
	v_mfma_f32_16x16x32_bf16 v[78:81], v[190:193], v[206:209], v[78:81]
	v_mfma_f32_16x16x32_bf16 v[74:77], v[190:193], v[214:217], v[74:77]
	v_mfma_f32_16x16x32_bf16 v[70:73], v[198:201], v[206:209], v[70:73]
	v_mfma_f32_16x16x32_bf16 v[66:69], v[198:201], v[214:217], v[66:69]
	v_mfma_f32_16x16x32_bf16 v[94:97], v[178:181], v[210:213], v[94:97]
	s_waitcnt lgkmcnt(0)
	v_mfma_f32_16x16x32_bf16 v[90:93], v[178:181], v[218:221], v[90:93]
	v_mfma_f32_16x16x32_bf16 v[86:89], v[186:189], v[210:213], v[86:89]
	v_mfma_f32_16x16x32_bf16 v[82:85], v[186:189], v[218:221], v[82:85]
	v_mfma_f32_16x16x32_bf16 v[78:81], v[194:197], v[210:213], v[78:81]
	v_mfma_f32_16x16x32_bf16 v[74:77], v[194:197], v[218:221], v[74:77]
	v_mfma_f32_16x16x32_bf16 v[70:73], v[202:205], v[210:213], v[70:73]
	v_mfma_f32_16x16x32_bf16 v[66:69], v[202:205], v[218:221], v[66:69]
	s_add_i32 m0, s100, 0x8000
	s_barrier
	ds_read_b128 v[174:177], v134 offset:49152
	ds_read_b128 v[178:181], v134 offset:50176
	ds_read_b128 v[182:185], v133 offset:49152
	ds_read_b128 v[186:189], v133 offset:50176
	ds_read_b128 v[190:193], v132 offset:49152
	ds_read_b128 v[194:197], v132 offset:50176
	ds_read_b128 v[198:201], v131 offset:49152
	buffer_load_dwordx4 v137, s[76:79], s3 offen lds
	s_add_i32 m0, s100, 0xa000
	ds_read_b128 v[202:205], v131 offset:50176
	buffer_load_dwordx4 v138, s[76:79], s3 offen lds
	s_barrier
	s_waitcnt lgkmcnt(1)
	v_mfma_f32_16x16x32_bf16 v[62:65], v[174:177], v[158:161], v[62:65]
	v_mfma_f32_16x16x32_bf16 v[58:61], v[174:177], v[166:169], v[58:61]
	v_mfma_f32_16x16x32_bf16 v[54:57], v[182:185], v[158:161], v[54:57]
	v_mfma_f32_16x16x32_bf16 v[50:53], v[182:185], v[166:169], v[50:53]
	v_mfma_f32_16x16x32_bf16 v[46:49], v[190:193], v[158:161], v[46:49]
	v_mfma_f32_16x16x32_bf16 v[42:45], v[190:193], v[166:169], v[42:45]
	v_mfma_f32_16x16x32_bf16 v[38:41], v[198:201], v[158:161], v[38:41]
	v_mfma_f32_16x16x32_bf16 v[34:37], v[198:201], v[166:169], v[34:37]
	v_mfma_f32_16x16x32_bf16 v[62:65], v[178:181], v[162:165], v[62:65]
	v_mfma_f32_16x16x32_bf16 v[58:61], v[178:181], v[170:173], v[58:61]
	v_mfma_f32_16x16x32_bf16 v[54:57], v[186:189], v[162:165], v[54:57]
	v_mfma_f32_16x16x32_bf16 v[50:53], v[186:189], v[170:173], v[50:53]
	v_mfma_f32_16x16x32_bf16 v[46:49], v[194:197], v[162:165], v[46:49]
	v_mfma_f32_16x16x32_bf16 v[42:45], v[194:197], v[170:173], v[42:45]
	s_waitcnt lgkmcnt(0)
	v_mfma_f32_16x16x32_bf16 v[38:41], v[202:205], v[162:165], v[38:41]
	v_mfma_f32_16x16x32_bf16 v[34:37], v[202:205], v[170:173], v[34:37]
	s_barrier
; #define WAIT_V(n) asm volatile("s_waitcnt vmcnt(" #n ")" ::: "memory")
; #define WAIT_L(n) asm volatile("s_waitcnt lgkmcnt(" #n ")" ::: "memory")
; #define BAR __builtin_amdgcn_s_barrier()
; #define SCHED __builtin_amdgcn_sched_barrier(0)
; __device__ __forceinline__ void mainloop_8phase(const u16* __restrict__ A, const u16* __restrict__ Bt, int K,
;                                                 f32x4 (&acc)[2][2][4][2], int wid_s, int ld) {
;     ...
;     LDA(At, 1, 1); STAGE(SA(1, 0), A, brow, t + 3);
;     BAR; WAIT_L(0); MMA(1, 0, At, B0); BAR; SCHED;
;     STAGE(SB(1, 1), Bt, bcol + G_HALF, t + 3);
;     WAIT_V(6); BAR; MMA(1, 1, At, B1); BAR;
;   }
;   { LDB(B0, 0, 0); LDA(At, 0, 0); STAGE(SA(1, 1), A, brow + G_HALF, nt - 1);
;     BAR; WAIT_L(0); MMA(0, 0, At, B0); BAR;
;     LDB(B1, 0, 1); BAR; WAIT_L(0); MMA(0, 1, At, B1); BAR;
;     LDA(At, 0, 1); WAIT_V(4); BAR; WAIT_L(0); MMA(1, 0, At, B0); MMA(1, 1, At, B1); BAR; }
;   { LDB(B0, 1, 0); LDA(At, 1, 0); WAIT_V(2); BAR; WAIT_L(0); MMA(0, 0, At, B0); BAR;
	s_addk_i32 s15, 0x180
	s_add_i32 m0, s100, 0x1c000
	s_nop 0
	buffer_load_dwordx4 v137, s[4:7], s15 offen lds
	s_add_i32 m0, s100, 0x1e000
	s_nop 0
	buffer_load_dwordx4 v138, s[4:7], s15 offen lds
	s_waitcnt vmcnt(6)
	s_barrier
	v_mfma_f32_16x16x32_bf16 v[30:33], v[174:177], v[206:209], v[30:33]
	v_mfma_f32_16x16x32_bf16 v[26:29], v[174:177], v[214:217], v[26:29]
	v_mfma_f32_16x16x32_bf16 v[22:25], v[182:185], v[206:209], v[22:25]
	v_mfma_f32_16x16x32_bf16 v[18:21], v[182:185], v[214:217], v[18:21]
	v_mfma_f32_16x16x32_bf16 v[14:17], v[190:193], v[206:209], v[14:17]
	v_mfma_f32_16x16x32_bf16 v[10:13], v[190:193], v[214:217], v[10:13]
	v_mfma_f32_16x16x32_bf16 v[6:9], v[198:201], v[206:209], v[6:9]
	v_mfma_f32_16x16x32_bf16 v[2:5], v[198:201], v[214:217], v[2:5]
	v_mfma_f32_16x16x32_bf16 v[30:33], v[178:181], v[210:213], v[30:33]
	v_mfma_f32_16x16x32_bf16 v[26:29], v[178:181], v[218:221], v[26:29]
	v_mfma_f32_16x16x32_bf16 v[22:25], v[186:189], v[210:213], v[22:25]
	v_mfma_f32_16x16x32_bf16 v[18:21], v[186:189], v[218:221], v[18:21]
	v_mfma_f32_16x16x32_bf16 v[14:17], v[194:197], v[210:213], v[14:17]
	v_mfma_f32_16x16x32_bf16 v[10:13], v[194:197], v[218:221], v[10:13]
	v_mfma_f32_16x16x32_bf16 v[6:9], v[202:205], v[210:213], v[6:9]
	v_mfma_f32_16x16x32_bf16 v[2:5], v[202:205], v[218:221], v[2:5]
	s_cmp_lt_u32 s2, s29
	s_mov_b32 s3, s14
	s_cbranch_scc1 .LBB0_565
	s_barrier
	v_readfirstlane_b32 s2, v146
	s_mov_b32 m0, s2
	v_readfirstlane_b32 s2, v145
	ds_read_b128 v[140:143], v156
	ds_read_b128 v[150:153], v156 offset:1024
	ds_read_b128 v[158:161], v156 offset:2048
	ds_read_b128 v[154:157], v156 offset:3072
	ds_read_b128 v[162:165], v134
	ds_read_b128 v[166:169], v134 offset:1024
	ds_read_b128 v[170:173], v133
	ds_read_b128 v[174:177], v133 offset:1024
	ds_read_b128 v[178:181], v132
	ds_read_b128 v[182:185], v132 offset:1024
	ds_read_b128 v[186:189], v131
	ds_read_b128 v[190:193], v131 offset:1024
	buffer_load_dwordx4 v137, s[76:79], s30 offen lds
	s_mov_b32 m0, s2
	s_nop 0
	buffer_load_dwordx4 v138, s[76:79], s30 offen lds
	s_barrier
	s_waitcnt lgkmcnt(0)
	v_mfma_f32_16x16x32_bf16 v[126:129], v[162:165], v[140:143], v[126:129]
	v_mfma_f32_16x16x32_bf16 v[118:121], v[170:173], v[140:143], v[118:121]
	v_mfma_f32_16x16x32_bf16 v[110:113], v[178:181], v[140:143], v[110:113]
	v_mfma_f32_16x16x32_bf16 v[102:105], v[186:189], v[140:143], v[102:105]
	v_mfma_f32_16x16x32_bf16 v[126:129], v[166:169], v[150:153], v[126:129]
	v_mfma_f32_16x16x32_bf16 v[122:125], v[162:165], v[158:161], v[122:125]
	v_mfma_f32_16x16x32_bf16 v[118:121], v[174:177], v[150:153], v[118:121]
	v_mfma_f32_16x16x32_bf16 v[114:117], v[170:173], v[158:161], v[114:117]
	v_mfma_f32_16x16x32_bf16 v[110:113], v[182:185], v[150:153], v[110:113]
	v_mfma_f32_16x16x32_bf16 v[106:109], v[178:181], v[158:161], v[106:109]
	v_mfma_f32_16x16x32_bf16 v[102:105], v[190:193], v[150:153], v[102:105]
	v_mfma_f32_16x16x32_bf16 v[98:101], v[186:189], v[158:161], v[98:101]
	v_mfma_f32_16x16x32_bf16 v[144:147], v[166:169], v[154:157], v[122:125]
	v_mfma_f32_16x16x32_bf16 v[194:197], v[174:177], v[154:157], v[114:117]
	v_mfma_f32_16x16x32_bf16 v[198:201], v[182:185], v[154:157], v[106:109]
	v_mfma_f32_16x16x32_bf16 v[202:205], v[190:193], v[154:157], v[98:101]
	s_barrier
	s_nop 1
	ds_read_b128 v[98:101], v148
	ds_read_b128 v[106:109], v148 offset:1024
	ds_read_b128 v[114:117], v148 offset:2048
	ds_read_b128 v[122:125], v148 offset:3072
	s_barrier
	s_waitcnt lgkmcnt(0)
	v_mfma_f32_16x16x32_bf16 v[94:97], v[162:165], v[98:101], v[94:97]
	v_mfma_f32_16x16x32_bf16 v[86:89], v[170:173], v[98:101], v[86:89]
	v_mfma_f32_16x16x32_bf16 v[78:81], v[178:181], v[98:101], v[78:81]
	v_mfma_f32_16x16x32_bf16 v[70:73], v[186:189], v[98:101], v[70:73]
	v_mfma_f32_16x16x32_bf16 v[94:97], v[166:169], v[106:109], v[94:97]
	v_mfma_f32_16x16x32_bf16 v[90:93], v[162:165], v[114:117], v[90:93]
	v_mfma_f32_16x16x32_bf16 v[86:89], v[174:177], v[106:109], v[86:89]
	v_mfma_f32_16x16x32_bf16 v[82:85], v[170:173], v[114:117], v[82:85]
	v_mfma_f32_16x16x32_bf16 v[78:81], v[182:185], v[106:109], v[78:81]
	v_mfma_f32_16x16x32_bf16 v[74:77], v[178:181], v[114:117], v[74:77]
	v_mfma_f32_16x16x32_bf16 v[70:73], v[190:193], v[106:109], v[70:73]
	v_mfma_f32_16x16x32_bf16 v[66:69], v[186:189], v[114:117], v[66:69]
	v_mfma_f32_16x16x32_bf16 v[162:165], v[166:169], v[122:125], v[90:93]
	v_mfma_f32_16x16x32_bf16 v[166:169], v[174:177], v[122:125], v[82:85]
	v_mfma_f32_16x16x32_bf16 v[170:173], v[182:185], v[122:125], v[74:77]
	v_mfma_f32_16x16x32_bf16 v[174:177], v[190:193], v[122:125], v[66:69]
	s_barrier
	s_nop 0
	ds_read_b128 v[66:69], v134 offset:16384
	ds_read_b128 v[74:77], v134 offset:17408
	ds_read_b128 v[82:85], v133 offset:16384
	ds_read_b128 v[90:93], v133 offset:17408
	ds_read_b128 v[178:181], v132 offset:16384
	ds_read_b128 v[182:185], v132 offset:17408
	ds_read_b128 v[186:189], v131 offset:16384
	ds_read_b128 v[190:193], v131 offset:17408
	s_waitcnt vmcnt(4)
	s_barrier
; #define WAIT_V(n) asm volatile("s_waitcnt vmcnt(" #n ")" ::: "memory")
; #define WAIT_L(n) asm volatile("s_waitcnt lgkmcnt(" #n ")" ::: "memory")
; #define BAR __builtin_amdgcn_s_barrier()
; __device__ __forceinline__ void mainloop_8phase(const u16* __restrict__ A, const u16* __restrict__ Bt, int K,
;                                                 f32x4 (&acc)[2][2][4][2], int wid_s, int ld) {
;     ...
;     LDA(At, 0, 1); WAIT_V(4); BAR; WAIT_L(0); MMA(1, 0, At, B0); MMA(1, 1, At, B1); BAR; }
;   { LDB(B0, 1, 0); LDA(At, 1, 0); WAIT_V(2); BAR; WAIT_L(0); MMA(0, 0, At, B0); BAR;
;     LDB(B1, 1, 1); WAIT_V(0); BAR; WAIT_L(0); MMA(0, 1, At, B1); BAR;
	s_waitcnt lgkmcnt(0)
	v_mfma_f32_16x16x32_bf16 v[62:65], v[66:69], v[140:143], v[62:65]
	v_mfma_f32_16x16x32_bf16 v[54:57], v[82:85], v[140:143], v[54:57]
	v_mfma_f32_16x16x32_bf16 v[46:49], v[178:181], v[140:143], v[46:49]
	v_mfma_f32_16x16x32_bf16 v[38:41], v[186:189], v[140:143], v[38:41]
	v_mfma_f32_16x16x32_bf16 v[62:65], v[74:77], v[150:153], v[62:65]
	v_mfma_f32_16x16x32_bf16 v[58:61], v[66:69], v[158:161], v[58:61]
	v_mfma_f32_16x16x32_bf16 v[54:57], v[90:93], v[150:153], v[54:57]
	v_mfma_f32_16x16x32_bf16 v[50:53], v[82:85], v[158:161], v[50:53]
	v_mfma_f32_16x16x32_bf16 v[46:49], v[182:185], v[150:153], v[46:49]
	v_mfma_f32_16x16x32_bf16 v[42:45], v[178:181], v[158:161], v[42:45]
	v_mfma_f32_16x16x32_bf16 v[38:41], v[190:193], v[150:153], v[38:41]
	v_mfma_f32_16x16x32_bf16 v[34:37], v[186:189], v[158:161], v[34:37]
	v_mfma_f32_16x16x32_bf16 v[206:209], v[74:77], v[154:157], v[58:61]
	v_mfma_f32_16x16x32_bf16 v[210:213], v[90:93], v[154:157], v[50:53]
	v_mfma_f32_16x16x32_bf16 v[214:217], v[182:185], v[154:157], v[42:45]
	v_mfma_f32_16x16x32_bf16 v[138:141], v[190:193], v[154:157], v[34:37]
	v_mfma_f32_16x16x32_bf16 v[30:33], v[66:69], v[98:101], v[30:33]
	v_mfma_f32_16x16x32_bf16 v[22:25], v[82:85], v[98:101], v[22:25]
	v_mfma_f32_16x16x32_bf16 v[14:17], v[178:181], v[98:101], v[14:17]
	v_mfma_f32_16x16x32_bf16 v[6:9], v[186:189], v[98:101], v[6:9]
	v_mfma_f32_16x16x32_bf16 v[30:33], v[74:77], v[106:109], v[30:33]
	v_mfma_f32_16x16x32_bf16 v[26:29], v[66:69], v[114:117], v[26:29]
	v_mfma_f32_16x16x32_bf16 v[22:25], v[90:93], v[106:109], v[22:25]
	v_mfma_f32_16x16x32_bf16 v[18:21], v[82:85], v[114:117], v[18:21]
	v_mfma_f32_16x16x32_bf16 v[14:17], v[182:185], v[106:109], v[14:17]
	v_mfma_f32_16x16x32_bf16 v[10:13], v[178:181], v[114:117], v[10:13]
	v_mfma_f32_16x16x32_bf16 v[6:9], v[190:193], v[106:109], v[6:9]
	v_mfma_f32_16x16x32_bf16 v[2:5], v[186:189], v[114:117], v[2:5]
	v_mfma_f32_16x16x32_bf16 v[148:151], v[74:77], v[122:125], v[26:29]
	v_mfma_f32_16x16x32_bf16 v[152:155], v[90:93], v[122:125], v[18:21]
	v_mfma_f32_16x16x32_bf16 v[156:159], v[182:185], v[122:125], v[10:13]
	v_mfma_f32_16x16x32_bf16 v[178:181], v[190:193], v[122:125], v[2:5]
	s_barrier
	s_nop 1
	ds_read_b128 v[2:5], v136
	ds_read_b128 v[10:13], v136 offset:1024
	ds_read_b128 v[18:21], v136 offset:2048
	ds_read_b128 v[26:29], v136 offset:3072
	ds_read_b128 v[34:37], v134 offset:32768
	ds_read_b128 v[42:45], v134 offset:33792
	ds_read_b128 v[50:53], v133 offset:32768
	ds_read_b128 v[58:61], v133 offset:33792
	ds_read_b128 v[66:69], v132 offset:32768
	ds_read_b128 v[182:185], v132 offset:33792
	ds_read_b128 v[186:189], v131 offset:32768
	ds_read_b128 v[190:193], v131 offset:33792
	s_waitcnt vmcnt(2)
	s_barrier
	s_waitcnt lgkmcnt(0)
	v_mfma_f32_16x16x32_bf16 v[74:77], v[34:37], v[2:5], v[126:129]
	v_mfma_f32_16x16x32_bf16 v[122:125], v[42:45], v[10:13], v[74:77]
	v_mfma_f32_16x16x32_bf16 v[74:77], v[34:37], v[18:21], v[144:147]
	v_mfma_f32_16x16x32_bf16 v[126:129], v[42:45], v[26:29], v[74:77]
	v_mfma_f32_16x16x32_bf16 v[74:77], v[50:53], v[2:5], v[118:121]
	v_mfma_f32_16x16x32_bf16 v[114:117], v[58:61], v[10:13], v[74:77]
	v_mfma_f32_16x16x32_bf16 v[74:77], v[50:53], v[18:21], v[194:197]
	v_mfma_f32_16x16x32_bf16 v[118:121], v[58:61], v[26:29], v[74:77]
	v_mfma_f32_16x16x32_bf16 v[74:77], v[66:69], v[2:5], v[110:113]
	v_mfma_f32_16x16x32_bf16 v[106:109], v[182:185], v[10:13], v[74:77]
	v_mfma_f32_16x16x32_bf16 v[74:77], v[66:69], v[18:21], v[198:201]
	v_mfma_f32_16x16x32_bf16 v[110:113], v[182:185], v[26:29], v[74:77]
	v_mfma_f32_16x16x32_bf16 v[74:77], v[186:189], v[2:5], v[102:105]
	v_mfma_f32_16x16x32_bf16 v[98:101], v[190:193], v[10:13], v[74:77]
	v_mfma_f32_16x16x32_bf16 v[74:77], v[186:189], v[18:21], v[202:205]
	v_mfma_f32_16x16x32_bf16 v[102:105], v[190:193], v[26:29], v[74:77]
	s_barrier
; #define WAIT_V(n) asm volatile("s_waitcnt vmcnt(" #n ")" ::: "memory")
; #define WAIT_L(n) asm volatile("s_waitcnt lgkmcnt(" #n ")" ::: "memory")
; #define BAR __builtin_amdgcn_s_barrier()
; __device__ __forceinline__ void mainloop_8phase(const u16* __restrict__ A, const u16* __restrict__ Bt, int K,
;                                                 f32x4 (&acc)[2][2][4][2], int wid_s, int ld) {
;     ...
;     LDB(B1, 1, 1); WAIT_V(0); BAR; WAIT_L(0); MMA(0, 1, At, B1); BAR;
;     LDA(At, 1, 1); BAR; WAIT_L(0); MMA(1, 0, At, B0); MMA(1, 1, At, B1); BAR; }
;   if (wr == 0) BAR;
	ds_read_b128 v[142:145], v135
	ds_read_b128 v[194:197], v135 offset:1024
	ds_read_b128 v[198:201], v135 offset:2048
	ds_read_b128 v[202:205], v135 offset:3072
	s_waitcnt vmcnt(0)
	s_barrier
	s_waitcnt lgkmcnt(0)
	v_mfma_f32_16x16x32_bf16 v[74:77], v[34:37], v[142:145], v[94:97]
	v_mfma_f32_16x16x32_bf16 v[34:37], v[34:37], v[198:201], v[162:165]
	v_mfma_f32_16x16x32_bf16 v[94:97], v[42:45], v[202:205], v[34:37]
	v_mfma_f32_16x16x32_bf16 v[34:37], v[50:53], v[142:145], v[86:89]
	v_mfma_f32_16x16x32_bf16 v[82:85], v[58:61], v[194:197], v[34:37]
	v_mfma_f32_16x16x32_bf16 v[34:37], v[50:53], v[198:201], v[166:169]
	v_mfma_f32_16x16x32_bf16 v[86:89], v[58:61], v[202:205], v[34:37]
	v_mfma_f32_16x16x32_bf16 v[34:37], v[66:69], v[142:145], v[78:81]
	v_mfma_f32_16x16x32_bf16 v[90:93], v[42:45], v[194:197], v[74:77]
	v_mfma_f32_16x16x32_bf16 v[74:77], v[182:185], v[194:197], v[34:37]
	v_mfma_f32_16x16x32_bf16 v[34:37], v[66:69], v[198:201], v[170:173]
	v_mfma_f32_16x16x32_bf16 v[78:81], v[182:185], v[202:205], v[34:37]
	v_mfma_f32_16x16x32_bf16 v[34:37], v[186:189], v[142:145], v[70:73]
	v_mfma_f32_16x16x32_bf16 v[66:69], v[190:193], v[194:197], v[34:37]
	v_mfma_f32_16x16x32_bf16 v[34:37], v[186:189], v[198:201], v[174:177]
	v_mfma_f32_16x16x32_bf16 v[70:73], v[190:193], v[202:205], v[34:37]
	s_barrier
	ds_read_b128 v[160:163], v134 offset:49152
	ds_read_b128 v[134:137], v134 offset:50176
	ds_read_b128 v[164:167], v133 offset:49152
	ds_read_b128 v[168:171], v133 offset:50176
	ds_read_b128 v[172:175], v132 offset:49152
	ds_read_b128 v[182:185], v132 offset:50176
	ds_read_b128 v[186:189], v131 offset:49152
	ds_read_b128 v[190:193], v131 offset:50176
	s_barrier
	s_waitcnt lgkmcnt(0)
	v_mfma_f32_16x16x32_bf16 v[34:37], v[160:163], v[2:5], v[62:65]
	v_mfma_f32_16x16x32_bf16 v[58:61], v[134:137], v[10:13], v[34:37]
	v_mfma_f32_16x16x32_bf16 v[34:37], v[160:163], v[18:21], v[206:209]
	v_mfma_f32_16x16x32_bf16 v[62:65], v[134:137], v[26:29], v[34:37]
	v_mfma_f32_16x16x32_bf16 v[34:37], v[164:167], v[2:5], v[54:57]
	v_mfma_f32_16x16x32_bf16 v[50:53], v[168:171], v[10:13], v[34:37]
	v_mfma_f32_16x16x32_bf16 v[34:37], v[164:167], v[18:21], v[210:213]
	v_mfma_f32_16x16x32_bf16 v[54:57], v[168:171], v[26:29], v[34:37]
	v_mfma_f32_16x16x32_bf16 v[34:37], v[172:175], v[2:5], v[46:49]
	v_mfma_f32_16x16x32_bf16 v[42:45], v[182:185], v[10:13], v[34:37]
	v_mfma_f32_16x16x32_bf16 v[34:37], v[172:175], v[18:21], v[214:217]
	v_mfma_f32_16x16x32_bf16 v[2:5], v[186:189], v[2:5], v[38:41]
	v_mfma_f32_16x16x32_bf16 v[46:49], v[182:185], v[26:29], v[34:37]
	v_mfma_f32_16x16x32_bf16 v[34:37], v[190:193], v[10:13], v[2:5]
	v_mfma_f32_16x16x32_bf16 v[2:5], v[186:189], v[18:21], v[138:141]
	v_mfma_f32_16x16x32_bf16 v[38:41], v[190:193], v[26:29], v[2:5]
	v_mfma_f32_16x16x32_bf16 v[2:5], v[160:163], v[142:145], v[30:33]
	v_mfma_f32_16x16x32_bf16 v[26:29], v[134:137], v[194:197], v[2:5]
	v_mfma_f32_16x16x32_bf16 v[2:5], v[160:163], v[198:201], v[148:151]
	v_mfma_f32_16x16x32_bf16 v[30:33], v[134:137], v[202:205], v[2:5]
	v_mfma_f32_16x16x32_bf16 v[2:5], v[164:167], v[142:145], v[22:25]
	v_mfma_f32_16x16x32_bf16 v[18:21], v[168:171], v[194:197], v[2:5]
	v_mfma_f32_16x16x32_bf16 v[2:5], v[164:167], v[198:201], v[152:155]
	v_mfma_f32_16x16x32_bf16 v[22:25], v[168:171], v[202:205], v[2:5]
	v_mfma_f32_16x16x32_bf16 v[2:5], v[172:175], v[142:145], v[14:17]
	v_mfma_f32_16x16x32_bf16 v[10:13], v[182:185], v[194:197], v[2:5]
	v_mfma_f32_16x16x32_bf16 v[2:5], v[172:175], v[198:201], v[156:159]
	v_mfma_f32_16x16x32_bf16 v[14:17], v[182:185], v[202:205], v[2:5]
	v_mfma_f32_16x16x32_bf16 v[2:5], v[186:189], v[142:145], v[6:9]
	v_mfma_f32_16x16x32_bf16 v[6:9], v[186:189], v[198:201], v[178:181]
	v_mfma_f32_16x16x32_bf16 v[2:5], v[190:193], v[194:197], v[2:5]
	v_mfma_f32_16x16x32_bf16 v[6:9], v[190:193], v[202:205], v[6:9]
	s_movk_i32 s2, 0x100
	v_cmp_gt_u32_e32 vcc, s2, v0
	s_barrier
	s_and_saveexec_b64 s[2:3], vcc
	s_cbranch_execz .LBB0_568
	s_barrier
